# pipelined GEMM epilogues (mlp-out, out-proj, mlp-in): loads batched and counted vmcnt instead of per-row vmcnt(0); SSM scan LDS reads hoisted
# speedup vs baseline: 1.0390x; 1.0390x over previous
; #define PG8_STAGE(bufoff, gbase, goff, voff) do { _Pragma("unroll") for (int _i = 0; _i < 2; ++_i) \
;     __builtin_amdgcn_global_load_lds((const unsigned*)((gbase) + (size_t)(goff) + (voff)[_i]), (LAS unsigned*)(lds + (bufoff) + ldsw + _i * 8192), 16, 0, 0); } while (0)
; #define PG8_LDA(dst, b, h) do { _Pragma("unroll") for (int m = 0; m < 4; ++m) _Pragma("unroll") for (int k = 0; k < 2; ++k) dst[m][k] = *(const LAS bf16x8*)(lds + PG8_SA(b, h) + aoff + m * 2048 + k * 1024); } while (0)
; #define PG8_LDB(dst, b, h) do { _Pragma("unroll") for (int n = 0; n < 2; ++n) _Pragma("unroll") for (int k = 0; k < 2; ++k) dst[n][k] = *(const LAS bf16x8*)(lds + PG8_SB(b, h) + boff + n * 2048 + k * 1024); } while (0)
; template <class Epi>
; DI void gemm_phase(LAS unsigned char* lds, const GemmD g, const Order& S, const Epi& E) {
;     ...
;     for (int t = 0; t < nt; t += 2) {
;       const bool last = (t == nt - 2);
;       const unsigned a1 = cA + (unsigned)(t + 1) * kstep;
;       const unsigned a2 = last ? nA : cA + (unsigned)(t + 2) * kstep; const unsigned b2 = last ? nB : cB + (unsigned)(t + 2) * kstep;
;       const unsigned a3 = a2 + kstep; const unsigned b3 = b2 + kstep;
;       PG8_LDB(B0, 0, 0); PG8_SCHED; PG8_LDA(At, 0, 0); PG8_STAGE(PG8_SA(1, 1), gA, a1 + hstepA, voffA);
;       PG8_WAIT_L(8); PG8_BAR; PG8_WAIT_L(0); PG8_MMA(0, 0, At, B0); PG8_BAR; PG8_SCHED;
;       PG8_LDB(B1, 0, 1); PG8_STAGE(PG8_SB(0, 0), gB, b2, voffB);
;       PG8_BAR; PG8_WAIT_L(0); PG8_MMA(0, 1, At, B1); PG8_BAR;
;       PG8_LDA(At, 0, 1); PG8_STAGE(PG8_SA(0, 0), gA, a2, voffA);
;       PG8_BAR; PG8_WAIT_L(0); PG8_MMA(1, 0, At, B0); PG8_BAR; PG8_SCHED;
;       PG8_STAGE(PG8_SB(0, 1), gB, b2 + hstepB, voffB);
;       PG8_WAIT_V(6); PG8_BAR; PG8_MMA(1, 1, At, B1); PG8_BAR;
;       PG8_LDB(B0, 1, 0); PG8_SCHED; PG8_LDA(At, 1, 0); PG8_STAGE(PG8_SA(0, 1), gA, a2 + hstepA, voffA);
;       PG8_WAIT_L(8); PG8_BAR; PG8_WAIT_L(0); PG8_MMA(0, 0, At, B0); PG8_BAR; PG8_SCHED;
;       PG8_LDB(B1, 1, 1); PG8_STAGE(PG8_SB(1, 0), gB, b3, voffB);
;       PG8_BAR; PG8_WAIT_L(0); PG8_MMA(0, 1, At, B1); PG8_BAR;
;       PG8_LDA(At, 1, 1); PG8_STAGE(PG8_SA(1, 0), gA, a3, voffA);
;       PG8_BAR; PG8_WAIT_L(0); PG8_MMA(1, 0, At, B0); PG8_BAR; PG8_SCHED;
;       PG8_STAGE(PG8_SB(1, 1), gB, b3 + hstepB, voffB);
;       PG8_WAIT_V(6); PG8_BAR; PG8_MMA(1, 1, At, B1); PG8_BAR;
.LBB0_217:
	s_add_i32 s69, 0, 0x10000
	v_add_u32_e32 v158, s69, v140
	ds_read_b128 v[142:145], v158
	ds_read_b128 v[146:149], v158 offset:1024
	ds_read_b128 v[150:153], v158 offset:2048
	ds_read_b128 v[158:161], v158 offset:3072
	s_add_i32 s8, s48, s12
	s_addk_i32 s8, 0x100
	s_add_i32 s9, s66, s12
	s_cmpk_eq_i32 s12, 0x1f00
	s_cselect_b32 s70, s39, s8
	s_cselect_b32 s68, s65, s9
	v_lshl_add_u64 v[196:197], v[138:139], 0, s[12:13]
	s_add_i32 m0, s20, 0xc000
	ds_read_b128 v[162:165], v141
	ds_read_b128 v[168:171], v141 offset:1024
	ds_read_b128 v[172:175], v141 offset:2048
	ds_read_b128 v[176:179], v141 offset:3072
	ds_read_b128 v[180:183], v141 offset:4096
	ds_read_b128 v[184:187], v141 offset:5120
	ds_read_b128 v[188:191], v141 offset:6144
	ds_read_b128 v[192:195], v141 offset:7168
	global_load_lds_dwordx4 v[196:197], off
	v_lshl_add_u64 v[196:197], v[136:137], 0, s[12:13]
	s_add_i32 m0, s20, 0xe000
	s_nop 0
	global_load_lds_dwordx4 v[196:197], off
	s_waitcnt lgkmcnt(8)
	s_barrier
	s_waitcnt lgkmcnt(0)
	s_setprio 1
	s_waitcnt lgkmcnt(0)
	v_mfma_f32_16x16x32_bf16 v[126:129], v[142:145], v[162:165], v[126:129]
	v_mfma_f32_16x16x32_bf16 v[98:101], v[150:153], v[162:165], v[98:101]
	v_mfma_f32_16x16x32_bf16 v[122:125], v[142:145], v[172:175], v[122:125]
	v_mfma_f32_16x16x32_bf16 v[94:97], v[150:153], v[172:175], v[94:97]
	v_mfma_f32_16x16x32_bf16 v[118:121], v[142:145], v[180:183], v[118:121]
	v_mfma_f32_16x16x32_bf16 v[86:89], v[150:153], v[180:183], v[86:89]
	v_mfma_f32_16x16x32_bf16 v[114:117], v[142:145], v[188:191], v[114:117]
	v_mfma_f32_16x16x32_bf16 v[82:85], v[150:153], v[188:191], v[82:85]
	v_mfma_f32_16x16x32_bf16 v[126:129], v[146:149], v[168:171], v[126:129]
	v_mfma_f32_16x16x32_bf16 v[98:101], v[158:161], v[168:171], v[98:101]
	v_mfma_f32_16x16x32_bf16 v[122:125], v[146:149], v[176:179], v[122:125]
	v_mfma_f32_16x16x32_bf16 v[94:97], v[158:161], v[176:179], v[94:97]
	v_mfma_f32_16x16x32_bf16 v[118:121], v[146:149], v[184:187], v[118:121]
	v_mfma_f32_16x16x32_bf16 v[86:89], v[158:161], v[184:187], v[86:89]
	v_mfma_f32_16x16x32_bf16 v[114:117], v[146:149], v[192:195], v[114:117]
	v_mfma_f32_16x16x32_bf16 v[82:85], v[158:161], v[192:195], v[82:85]
	s_setprio 0
	s_barrier
	s_add_i32 s71, 0, 0x14000
	s_add_u32 s8, s17, s68
	s_addc_u32 s9, s18, 0
	s_add_i32 s69, s69, s19
	v_add_u32_e32 v167, s71, v140
	v_lshl_add_u64 v[200:201], s[8:9], 0, v[32:33]
	s_mov_b32 m0, s69
	ds_read_b128 v[196:199], v167
	ds_read_b128 v[216:219], v167 offset:1024
	ds_read_b128 v[220:223], v167 offset:2048
	ds_read_b128 v[224:227], v167 offset:3072
	global_load_lds_dwordx4 v[200:201], off
	v_lshl_add_u64 v[204:205], s[8:9], 0, v[130:131]
	s_add_i32 m0, s69, 0x2000
	s_nop 0
	global_load_lds_dwordx4 v[204:205], off
	s_barrier
	s_waitcnt lgkmcnt(0)
	s_setprio 1
	s_waitcnt lgkmcnt(0)
	v_mfma_f32_16x16x32_bf16 v[78:81], v[196:199], v[162:165], v[78:81]
	v_mfma_f32_16x16x32_bf16 v[54:57], v[220:223], v[162:165], v[54:57]
	v_mfma_f32_16x16x32_bf16 v[74:77], v[196:199], v[172:175], v[74:77]
	v_mfma_f32_16x16x32_bf16 v[46:49], v[220:223], v[172:175], v[46:49]
	v_mfma_f32_16x16x32_bf16 v[66:69], v[196:199], v[180:183], v[66:69]
	v_mfma_f32_16x16x32_bf16 v[38:41], v[220:223], v[180:183], v[38:41]
	v_mfma_f32_16x16x32_bf16 v[58:61], v[196:199], v[188:191], v[58:61]
	v_mfma_f32_16x16x32_bf16 v[34:37], v[220:223], v[188:191], v[34:37]
	v_mfma_f32_16x16x32_bf16 v[78:81], v[216:219], v[168:171], v[78:81]
	v_mfma_f32_16x16x32_bf16 v[54:57], v[224:227], v[168:171], v[54:57]
	v_mfma_f32_16x16x32_bf16 v[74:77], v[216:219], v[176:179], v[74:77]
	v_mfma_f32_16x16x32_bf16 v[46:49], v[224:227], v[176:179], v[46:49]
	v_mfma_f32_16x16x32_bf16 v[66:69], v[216:219], v[184:187], v[66:69]
	v_mfma_f32_16x16x32_bf16 v[38:41], v[224:227], v[184:187], v[38:41]
	v_mfma_f32_16x16x32_bf16 v[58:61], v[216:219], v[192:195], v[58:61]
	v_mfma_f32_16x16x32_bf16 v[34:37], v[224:227], v[192:195], v[34:37]
	s_setprio 0
	s_add_u32 s8, s6, s70
	s_addc_u32 s9, s7, 0
	s_mov_b32 m0, s20
	v_lshl_add_u64 v[208:209], s[8:9], 0, v[32:33]
	s_barrier
	ds_read_b128 v[162:165], v141 offset:16384
	ds_read_b128 v[168:171], v141 offset:17408
	ds_read_b128 v[172:175], v141 offset:18432
	ds_read_b128 v[176:179], v141 offset:19456
	ds_read_b128 v[180:183], v141 offset:20480
	ds_read_b128 v[184:187], v141 offset:21504
	ds_read_b128 v[188:191], v141 offset:22528
	ds_read_b128 v[192:195], v141 offset:23552
	global_load_lds_dwordx4 v[208:209], off
	v_lshl_add_u64 v[228:229], s[8:9], 0, v[130:131]
	s_mov_b32 m0, s21
	s_nop 0
	global_load_lds_dwordx4 v[228:229], off
	s_barrier
	s_waitcnt lgkmcnt(0)
	s_setprio 1
	s_waitcnt lgkmcnt(0)
	v_mfma_f32_16x16x32_bf16 v[110:113], v[142:145], v[162:165], v[110:113]
	v_mfma_f32_16x16x32_bf16 v[70:73], v[150:153], v[162:165], v[70:73]
	v_mfma_f32_16x16x32_bf16 v[106:109], v[142:145], v[172:175], v[106:109]
	v_mfma_f32_16x16x32_bf16 v[62:65], v[150:153], v[172:175], v[62:65]
	v_mfma_f32_16x16x32_bf16 v[102:105], v[142:145], v[180:183], v[102:105]
	v_mfma_f32_16x16x32_bf16 v[50:53], v[150:153], v[180:183], v[50:53]
	v_mfma_f32_16x16x32_bf16 v[90:93], v[142:145], v[188:191], v[90:93]
	v_mfma_f32_16x16x32_bf16 v[42:45], v[150:153], v[188:191], v[42:45]
	v_mfma_f32_16x16x32_bf16 v[110:113], v[146:149], v[168:171], v[110:113]
	v_mfma_f32_16x16x32_bf16 v[70:73], v[158:161], v[168:171], v[70:73]
	v_mfma_f32_16x16x32_bf16 v[106:109], v[146:149], v[176:179], v[106:109]
	v_mfma_f32_16x16x32_bf16 v[62:65], v[158:161], v[176:179], v[62:65]
	v_mfma_f32_16x16x32_bf16 v[102:105], v[146:149], v[184:187], v[102:105]
	v_mfma_f32_16x16x32_bf16 v[50:53], v[158:161], v[184:187], v[50:53]
	v_mfma_f32_16x16x32_bf16 v[90:93], v[146:149], v[192:195], v[90:93]
	v_mfma_f32_16x16x32_bf16 v[42:45], v[158:161], v[192:195], v[42:45]
	s_setprio 0
	s_barrier
; #define PG8_STAGE(bufoff, gbase, goff, voff) do { _Pragma("unroll") for (int _i = 0; _i < 2; ++_i) \
;     __builtin_amdgcn_global_load_lds((const unsigned*)((gbase) + (size_t)(goff) + (voff)[_i]), (LAS unsigned*)(lds + (bufoff) + ldsw + _i * 8192), 16, 0, 0); } while (0)
; #define PG8_LDA(dst, b, h) do { _Pragma("unroll") for (int m = 0; m < 4; ++m) _Pragma("unroll") for (int k = 0; k < 2; ++k) dst[m][k] = *(const LAS bf16x8*)(lds + PG8_SA(b, h) + aoff + m * 2048 + k * 1024); } while (0)
; #define PG8_LDB(dst, b, h) do { _Pragma("unroll") for (int n = 0; n < 2; ++n) _Pragma("unroll") for (int k = 0; k < 2; ++k) dst[n][k] = *(const LAS bf16x8*)(lds + PG8_SB(b, h) + boff + n * 2048 + k * 1024); } while (0)
; #define PG8_MMA(ai, bj, At, Bt) do { __builtin_amdgcn_s_setprio(1); _Pragma("unroll") for (int m = 0; m < 4; ++m) _Pragma("unroll") for (int n = 0; n < 2; ++n) _Pragma("unroll") for (int k = 0; k < 2; ++k) \
;     acc[ai][bj][m][n] = __builtin_amdgcn_mfma_f32_16x16x32_bf16(Bt[n][k], At[m][k], acc[ai][bj][m][n], 0, 0, 0); __builtin_amdgcn_s_setprio(0); } while (0)
; template <class Epi>
; DI void gemm_phase(LAS unsigned char* lds, const GemmD g, const Order& S, const Epi& E) {
;     ...
;       PG8_LDB(B0, 0, 0); PG8_SCHED; PG8_LDA(At, 0, 0); PG8_STAGE(PG8_SA(1, 1), gA, a1 + hstepA, voffA);
;       PG8_WAIT_L(8); PG8_BAR; PG8_WAIT_L(0); PG8_MMA(0, 0, At, B0); PG8_BAR; PG8_SCHED;
;       PG8_LDB(B1, 0, 1); PG8_STAGE(PG8_SB(0, 0), gB, b2, voffB);
;       PG8_BAR; PG8_WAIT_L(0); PG8_MMA(0, 1, At, B1); PG8_BAR;
;       PG8_LDA(At, 0, 1); PG8_STAGE(PG8_SA(0, 0), gA, a2, voffA);
;       PG8_BAR; PG8_WAIT_L(0); PG8_MMA(1, 0, At, B0); PG8_BAR; PG8_SCHED;
;       PG8_STAGE(PG8_SB(0, 1), gB, b2 + hstepB, voffB);
;       PG8_WAIT_V(6); PG8_BAR; PG8_MMA(1, 1, At, B1); PG8_BAR;
;       PG8_LDB(B0, 1, 0); PG8_SCHED; PG8_LDA(At, 1, 0); PG8_STAGE(PG8_SA(0, 1), gA, a2 + hstepA, voffA);
;       PG8_WAIT_L(8); PG8_BAR; PG8_WAIT_L(0); PG8_MMA(0, 0, At, B0); PG8_BAR; PG8_SCHED;
;       PG8_LDB(B1, 1, 1); PG8_STAGE(PG8_SB(1, 0), gB, b3, voffB);
;       PG8_BAR; PG8_WAIT_L(0); PG8_MMA(0, 1, At, B1); PG8_BAR;
;       PG8_LDA(At, 1, 1); PG8_STAGE(PG8_SA(1, 0), gA, a3, voffA);
;       PG8_BAR; PG8_WAIT_L(0); PG8_MMA(1, 0, At, B0); PG8_BAR; PG8_SCHED;
;       PG8_STAGE(PG8_SB(1, 1), gB, b3 + hstepB, voffB);
;       PG8_WAIT_V(6); PG8_BAR; PG8_MMA(1, 1, At, B1); PG8_BAR;
	s_add_i32 s8, s68, 0x100000
	s_add_u32 s8, s17, s8
	s_addc_u32 s9, s18, 0
	s_add_i32 s69, s71, s19
	v_lshl_add_u64 v[142:143], s[8:9], 0, v[32:33]
	s_mov_b32 m0, s69
	s_nop 0
	global_load_lds_dwordx4 v[142:143], off
	v_lshl_add_u64 v[142:143], s[8:9], 0, v[130:131]
	s_add_i32 m0, s69, 0x2000
	s_nop 0
	global_load_lds_dwordx4 v[142:143], off
	s_waitcnt vmcnt(6)
	s_barrier
	s_setprio 1
	v_mfma_f32_16x16x32_bf16 v[28:31], v[196:199], v[162:165], v[28:31]
	v_mfma_f32_16x16x32_bf16 v[12:15], v[220:223], v[162:165], v[12:15]
	v_mfma_f32_16x16x32_bf16 v[24:27], v[196:199], v[172:175], v[24:27]
	v_mfma_f32_16x16x32_bf16 v[8:11], v[220:223], v[172:175], v[8:11]
	v_mfma_f32_16x16x32_bf16 v[20:23], v[196:199], v[180:183], v[20:23]
	v_mfma_f32_16x16x32_bf16 v[4:7], v[220:223], v[180:183], v[4:7]
	v_mfma_f32_16x16x32_bf16 v[16:19], v[196:199], v[188:191], v[16:19]
	v_mfma_f32_16x16x32_bf16 v[0:3], v[220:223], v[188:191], v[0:3]
	v_mfma_f32_16x16x32_bf16 v[28:31], v[216:219], v[168:171], v[28:31]
	v_mfma_f32_16x16x32_bf16 v[12:15], v[224:227], v[168:171], v[12:15]
	v_mfma_f32_16x16x32_bf16 v[24:27], v[216:219], v[176:179], v[24:27]
	v_mfma_f32_16x16x32_bf16 v[8:11], v[224:227], v[176:179], v[8:11]
	v_mfma_f32_16x16x32_bf16 v[20:23], v[216:219], v[184:187], v[20:23]
	v_mfma_f32_16x16x32_bf16 v[4:7], v[224:227], v[184:187], v[4:7]
	v_mfma_f32_16x16x32_bf16 v[16:19], v[216:219], v[192:195], v[16:19]
	v_mfma_f32_16x16x32_bf16 v[0:3], v[224:227], v[192:195], v[0:3]
	s_setprio 0
	s_add_i32 s69, 0, 0x18000
	v_add_u32_e32 v158, s69, v140
	s_barrier
	ds_read_b128 v[142:145], v158
	ds_read_b128 v[146:149], v158 offset:1024
	ds_read_b128 v[150:153], v158 offset:2048
	ds_read_b128 v[158:161], v158 offset:3072
	s_add_i32 s70, s70, 0x100000
	s_add_u32 s8, s6, s70
	s_addc_u32 s9, s7, 0
	s_mov_b32 m0, s22
	v_lshl_add_u64 v[196:197], s[8:9], 0, v[32:33]
	ds_read_b128 v[162:165], v141 offset:32768
	ds_read_b128 v[168:171], v141 offset:33792
	ds_read_b128 v[172:175], v141 offset:34816
	ds_read_b128 v[176:179], v141 offset:35840
	ds_read_b128 v[180:183], v141 offset:36864
	ds_read_b128 v[184:187], v141 offset:37888
	ds_read_b128 v[188:191], v141 offset:38912
	ds_read_b128 v[192:195], v141 offset:39936
	global_load_lds_dwordx4 v[196:197], off
	v_lshl_add_u64 v[196:197], s[8:9], 0, v[130:131]
	s_mov_b32 m0, s23
	s_nop 0
	global_load_lds_dwordx4 v[196:197], off
	s_waitcnt lgkmcnt(8)
	s_barrier
	s_waitcnt lgkmcnt(0)
	s_setprio 1
	s_waitcnt lgkmcnt(0)
	v_mfma_f32_16x16x32_bf16 v[126:129], v[142:145], v[162:165], v[126:129]
	v_mfma_f32_16x16x32_bf16 v[98:101], v[150:153], v[162:165], v[98:101]
	v_mfma_f32_16x16x32_bf16 v[122:125], v[142:145], v[172:175], v[122:125]
	v_mfma_f32_16x16x32_bf16 v[94:97], v[150:153], v[172:175], v[94:97]
	v_mfma_f32_16x16x32_bf16 v[118:121], v[142:145], v[180:183], v[118:121]
	v_mfma_f32_16x16x32_bf16 v[86:89], v[150:153], v[180:183], v[86:89]
	v_mfma_f32_16x16x32_bf16 v[114:117], v[142:145], v[188:191], v[114:117]
	v_mfma_f32_16x16x32_bf16 v[82:85], v[150:153], v[188:191], v[82:85]
	v_mfma_f32_16x16x32_bf16 v[126:129], v[146:149], v[168:171], v[126:129]
	v_mfma_f32_16x16x32_bf16 v[98:101], v[158:161], v[168:171], v[98:101]
	v_mfma_f32_16x16x32_bf16 v[122:125], v[146:149], v[176:179], v[122:125]
	v_mfma_f32_16x16x32_bf16 v[94:97], v[158:161], v[176:179], v[94:97]
	v_mfma_f32_16x16x32_bf16 v[118:121], v[146:149], v[184:187], v[118:121]
	v_mfma_f32_16x16x32_bf16 v[86:89], v[158:161], v[184:187], v[86:89]
	v_mfma_f32_16x16x32_bf16 v[114:117], v[146:149], v[192:195], v[114:117]
	v_mfma_f32_16x16x32_bf16 v[82:85], v[158:161], v[192:195], v[82:85]
	s_setprio 0
	s_barrier
	s_add_i32 s70, 0, 0x1c000
	s_add_i32 s8, s69, s19
	v_add_u32_e32 v167, s70, v140
	v_lshl_add_u64 v[200:201], v[200:201], 0, s[50:51]
	s_mov_b32 m0, s8
	ds_read_b128 v[196:199], v167
	ds_read_b128 v[216:219], v167 offset:1024
	ds_read_b128 v[220:223], v167 offset:2048
	ds_read_b128 v[224:227], v167 offset:3072
	global_load_lds_dwordx4 v[200:201], off
	v_lshl_add_u64 v[200:201], v[204:205], 0, s[50:51]
	s_add_i32 m0, s8, 0x2000
	s_nop 0
	global_load_lds_dwordx4 v[200:201], off
	s_barrier
	s_waitcnt lgkmcnt(0)
	s_setprio 1
	s_waitcnt lgkmcnt(0)
	v_mfma_f32_16x16x32_bf16 v[78:81], v[196:199], v[162:165], v[78:81]
	v_mfma_f32_16x16x32_bf16 v[54:57], v[220:223], v[162:165], v[54:57]
	v_mfma_f32_16x16x32_bf16 v[74:77], v[196:199], v[172:175], v[74:77]
	v_mfma_f32_16x16x32_bf16 v[46:49], v[220:223], v[172:175], v[46:49]
	v_mfma_f32_16x16x32_bf16 v[66:69], v[196:199], v[180:183], v[66:69]
	v_mfma_f32_16x16x32_bf16 v[38:41], v[220:223], v[180:183], v[38:41]
	v_mfma_f32_16x16x32_bf16 v[58:61], v[196:199], v[188:191], v[58:61]
	v_mfma_f32_16x16x32_bf16 v[34:37], v[220:223], v[188:191], v[34:37]
	v_mfma_f32_16x16x32_bf16 v[78:81], v[216:219], v[168:171], v[78:81]
	v_mfma_f32_16x16x32_bf16 v[54:57], v[224:227], v[168:171], v[54:57]
	v_mfma_f32_16x16x32_bf16 v[74:77], v[216:219], v[176:179], v[74:77]
	v_mfma_f32_16x16x32_bf16 v[46:49], v[224:227], v[176:179], v[46:49]
	v_mfma_f32_16x16x32_bf16 v[66:69], v[216:219], v[184:187], v[66:69]
	v_mfma_f32_16x16x32_bf16 v[38:41], v[224:227], v[184:187], v[38:41]
	v_mfma_f32_16x16x32_bf16 v[58:61], v[216:219], v[192:195], v[58:61]
	v_mfma_f32_16x16x32_bf16 v[34:37], v[224:227], v[192:195], v[34:37]
	s_setprio 0
	s_mov_b32 m0, s26
	v_lshl_add_u64 v[200:201], v[208:209], 0, s[50:51]
	s_barrier
	ds_read_b128 v[162:165], v141 offset:49152
	ds_read_b128 v[168:171], v141 offset:50176
	ds_read_b128 v[172:175], v141 offset:51200
	ds_read_b128 v[176:179], v141 offset:52224
	ds_read_b128 v[180:183], v141 offset:53248
	ds_read_b128 v[184:187], v141 offset:54272
	ds_read_b128 v[188:191], v141 offset:55296
	ds_read_b128 v[192:195], v141 offset:56320
	global_load_lds_dwordx4 v[200:201], off
	v_lshl_add_u64 v[200:201], v[228:229], 0, s[50:51]
	s_mov_b32 m0, s27
	s_nop 0
	global_load_lds_dwordx4 v[200:201], off
	s_barrier
; #define PG8_WAIT_V(n) asm volatile("s_waitcnt vmcnt(" #n ")" ::: "memory")
; template <class Epi>
; DI void gemm_phase(LAS unsigned char* lds, const GemmD g, const Order& S, const Epi& E) {
;     ...
;     for (int t = 0; t < nt; t += 2) {
;       const bool last = (t == nt - 2);
;       const unsigned a1 = cA + (unsigned)(t + 1) * kstep;
;       const unsigned a2 = last ? nA : cA + (unsigned)(t + 2) * kstep; const unsigned b2 = last ? nB : cB + (unsigned)(t + 2) * kstep;
;       const unsigned a3 = a2 + kstep; const unsigned b3 = b2 + kstep;
;       PG8_LDB(B0, 0, 0); PG8_SCHED; PG8_LDA(At, 0, 0); PG8_STAGE(PG8_SA(1, 1), gA, a1 + hstepA, voffA);
;       PG8_WAIT_L(8); PG8_BAR; PG8_WAIT_L(0); PG8_MMA(0, 0, At, B0); PG8_BAR; PG8_SCHED;
;       PG8_LDB(B1, 0, 1); PG8_STAGE(PG8_SB(0, 0), gB, b2, voffB);
;       PG8_BAR; PG8_WAIT_L(0); PG8_MMA(0, 1, At, B1); PG8_BAR;
;       PG8_LDA(At, 0, 1); PG8_STAGE(PG8_SA(0, 0), gA, a2, voffA);
;       PG8_BAR; PG8_WAIT_L(0); PG8_MMA(1, 0, At, B0); PG8_BAR; PG8_SCHED;
;       PG8_STAGE(PG8_SB(0, 1), gB, b2 + hstepB, voffB);
;       PG8_WAIT_V(6); PG8_BAR; PG8_MMA(1, 1, At, B1); PG8_BAR;
;       PG8_LDB(B0, 1, 0); PG8_SCHED; PG8_LDA(At, 1, 0); PG8_STAGE(PG8_SA(0, 1), gA, a2 + hstepA, voffA);
;       PG8_WAIT_L(8); PG8_BAR; PG8_WAIT_L(0); PG8_MMA(0, 0, At, B0); PG8_BAR; PG8_SCHED;
;       PG8_LDB(B1, 1, 1); PG8_STAGE(PG8_SB(1, 0), gB, b3, voffB);
;       PG8_BAR; PG8_WAIT_L(0); PG8_MMA(0, 1, At, B1); PG8_BAR;
;       PG8_LDA(At, 1, 1); PG8_STAGE(PG8_SA(1, 0), gA, a3, voffA);
;       PG8_BAR; PG8_WAIT_L(0); PG8_MMA(1, 0, At, B0); PG8_BAR; PG8_SCHED;
;       PG8_STAGE(PG8_SB(1, 1), gB, b3 + hstepB, voffB);
;       PG8_WAIT_V(6); PG8_BAR; PG8_MMA(1, 1, At, B1); PG8_BAR;
;     }
;   DI bool operator()(f32x4 (&acc)[2][2][4][2], const Unit& u, int, int, int, int) const {
;     ...
;     if (!GROUPS) {
; #pragma unroll
;       for (int bj = 0; bj < 2; ++bj)
; #pragma unroll
;         for (int n = 0; n < 2; ++n) {
;           const int c = col0l + bj * HALF + n * 16;
;           const f32x4 gv = *(const f32x4*)(g + c);
; #pragma unroll
;           for (int ai = 0; ai < 2; ++ai)
; #pragma unroll
;             for (int m = 0; m < 4; ++m) {
;               const size_t o = (size_t)(row0 + ai * HALF + m * 16) * 1024 + c;
;               *(f32x4*)(xdst + o) = *(const f32x4*)(xsrc + o) + gv * acc[ai][bj][m][n];
;             }
;         }
	s_waitcnt lgkmcnt(0)
	s_setprio 1
	s_waitcnt lgkmcnt(0)
	v_mfma_f32_16x16x32_bf16 v[110:113], v[142:145], v[162:165], v[110:113]
	v_mfma_f32_16x16x32_bf16 v[70:73], v[150:153], v[162:165], v[70:73]
	v_mfma_f32_16x16x32_bf16 v[106:109], v[142:145], v[172:175], v[106:109]
	v_mfma_f32_16x16x32_bf16 v[62:65], v[150:153], v[172:175], v[62:65]
	v_mfma_f32_16x16x32_bf16 v[102:105], v[142:145], v[180:183], v[102:105]
	v_mfma_f32_16x16x32_bf16 v[50:53], v[150:153], v[180:183], v[50:53]
	v_mfma_f32_16x16x32_bf16 v[90:93], v[142:145], v[188:191], v[90:93]
	v_mfma_f32_16x16x32_bf16 v[42:45], v[150:153], v[188:191], v[42:45]
	v_mfma_f32_16x16x32_bf16 v[110:113], v[146:149], v[168:171], v[110:113]
	v_mfma_f32_16x16x32_bf16 v[70:73], v[158:161], v[168:171], v[70:73]
	v_mfma_f32_16x16x32_bf16 v[106:109], v[146:149], v[176:179], v[106:109]
	v_mfma_f32_16x16x32_bf16 v[62:65], v[158:161], v[176:179], v[62:65]
	v_mfma_f32_16x16x32_bf16 v[102:105], v[146:149], v[184:187], v[102:105]
	v_mfma_f32_16x16x32_bf16 v[50:53], v[158:161], v[184:187], v[50:53]
	v_mfma_f32_16x16x32_bf16 v[90:93], v[146:149], v[192:195], v[90:93]
	v_mfma_f32_16x16x32_bf16 v[42:45], v[158:161], v[192:195], v[42:45]
	s_setprio 0
	s_barrier
	s_add_i32 s68, s68, 0x100080
	s_add_u32 s8, s17, s68
	s_addc_u32 s9, s18, 0
	s_add_i32 s68, s70, s19
	v_lshl_add_u64 v[142:143], s[8:9], 0, v[32:33]
	s_mov_b32 m0, s68
	s_nop 0
	global_load_lds_dwordx4 v[142:143], off
	v_lshl_add_u64 v[142:143], s[8:9], 0, v[130:131]
	s_add_i32 m0, s68, 0x2000
	s_nop 0
	global_load_lds_dwordx4 v[142:143], off
	s_waitcnt vmcnt(6)
	s_barrier
	s_setprio 1
	v_mfma_f32_16x16x32_bf16 v[28:31], v[196:199], v[162:165], v[28:31]
	v_mfma_f32_16x16x32_bf16 v[12:15], v[220:223], v[162:165], v[12:15]
	v_mfma_f32_16x16x32_bf16 v[24:27], v[196:199], v[172:175], v[24:27]
	v_mfma_f32_16x16x32_bf16 v[8:11], v[220:223], v[172:175], v[8:11]
	v_mfma_f32_16x16x32_bf16 v[20:23], v[196:199], v[180:183], v[20:23]
	v_mfma_f32_16x16x32_bf16 v[4:7], v[220:223], v[180:183], v[4:7]
	v_mfma_f32_16x16x32_bf16 v[16:19], v[196:199], v[188:191], v[16:19]
	v_mfma_f32_16x16x32_bf16 v[0:3], v[220:223], v[188:191], v[0:3]
	v_mfma_f32_16x16x32_bf16 v[28:31], v[216:219], v[168:171], v[28:31]
	v_mfma_f32_16x16x32_bf16 v[12:15], v[224:227], v[168:171], v[12:15]
	v_mfma_f32_16x16x32_bf16 v[24:27], v[216:219], v[176:179], v[24:27]
	v_mfma_f32_16x16x32_bf16 v[8:11], v[224:227], v[176:179], v[8:11]
	v_mfma_f32_16x16x32_bf16 v[20:23], v[216:219], v[184:187], v[20:23]
	v_mfma_f32_16x16x32_bf16 v[4:7], v[224:227], v[184:187], v[4:7]
	v_mfma_f32_16x16x32_bf16 v[16:19], v[216:219], v[192:195], v[16:19]
	v_mfma_f32_16x16x32_bf16 v[0:3], v[224:227], v[192:195], v[0:3]
	s_setprio 0
	s_add_i32 s67, s67, 2
	s_add_u32 s12, s12, 0x100
	s_addc_u32 s13, s13, 0
	s_cmp_gt_u32 s67, 61
	s_barrier
	s_cbranch_scc0 .LBB0_217
	v_mov_b32_e32 v137, v202
	s_lshl_b32 s8, s38, 8
	v_ashrrev_i32_e32 v136, 2, v137
	v_and_b32_e32 v138, 0xffffffc0, v136
	v_lshrrev_b32_e32 v136, 1, v137
	v_lshrrev_b32_e32 v139, 2, v137
	v_and_b32_e32 v136, 0x60, v136
	v_and_b32_e32 v139, 12, v139
	v_or3_b32 v136, v136, s8, v139
	s_ashr_i32 s8, s31, 31
	s_lshl_b32 s12, s31, 8
	s_lshr_b32 s8, s8, 26
	s_add_i32 s8, s31, s8
	v_and_or_b32 v137, v137, 15, s12
	s_ashr_i32 s8, s8, 6
	v_add_u32_e32 v150, v137, v138
	s_mul_hi_i32 s9, s8, 0x6000
	s_mulk_i32 s8, 0x6000
	v_ashrrev_i32_e32 v151, 31, v150
	s_add_u32 s8, s24, s8
	v_ashrrev_i32_e32 v137, 31, v136
	v_lshlrev_b64 v[138:139], 12, v[150:151]
	s_addc_u32 s9, s25, s9
	v_lshlrev_b64 v[152:153], 2, v[136:137]
	v_lshl_add_u64 v[138:139], s[10:11], 0, v[138:139]
	v_lshl_add_u64 v[136:137], s[8:9], 0, v[152:153]
	v_lshl_add_u64 v[138:139], v[138:139], 0, v[152:153]
	global_load_dwordx4 v[142:145], v[136:137], off
	global_load_dwordx4 v[146:149], v[136:137], off offset:64
	global_load_dwordx4 v[158:161], v[136:137], off offset:512
	global_load_dwordx4 v[162:165], v[136:137], off offset:576
	s_mov_b64 s[8:9], 0x10000
	v_lshl_add_u64 v[216:217], v[138:139], 0, s[8:9]
	s_mov_b64 s[8:9], 0x20000
	v_lshl_add_u64 v[218:219], v[138:139], 0, s[8:9]
	s_mov_b64 s[8:9], 0x30000
	v_lshl_add_u64 v[220:221], v[138:139], 0, s[8:9]
	s_mov_b64 s[8:9], 0x80000
	v_lshl_add_u64 v[222:223], v[138:139], 0, s[8:9]
	s_mov_b64 s[8:9], 0x90000
	v_lshl_add_u64 v[224:225], v[138:139], 0, s[8:9]
	s_mov_b64 s[8:9], 0xa0000
	v_lshl_add_u64 v[226:227], v[138:139], 0, s[8:9]
	s_mov_b64 s[8:9], 0xb0000
	v_lshl_add_u64 v[150:151], v[138:139], 0, s[8:9]
	s_mov_b32 s38, s14
	s_mov_b32 s31, s15
	s_mov_b32 s66, s30
	s_mov_b32 s48, s29
	global_load_dwordx4 v[168:171], v[138:139], off
	global_load_dwordx4 v[172:175], v[216:217], off
	global_load_dwordx4 v[176:179], v[218:219], off
	global_load_dwordx4 v[180:183], v[220:221], off
	global_load_dwordx4 v[184:187], v[222:223], off
	global_load_dwordx4 v[188:191], v[224:225], off
	global_load_dwordx4 v[192:195], v[226:227], off
	global_load_dwordx4 v[196:199], v[150:151], off
	s_waitcnt vmcnt(7)
	v_pk_fma_f32 v[128:129], v[128:129], v[144:145], v[170:171]
	v_pk_fma_f32 v[126:127], v[126:127], v[142:143], v[168:169]
	global_store_dwordx4 v[138:139], v[126:129], off
	global_load_dwordx4 v[168:171], v[138:139], off offset:64
	s_waitcnt vmcnt(8)
	v_pk_fma_f32 v[124:125], v[124:125], v[144:145], v[174:175]
	v_pk_fma_f32 v[122:123], v[122:123], v[142:143], v[172:173]
	global_store_dwordx4 v[216:217], v[122:125], off
	global_load_dwordx4 v[172:175], v[216:217], off offset:64
	s_waitcnt vmcnt(9)
	v_pk_fma_f32 v[120:121], v[120:121], v[144:145], v[178:179]
	v_pk_fma_f32 v[118:119], v[118:119], v[142:143], v[176:177]
	global_store_dwordx4 v[218:219], v[118:121], off
	global_load_dwordx4 v[176:179], v[218:219], off offset:64
	s_waitcnt vmcnt(10)
; template <class Epi>
; DI void gemm_phase(LAS unsigned char* lds, const GemmD g, const Order& S, const Epi& E) {
;     ...
;     const bool keep = E(acc, cur, wr, wc, fr, fq);
;     if (!has_next) break;
;     if (!Epi::MAY_KEEP || !keep) {
;   DI bool operator()(f32x4 (&acc)[2][2][4][2], const Unit& u, int, int, int, int) const {
;     ...
;       for (int bj = 0; bj < 2; ++bj)
; #pragma unroll
;         for (int n = 0; n < 2; ++n) {
;           const int c = col0l + bj * HALF + n * 16;
;           const f32x4 gv = *(const f32x4*)(g + c);
; #pragma unroll
;           for (int ai = 0; ai < 2; ++ai)
; #pragma unroll
;             for (int m = 0; m < 4; ++m) {
;               const size_t o = (size_t)(row0 + ai * HALF + m * 16) * 1024 + c;
;               *(f32x4*)(xdst + o) = *(const f32x4*)(xsrc + o) + gv * acc[ai][bj][m][n];
;             }
;         }
	v_pk_fma_f32 v[116:117], v[116:117], v[144:145], v[182:183]
	v_pk_fma_f32 v[114:115], v[114:115], v[142:143], v[180:181]
	global_store_dwordx4 v[220:221], v[114:117], off
	global_load_dwordx4 v[180:183], v[220:221], off offset:64
	s_waitcnt vmcnt(11)
	v_pk_fma_f32 v[112:113], v[112:113], v[144:145], v[186:187]
	v_pk_fma_f32 v[110:111], v[110:111], v[142:143], v[184:185]
	global_store_dwordx4 v[222:223], v[110:113], off
	global_load_dwordx4 v[184:187], v[222:223], off offset:64
	s_waitcnt vmcnt(12)
	v_pk_fma_f32 v[108:109], v[108:109], v[144:145], v[190:191]
	v_pk_fma_f32 v[106:107], v[106:107], v[142:143], v[188:189]
	global_store_dwordx4 v[224:225], v[106:109], off
	global_load_dwordx4 v[188:191], v[224:225], off offset:64
	s_waitcnt vmcnt(13)
	v_pk_fma_f32 v[104:105], v[104:105], v[144:145], v[194:195]
	v_pk_fma_f32 v[102:103], v[102:103], v[142:143], v[192:193]
	global_store_dwordx4 v[226:227], v[102:105], off
	global_load_dwordx4 v[192:195], v[226:227], off offset:64
	s_waitcnt vmcnt(14)
	v_pk_fma_f32 v[92:93], v[92:93], v[144:145], v[198:199]
	v_pk_fma_f32 v[90:91], v[90:91], v[142:143], v[196:197]
	global_store_dwordx4 v[150:151], v[90:93], off
	global_load_dwordx4 v[196:199], v[150:151], off offset:64
	s_waitcnt vmcnt(14)
	v_pk_fma_f32 v[100:101], v[100:101], v[148:149], v[170:171]
	v_pk_fma_f32 v[98:99], v[98:99], v[146:147], v[168:169]
	global_store_dwordx4 v[138:139], v[98:101], off offset:64
	global_load_dwordx4 v[168:171], v[138:139], off offset:512
	s_waitcnt vmcnt(14)
	v_pk_fma_f32 v[96:97], v[96:97], v[148:149], v[174:175]
	v_pk_fma_f32 v[94:95], v[94:95], v[146:147], v[172:173]
	global_store_dwordx4 v[216:217], v[94:97], off offset:64
	global_load_dwordx4 v[172:175], v[216:217], off offset:512
	s_waitcnt vmcnt(14)
	v_pk_fma_f32 v[88:89], v[88:89], v[148:149], v[178:179]
	v_pk_fma_f32 v[86:87], v[86:87], v[146:147], v[176:177]
	global_store_dwordx4 v[218:219], v[86:89], off offset:64
	global_load_dwordx4 v[176:179], v[218:219], off offset:512
	s_waitcnt vmcnt(14)
	v_pk_fma_f32 v[84:85], v[84:85], v[148:149], v[182:183]
	v_pk_fma_f32 v[82:83], v[82:83], v[146:147], v[180:181]
	global_store_dwordx4 v[220:221], v[82:85], off offset:64
	global_load_dwordx4 v[180:183], v[220:221], off offset:512
	s_waitcnt vmcnt(14)
	v_pk_fma_f32 v[72:73], v[72:73], v[148:149], v[186:187]
	v_pk_fma_f32 v[70:71], v[70:71], v[146:147], v[184:185]
	global_store_dwordx4 v[222:223], v[70:73], off offset:64
	global_load_dwordx4 v[184:187], v[222:223], off offset:512
	s_waitcnt vmcnt(14)
	v_pk_fma_f32 v[64:65], v[64:65], v[148:149], v[190:191]
	v_pk_fma_f32 v[62:63], v[62:63], v[146:147], v[188:189]
	global_store_dwordx4 v[224:225], v[62:65], off offset:64
	global_load_dwordx4 v[188:191], v[224:225], off offset:512
	s_waitcnt vmcnt(14)
	v_pk_fma_f32 v[52:53], v[52:53], v[148:149], v[194:195]
	v_pk_fma_f32 v[50:51], v[50:51], v[146:147], v[192:193]
	global_store_dwordx4 v[226:227], v[50:53], off offset:64
	global_load_dwordx4 v[192:195], v[226:227], off offset:512
	s_waitcnt vmcnt(14)
	v_pk_fma_f32 v[44:45], v[44:45], v[148:149], v[198:199]
	v_pk_fma_f32 v[42:43], v[42:43], v[146:147], v[196:197]
	global_store_dwordx4 v[150:151], v[42:45], off offset:64
	global_load_dwordx4 v[196:199], v[150:151], off offset:512
	s_waitcnt vmcnt(14)
	v_pk_fma_f32 v[80:81], v[80:81], v[160:161], v[170:171]
	v_pk_fma_f32 v[78:79], v[78:79], v[158:159], v[168:169]
	global_store_dwordx4 v[138:139], v[78:81], off offset:512
	global_load_dwordx4 v[168:171], v[138:139], off offset:576
	s_waitcnt vmcnt(14)
	v_pk_fma_f32 v[76:77], v[76:77], v[160:161], v[174:175]
	v_pk_fma_f32 v[74:75], v[74:75], v[158:159], v[172:173]
	global_store_dwordx4 v[216:217], v[74:77], off offset:512
	global_load_dwordx4 v[172:175], v[216:217], off offset:576
	s_waitcnt vmcnt(14)
	v_pk_fma_f32 v[68:69], v[68:69], v[160:161], v[178:179]
	v_pk_fma_f32 v[66:67], v[66:67], v[158:159], v[176:177]
	global_store_dwordx4 v[218:219], v[66:69], off offset:512
	global_load_dwordx4 v[176:179], v[218:219], off offset:576
	s_waitcnt vmcnt(14)
	v_pk_fma_f32 v[60:61], v[60:61], v[160:161], v[182:183]
	v_pk_fma_f32 v[58:59], v[58:59], v[158:159], v[180:181]
	global_store_dwordx4 v[220:221], v[58:61], off offset:512
	global_load_dwordx4 v[180:183], v[220:221], off offset:576
	s_waitcnt vmcnt(14)
	v_pk_fma_f32 v[30:31], v[30:31], v[160:161], v[186:187]
	v_pk_fma_f32 v[28:29], v[28:29], v[158:159], v[184:185]
	global_store_dwordx4 v[222:223], v[28:31], off offset:512
	global_load_dwordx4 v[184:187], v[222:223], off offset:576
	s_waitcnt vmcnt(14)
	v_pk_fma_f32 v[26:27], v[26:27], v[160:161], v[190:191]
	v_pk_fma_f32 v[24:25], v[24:25], v[158:159], v[188:189]
	global_store_dwordx4 v[224:225], v[24:27], off offset:512
	global_load_dwordx4 v[188:191], v[224:225], off offset:576
	s_waitcnt vmcnt(14)
	v_pk_fma_f32 v[22:23], v[22:23], v[160:161], v[194:195]
	v_pk_fma_f32 v[20:21], v[20:21], v[158:159], v[192:193]
	global_store_dwordx4 v[226:227], v[20:23], off offset:512
	global_load_dwordx4 v[192:195], v[226:227], off offset:576
	s_waitcnt vmcnt(14)
	v_pk_fma_f32 v[18:19], v[18:19], v[160:161], v[198:199]
	v_pk_fma_f32 v[16:17], v[16:17], v[158:159], v[196:197]
	global_store_dwordx4 v[150:151], v[16:19], off offset:512
	global_load_dwordx4 v[196:199], v[150:151], off offset:576
	s_waitcnt vmcnt(14)
	v_pk_fma_f32 v[56:57], v[56:57], v[164:165], v[170:171]
	v_pk_fma_f32 v[54:55], v[54:55], v[162:163], v[168:169]
	global_store_dwordx4 v[138:139], v[54:57], off offset:576
	s_waitcnt vmcnt(13)
	v_pk_fma_f32 v[48:49], v[48:49], v[164:165], v[174:175]
	v_pk_fma_f32 v[46:47], v[46:47], v[162:163], v[172:173]
	global_store_dwordx4 v[216:217], v[46:49], off offset:576
	s_waitcnt vmcnt(12)
	v_pk_fma_f32 v[40:41], v[40:41], v[164:165], v[178:179]
	v_pk_fma_f32 v[38:39], v[38:39], v[162:163], v[176:177]
	global_store_dwordx4 v[218:219], v[38:41], off offset:576
	s_waitcnt vmcnt(11)
	v_pk_fma_f32 v[36:37], v[36:37], v[164:165], v[182:183]
	v_pk_fma_f32 v[34:35], v[34:35], v[162:163], v[180:181]
	global_store_dwordx4 v[220:221], v[34:37], off offset:576
	s_waitcnt vmcnt(10)
	v_pk_fma_f32 v[14:15], v[14:15], v[164:165], v[186:187]
	v_pk_fma_f32 v[12:13], v[12:13], v[162:163], v[184:185]
	global_store_dwordx4 v[222:223], v[12:15], off offset:576
	s_waitcnt vmcnt(9)
	v_pk_fma_f32 v[10:11], v[10:11], v[164:165], v[190:191]
	v_pk_fma_f32 v[8:9], v[8:9], v[162:163], v[188:189]
	global_store_dwordx4 v[224:225], v[8:11], off offset:576
	s_waitcnt vmcnt(8)
	v_pk_fma_f32 v[6:7], v[6:7], v[164:165], v[194:195]
	v_pk_fma_f32 v[4:5], v[4:5], v[162:163], v[192:193]
	global_store_dwordx4 v[226:227], v[4:7], off offset:576
	s_waitcnt vmcnt(7)
	v_pk_fma_f32 v[2:3], v[2:3], v[164:165], v[198:199]
	v_pk_fma_f32 v[0:1], v[0:1], v[162:163], v[196:197]
	global_store_dwordx4 v[150:151], v[0:3], off offset:576
	s_and_b64 vcc, exec, s[4:5]
	s_cbranch_vccz .LBB0_210
	s_waitcnt vmcnt(0)
	s_cmpk_gt_u32 s16, 0xff
	s_cbranch_scc1 .LBB0_221
	s_barrier

; #define PG8_STAGE(bufoff, gbase, goff, voff) do { _Pragma("unroll") for (int _i = 0; _i < 2; ++_i) \
;     __builtin_amdgcn_global_load_lds((const unsigned*)((gbase) + (size_t)(goff) + (voff)[_i]), (LAS unsigned*)(lds + (bufoff) + ldsw + _i * 8192), 16, 0, 0); } while (0)
; #define PG8_LDA(dst, b, h) do { _Pragma("unroll") for (int m = 0; m < 4; ++m) _Pragma("unroll") for (int k = 0; k < 2; ++k) dst[m][k] = *(const LAS bf16x8*)(lds + PG8_SA(b, h) + aoff + m * 2048 + k * 1024); } while (0)
; #define PG8_LDB(dst, b, h) do { _Pragma("unroll") for (int n = 0; n < 2; ++n) _Pragma("unroll") for (int k = 0; k < 2; ++k) dst[n][k] = *(const LAS bf16x8*)(lds + PG8_SB(b, h) + boff + n * 2048 + k * 1024); } while (0)
; template <class Epi>
; DI void gemm_phase(LAS unsigned char* lds, const GemmD g, const Order& S, const Epi& E) {
;     ...
;     for (int t = 0; t < nt; t += 2) {
;       const bool last = (t == nt - 2);
;       const unsigned a1 = cA + (unsigned)(t + 1) * kstep;
;       const unsigned a2 = last ? nA : cA + (unsigned)(t + 2) * kstep; const unsigned b2 = last ? nB : cB + (unsigned)(t + 2) * kstep;
;       const unsigned a3 = a2 + kstep; const unsigned b3 = b2 + kstep;
;       PG8_LDB(B0, 0, 0); PG8_SCHED; PG8_LDA(At, 0, 0); PG8_STAGE(PG8_SA(1, 1), gA, a1 + hstepA, voffA);
;       PG8_WAIT_L(8); PG8_BAR; PG8_WAIT_L(0); PG8_MMA(0, 0, At, B0); PG8_BAR; PG8_SCHED;
;       PG8_LDB(B1, 0, 1); PG8_STAGE(PG8_SB(0, 0), gB, b2, voffB);
;       PG8_BAR; PG8_WAIT_L(0); PG8_MMA(0, 1, At, B1); PG8_BAR;
;       PG8_LDA(At, 0, 1); PG8_STAGE(PG8_SA(0, 0), gA, a2, voffA);
;       PG8_BAR; PG8_WAIT_L(0); PG8_MMA(1, 0, At, B0); PG8_BAR; PG8_SCHED;
;       PG8_STAGE(PG8_SB(0, 1), gB, b2 + hstepB, voffB);
;       PG8_WAIT_V(6); PG8_BAR; PG8_MMA(1, 1, At, B1); PG8_BAR;
;       PG8_LDB(B0, 1, 0); PG8_SCHED; PG8_LDA(At, 1, 0); PG8_STAGE(PG8_SA(0, 1), gA, a2 + hstepA, voffA);
;       PG8_WAIT_L(8); PG8_BAR; PG8_WAIT_L(0); PG8_MMA(0, 0, At, B0); PG8_BAR; PG8_SCHED;
;       PG8_LDB(B1, 1, 1); PG8_STAGE(PG8_SB(1, 0), gB, b3, voffB);
;       PG8_BAR; PG8_WAIT_L(0); PG8_MMA(0, 1, At, B1); PG8_BAR;
;       PG8_LDA(At, 1, 1); PG8_STAGE(PG8_SA(1, 0), gA, a3, voffA);
;       PG8_BAR; PG8_WAIT_L(0); PG8_MMA(1, 0, At, B0); PG8_BAR; PG8_SCHED;
;       PG8_STAGE(PG8_SB(1, 1), gB, b3 + hstepB, voffB);
;       PG8_WAIT_V(6); PG8_BAR; PG8_MMA(1, 1, At, B1); PG8_BAR;
.LBB0_235:
	s_add_i32 s71, 0, 0x10000
	v_add_u32_e32 v148, s71, v150
	ds_read_b128 v[144:147], v148
	ds_read_b128 v[158:161], v148 offset:1024
	ds_read_b128 v[162:165], v148 offset:2048
	ds_read_b128 v[168:171], v148 offset:3072
	s_add_i32 s8, s48, s6
	s_addk_i32 s8, 0x100
	s_add_i32 s9, s68, s6
	s_cmpk_eq_i32 s6, 0x700
	s_cselect_b32 s72, s66, s8
	s_cselect_b32 s70, s67, s9
	v_lshl_add_u64 v[148:149], v[142:143], 0, s[6:7]
	s_add_i32 m0, s24, 0xc000
	ds_read_b128 v[172:175], v151
	ds_read_b128 v[176:179], v151 offset:1024
	ds_read_b128 v[180:183], v151 offset:2048
	ds_read_b128 v[184:187], v151 offset:3072
	ds_read_b128 v[188:191], v151 offset:4096
	ds_read_b128 v[192:195], v151 offset:5120
	ds_read_b128 v[196:199], v151 offset:6144
	ds_read_b128 v[216:219], v151 offset:7168
	global_load_lds_dwordx4 v[148:149], off
	v_lshl_add_u64 v[148:149], v[140:141], 0, s[6:7]
	s_add_i32 m0, s24, 0xe000
	s_nop 0
	global_load_lds_dwordx4 v[148:149], off
	s_waitcnt lgkmcnt(8)
	s_barrier
	s_waitcnt lgkmcnt(0)
	s_setprio 1
	s_waitcnt lgkmcnt(0)
	v_mfma_f32_16x16x32_bf16 v[126:129], v[144:147], v[172:175], v[126:129]
	v_mfma_f32_16x16x32_bf16 v[122:125], v[162:165], v[172:175], v[122:125]
	v_mfma_f32_16x16x32_bf16 v[110:113], v[144:147], v[180:183], v[110:113]
	v_mfma_f32_16x16x32_bf16 v[106:109], v[162:165], v[180:183], v[106:109]
	v_mfma_f32_16x16x32_bf16 v[94:97], v[144:147], v[188:191], v[94:97]
	v_mfma_f32_16x16x32_bf16 v[90:93], v[162:165], v[188:191], v[90:93]
	v_mfma_f32_16x16x32_bf16 v[78:81], v[144:147], v[196:199], v[78:81]
	v_mfma_f32_16x16x32_bf16 v[74:77], v[162:165], v[196:199], v[74:77]
	v_mfma_f32_16x16x32_bf16 v[126:129], v[158:161], v[176:179], v[126:129]
	v_mfma_f32_16x16x32_bf16 v[122:125], v[168:171], v[176:179], v[122:125]
	v_mfma_f32_16x16x32_bf16 v[110:113], v[158:161], v[184:187], v[110:113]
	v_mfma_f32_16x16x32_bf16 v[106:109], v[168:171], v[184:187], v[106:109]
	v_mfma_f32_16x16x32_bf16 v[94:97], v[158:161], v[192:195], v[94:97]
	v_mfma_f32_16x16x32_bf16 v[90:93], v[168:171], v[192:195], v[90:93]
	v_mfma_f32_16x16x32_bf16 v[78:81], v[158:161], v[216:219], v[78:81]
	v_mfma_f32_16x16x32_bf16 v[74:77], v[168:171], v[216:219], v[74:77]
	s_setprio 0
	s_barrier
	s_add_i32 s73, 0, 0x14000
	s_add_u32 s8, s21, s70
	v_add_u32_e32 v148, s73, v150
	s_addc_u32 s9, s22, 0
	s_add_i32 s71, s71, s23
	ds_read_b128 v[220:223], v148
	ds_read_b128 v[224:227], v148 offset:1024
	ds_read_b128 v[228:231], v148 offset:2048
	ds_read_b128 v[232:235], v148 offset:3072
	v_lshl_add_u64 v[148:149], s[8:9], 0, v[32:33]
	s_mov_b32 m0, s71
	v_lshl_add_u64 v[152:153], s[8:9], 0, v[130:131]
	global_load_lds_dwordx4 v[148:149], off
	s_add_i32 m0, s71, 0x2000
	s_nop 0
	global_load_lds_dwordx4 v[152:153], off
	s_barrier
	s_waitcnt lgkmcnt(0)
	s_setprio 1
	s_waitcnt lgkmcnt(0)
	v_mfma_f32_16x16x32_bf16 v[118:121], v[220:223], v[172:175], v[118:121]
	v_mfma_f32_16x16x32_bf16 v[114:117], v[228:231], v[172:175], v[114:117]
	v_mfma_f32_16x16x32_bf16 v[102:105], v[220:223], v[180:183], v[102:105]
	v_mfma_f32_16x16x32_bf16 v[98:101], v[228:231], v[180:183], v[98:101]
	v_mfma_f32_16x16x32_bf16 v[86:89], v[220:223], v[188:191], v[86:89]
	v_mfma_f32_16x16x32_bf16 v[82:85], v[228:231], v[188:191], v[82:85]
	v_mfma_f32_16x16x32_bf16 v[70:73], v[220:223], v[196:199], v[70:73]
	v_mfma_f32_16x16x32_bf16 v[66:69], v[228:231], v[196:199], v[66:69]
	v_mfma_f32_16x16x32_bf16 v[118:121], v[224:227], v[176:179], v[118:121]
	v_mfma_f32_16x16x32_bf16 v[114:117], v[232:235], v[176:179], v[114:117]
	v_mfma_f32_16x16x32_bf16 v[102:105], v[224:227], v[184:187], v[102:105]
	v_mfma_f32_16x16x32_bf16 v[98:101], v[232:235], v[184:187], v[98:101]
	v_mfma_f32_16x16x32_bf16 v[86:89], v[224:227], v[192:195], v[86:89]
	v_mfma_f32_16x16x32_bf16 v[82:85], v[232:235], v[192:195], v[82:85]
	v_mfma_f32_16x16x32_bf16 v[70:73], v[224:227], v[216:219], v[70:73]
	v_mfma_f32_16x16x32_bf16 v[66:69], v[232:235], v[216:219], v[66:69]
	s_setprio 0
	s_add_u32 s8, s14, s72
	s_addc_u32 s9, s15, 0
	s_mov_b32 m0, s24
	v_lshl_add_u64 v[200:201], s[8:9], 0, v[134:135]
	s_barrier
	ds_read_b128 v[172:175], v151 offset:16384
	ds_read_b128 v[176:179], v151 offset:17408
	ds_read_b128 v[180:183], v151 offset:18432
	ds_read_b128 v[184:187], v151 offset:19456
	ds_read_b128 v[188:191], v151 offset:20480
	ds_read_b128 v[192:195], v151 offset:21504
	ds_read_b128 v[196:199], v151 offset:22528
	ds_read_b128 v[216:219], v151 offset:23552
	global_load_lds_dwordx4 v[200:201], off
	v_lshl_add_u64 v[204:205], s[8:9], 0, v[132:133]
	s_mov_b32 m0, s25
	s_nop 0
	global_load_lds_dwordx4 v[204:205], off
	s_barrier
	s_waitcnt lgkmcnt(0)
	s_setprio 1
	s_waitcnt lgkmcnt(0)
	v_mfma_f32_16x16x32_bf16 v[62:65], v[144:147], v[172:175], v[62:65]
	v_mfma_f32_16x16x32_bf16 v[58:61], v[162:165], v[172:175], v[58:61]
	v_mfma_f32_16x16x32_bf16 v[46:49], v[144:147], v[180:183], v[46:49]
	v_mfma_f32_16x16x32_bf16 v[42:45], v[162:165], v[180:183], v[42:45]
	v_mfma_f32_16x16x32_bf16 v[28:31], v[144:147], v[188:191], v[28:31]
	v_mfma_f32_16x16x32_bf16 v[24:27], v[162:165], v[188:191], v[24:27]
	v_mfma_f32_16x16x32_bf16 v[12:15], v[144:147], v[196:199], v[12:15]
	v_mfma_f32_16x16x32_bf16 v[8:11], v[162:165], v[196:199], v[8:11]
	v_mfma_f32_16x16x32_bf16 v[62:65], v[158:161], v[176:179], v[62:65]
	v_mfma_f32_16x16x32_bf16 v[58:61], v[168:171], v[176:179], v[58:61]
	v_mfma_f32_16x16x32_bf16 v[46:49], v[158:161], v[184:187], v[46:49]
	v_mfma_f32_16x16x32_bf16 v[42:45], v[168:171], v[184:187], v[42:45]
	v_mfma_f32_16x16x32_bf16 v[28:31], v[158:161], v[192:195], v[28:31]
	v_mfma_f32_16x16x32_bf16 v[24:27], v[168:171], v[192:195], v[24:27]
	v_mfma_f32_16x16x32_bf16 v[12:15], v[158:161], v[216:219], v[12:15]
	v_mfma_f32_16x16x32_bf16 v[8:11], v[168:171], v[216:219], v[8:11]
	s_setprio 0
	s_barrier
; #define PG8_STAGE(bufoff, gbase, goff, voff) do { _Pragma("unroll") for (int _i = 0; _i < 2; ++_i) \
;     __builtin_amdgcn_global_load_lds((const unsigned*)((gbase) + (size_t)(goff) + (voff)[_i]), (LAS unsigned*)(lds + (bufoff) + ldsw + _i * 8192), 16, 0, 0); } while (0)
; #define PG8_LDA(dst, b, h) do { _Pragma("unroll") for (int m = 0; m < 4; ++m) _Pragma("unroll") for (int k = 0; k < 2; ++k) dst[m][k] = *(const LAS bf16x8*)(lds + PG8_SA(b, h) + aoff + m * 2048 + k * 1024); } while (0)
; #define PG8_LDB(dst, b, h) do { _Pragma("unroll") for (int n = 0; n < 2; ++n) _Pragma("unroll") for (int k = 0; k < 2; ++k) dst[n][k] = *(const LAS bf16x8*)(lds + PG8_SB(b, h) + boff + n * 2048 + k * 1024); } while (0)
; #define PG8_MMA(ai, bj, At, Bt) do { __builtin_amdgcn_s_setprio(1); _Pragma("unroll") for (int m = 0; m < 4; ++m) _Pragma("unroll") for (int n = 0; n < 2; ++n) _Pragma("unroll") for (int k = 0; k < 2; ++k) \
;     acc[ai][bj][m][n] = __builtin_amdgcn_mfma_f32_16x16x32_bf16(Bt[n][k], At[m][k], acc[ai][bj][m][n], 0, 0, 0); __builtin_amdgcn_s_setprio(0); } while (0)
; template <class Epi>
; DI void gemm_phase(LAS unsigned char* lds, const GemmD g, const Order& S, const Epi& E) {
;     ...
;       PG8_LDB(B0, 0, 0); PG8_SCHED; PG8_LDA(At, 0, 0); PG8_STAGE(PG8_SA(1, 1), gA, a1 + hstepA, voffA);
;       PG8_WAIT_L(8); PG8_BAR; PG8_WAIT_L(0); PG8_MMA(0, 0, At, B0); PG8_BAR; PG8_SCHED;
;       PG8_LDB(B1, 0, 1); PG8_STAGE(PG8_SB(0, 0), gB, b2, voffB);
;       PG8_BAR; PG8_WAIT_L(0); PG8_MMA(0, 1, At, B1); PG8_BAR;
;       PG8_LDA(At, 0, 1); PG8_STAGE(PG8_SA(0, 0), gA, a2, voffA);
;       PG8_BAR; PG8_WAIT_L(0); PG8_MMA(1, 0, At, B0); PG8_BAR; PG8_SCHED;
;       PG8_STAGE(PG8_SB(0, 1), gB, b2 + hstepB, voffB);
;       PG8_WAIT_V(6); PG8_BAR; PG8_MMA(1, 1, At, B1); PG8_BAR;
;       PG8_LDB(B0, 1, 0); PG8_SCHED; PG8_LDA(At, 1, 0); PG8_STAGE(PG8_SA(0, 1), gA, a2 + hstepA, voffA);
;       PG8_WAIT_L(8); PG8_BAR; PG8_WAIT_L(0); PG8_MMA(0, 0, At, B0); PG8_BAR; PG8_SCHED;
;       PG8_LDB(B1, 1, 1); PG8_STAGE(PG8_SB(1, 0), gB, b3, voffB);
;       PG8_BAR; PG8_WAIT_L(0); PG8_MMA(0, 1, At, B1); PG8_BAR;
;       PG8_LDA(At, 1, 1); PG8_STAGE(PG8_SA(1, 0), gA, a3, voffA);
;       PG8_BAR; PG8_WAIT_L(0); PG8_MMA(1, 0, At, B0); PG8_BAR; PG8_SCHED;
;       PG8_STAGE(PG8_SB(1, 1), gB, b3 + hstepB, voffB);
;       PG8_WAIT_V(6); PG8_BAR; PG8_MMA(1, 1, At, B1); PG8_BAR;
	s_add_i32 s8, s70, 0x40000
	s_add_u32 s8, s21, s8
	s_addc_u32 s9, s22, 0
	s_add_i32 s71, s73, s23
	v_lshl_add_u64 v[144:145], s[8:9], 0, v[32:33]
	s_mov_b32 m0, s71
	s_nop 0
	global_load_lds_dwordx4 v[144:145], off
	v_lshl_add_u64 v[144:145], s[8:9], 0, v[130:131]
	s_add_i32 m0, s71, 0x2000
	s_nop 0
	global_load_lds_dwordx4 v[144:145], off
	s_waitcnt vmcnt(6)
	s_barrier
	s_setprio 1
	v_mfma_f32_16x16x32_bf16 v[54:57], v[220:223], v[172:175], v[54:57]
	v_mfma_f32_16x16x32_bf16 v[50:53], v[228:231], v[172:175], v[50:53]
	v_mfma_f32_16x16x32_bf16 v[38:41], v[220:223], v[180:183], v[38:41]
	v_mfma_f32_16x16x32_bf16 v[34:37], v[228:231], v[180:183], v[34:37]
	v_mfma_f32_16x16x32_bf16 v[20:23], v[220:223], v[188:191], v[20:23]
	v_mfma_f32_16x16x32_bf16 v[16:19], v[228:231], v[188:191], v[16:19]
	v_mfma_f32_16x16x32_bf16 v[4:7], v[220:223], v[196:199], v[4:7]
	v_mfma_f32_16x16x32_bf16 v[0:3], v[228:231], v[196:199], v[0:3]
	v_mfma_f32_16x16x32_bf16 v[54:57], v[224:227], v[176:179], v[54:57]
	v_mfma_f32_16x16x32_bf16 v[50:53], v[232:235], v[176:179], v[50:53]
	v_mfma_f32_16x16x32_bf16 v[38:41], v[224:227], v[184:187], v[38:41]
	v_mfma_f32_16x16x32_bf16 v[34:37], v[232:235], v[184:187], v[34:37]
	v_mfma_f32_16x16x32_bf16 v[20:23], v[224:227], v[192:195], v[20:23]
	v_mfma_f32_16x16x32_bf16 v[16:19], v[232:235], v[192:195], v[16:19]
	v_mfma_f32_16x16x32_bf16 v[4:7], v[224:227], v[216:219], v[4:7]
	v_mfma_f32_16x16x32_bf16 v[0:3], v[232:235], v[216:219], v[0:3]
	s_setprio 0
	s_add_i32 s71, 0, 0x18000
	v_add_u32_e32 v167, s71, v150
	s_barrier
	ds_read_b128 v[144:147], v167
	ds_read_b128 v[158:161], v167 offset:1024
	ds_read_b128 v[162:165], v167 offset:2048
	ds_read_b128 v[168:171], v167 offset:3072
	s_add_i32 s72, s72, 0x40000
	s_add_u32 s8, s14, s72
	s_addc_u32 s9, s15, 0
	s_mov_b32 m0, s26
	v_lshl_add_u64 v[208:209], s[8:9], 0, v[134:135]
	ds_read_b128 v[172:175], v151 offset:32768
	ds_read_b128 v[176:179], v151 offset:33792
	ds_read_b128 v[180:183], v151 offset:34816
	ds_read_b128 v[184:187], v151 offset:35840
	ds_read_b128 v[188:191], v151 offset:36864
	ds_read_b128 v[192:195], v151 offset:37888
	ds_read_b128 v[196:199], v151 offset:38912
	ds_read_b128 v[216:219], v151 offset:39936
	global_load_lds_dwordx4 v[208:209], off
	v_lshl_add_u64 v[208:209], s[8:9], 0, v[132:133]
	s_mov_b32 m0, s27
	s_nop 0
	global_load_lds_dwordx4 v[208:209], off
	s_waitcnt lgkmcnt(8)
	s_barrier
	s_waitcnt lgkmcnt(0)
	s_setprio 1
	s_waitcnt lgkmcnt(0)
	v_mfma_f32_16x16x32_bf16 v[126:129], v[144:147], v[172:175], v[126:129]
	v_mfma_f32_16x16x32_bf16 v[122:125], v[162:165], v[172:175], v[122:125]
	v_mfma_f32_16x16x32_bf16 v[110:113], v[144:147], v[180:183], v[110:113]
	v_mfma_f32_16x16x32_bf16 v[106:109], v[162:165], v[180:183], v[106:109]
	v_mfma_f32_16x16x32_bf16 v[94:97], v[144:147], v[188:191], v[94:97]
	v_mfma_f32_16x16x32_bf16 v[90:93], v[162:165], v[188:191], v[90:93]
	v_mfma_f32_16x16x32_bf16 v[78:81], v[144:147], v[196:199], v[78:81]
	v_mfma_f32_16x16x32_bf16 v[74:77], v[162:165], v[196:199], v[74:77]
	v_mfma_f32_16x16x32_bf16 v[126:129], v[158:161], v[176:179], v[126:129]
	v_mfma_f32_16x16x32_bf16 v[122:125], v[168:171], v[176:179], v[122:125]
	v_mfma_f32_16x16x32_bf16 v[110:113], v[158:161], v[184:187], v[110:113]
	v_mfma_f32_16x16x32_bf16 v[106:109], v[168:171], v[184:187], v[106:109]
	v_mfma_f32_16x16x32_bf16 v[94:97], v[158:161], v[192:195], v[94:97]
	v_mfma_f32_16x16x32_bf16 v[90:93], v[168:171], v[192:195], v[90:93]
	v_mfma_f32_16x16x32_bf16 v[78:81], v[158:161], v[216:219], v[78:81]
	v_mfma_f32_16x16x32_bf16 v[74:77], v[168:171], v[216:219], v[74:77]
	s_setprio 0
	s_barrier
	s_add_i32 s72, 0, 0x1c000
	s_add_i32 s8, s71, s23
	v_add_u32_e32 v167, s72, v150
	v_lshl_add_u64 v[148:149], v[148:149], 0, s[50:51]
	s_mov_b32 m0, s8
	ds_read_b128 v[220:223], v167
	ds_read_b128 v[224:227], v167 offset:1024
	ds_read_b128 v[228:231], v167 offset:2048
	ds_read_b128 v[232:235], v167 offset:3072
	global_load_lds_dwordx4 v[148:149], off
	v_lshl_add_u64 v[148:149], v[152:153], 0, s[50:51]
	s_add_i32 m0, s8, 0x2000
	s_nop 0
	global_load_lds_dwordx4 v[148:149], off
	s_barrier
	s_waitcnt lgkmcnt(0)
	s_setprio 1
	s_waitcnt lgkmcnt(0)
	v_mfma_f32_16x16x32_bf16 v[118:121], v[220:223], v[172:175], v[118:121]
	v_mfma_f32_16x16x32_bf16 v[114:117], v[228:231], v[172:175], v[114:117]
	v_mfma_f32_16x16x32_bf16 v[102:105], v[220:223], v[180:183], v[102:105]
	v_mfma_f32_16x16x32_bf16 v[98:101], v[228:231], v[180:183], v[98:101]
	v_mfma_f32_16x16x32_bf16 v[86:89], v[220:223], v[188:191], v[86:89]
	v_mfma_f32_16x16x32_bf16 v[82:85], v[228:231], v[188:191], v[82:85]
	v_mfma_f32_16x16x32_bf16 v[70:73], v[220:223], v[196:199], v[70:73]
	v_mfma_f32_16x16x32_bf16 v[66:69], v[228:231], v[196:199], v[66:69]
	v_mfma_f32_16x16x32_bf16 v[118:121], v[224:227], v[176:179], v[118:121]
	v_mfma_f32_16x16x32_bf16 v[114:117], v[232:235], v[176:179], v[114:117]
	v_mfma_f32_16x16x32_bf16 v[102:105], v[224:227], v[184:187], v[102:105]
	v_mfma_f32_16x16x32_bf16 v[98:101], v[232:235], v[184:187], v[98:101]
	v_mfma_f32_16x16x32_bf16 v[86:89], v[224:227], v[192:195], v[86:89]
	v_mfma_f32_16x16x32_bf16 v[82:85], v[232:235], v[192:195], v[82:85]
	v_mfma_f32_16x16x32_bf16 v[70:73], v[224:227], v[216:219], v[70:73]
	v_mfma_f32_16x16x32_bf16 v[66:69], v[232:235], v[216:219], v[66:69]
	s_setprio 0
	s_mov_b32 m0, s28
	v_lshl_add_u64 v[148:149], v[200:201], 0, s[50:51]
	s_barrier
; #define PG8_STAGE(bufoff, gbase, goff, voff) do { _Pragma("unroll") for (int _i = 0; _i < 2; ++_i) \
;     __builtin_amdgcn_global_load_lds((const unsigned*)((gbase) + (size_t)(goff) + (voff)[_i]), (LAS unsigned*)(lds + (bufoff) + ldsw + _i * 8192), 16, 0, 0); } while (0)
; #define PG8_LDA(dst, b, h) do { _Pragma("unroll") for (int m = 0; m < 4; ++m) _Pragma("unroll") for (int k = 0; k < 2; ++k) dst[m][k] = *(const LAS bf16x8*)(lds + PG8_SA(b, h) + aoff + m * 2048 + k * 1024); } while (0)
; #define PG8_LDB(dst, b, h) do { _Pragma("unroll") for (int n = 0; n < 2; ++n) _Pragma("unroll") for (int k = 0; k < 2; ++k) dst[n][k] = *(const LAS bf16x8*)(lds + PG8_SB(b, h) + boff + n * 2048 + k * 1024); } while (0)
; #define PG8_WAIT_V(n) asm volatile("s_waitcnt vmcnt(" #n ")" ::: "memory")
; #define PG8_WAIT_L(n) asm volatile("s_waitcnt lgkmcnt(" #n ")" ::: "memory")
; #define PG8_BAR __builtin_amdgcn_s_barrier()
; #define PG8_SCHED __builtin_amdgcn_sched_barrier(0)
; template <class Epi>
; DI void gemm_phase(LAS unsigned char* lds, const GemmD g, const Order& S, const Epi& E) {
;     ...
;       PG8_WAIT_L(8); PG8_BAR; PG8_WAIT_L(0); PG8_MMA(0, 0, At, B0); PG8_BAR; PG8_SCHED;
;       PG8_LDB(B1, 1, 1); PG8_STAGE(PG8_SB(1, 0), gB, b3, voffB);
;       PG8_BAR; PG8_WAIT_L(0); PG8_MMA(0, 1, At, B1); PG8_BAR;
;       PG8_LDA(At, 1, 1); PG8_STAGE(PG8_SA(1, 0), gA, a3, voffA);
;       PG8_BAR; PG8_WAIT_L(0); PG8_MMA(1, 0, At, B0); PG8_BAR; PG8_SCHED;
;       PG8_STAGE(PG8_SB(1, 1), gB, b3 + hstepB, voffB);
;       PG8_WAIT_V(6); PG8_BAR; PG8_MMA(1, 1, At, B1); PG8_BAR;
;     }
;   DI bool operator()(f32x4 (&acc)[2][2][4][2], const Unit& u, int, int, int, int) const {
;     ...
;     const int row0 = u.pm * BM + wr * 64 + fr, col0 = u.pn * BM + wc * 32 + 8 * fq;
; #pragma unroll
;     for (int ai = 0; ai < 2; ++ai)
; #pragma unroll
;       for (int m = 0; m < 4; ++m) {
;         const int r = row0 + ai * HALF + m * 16;
;         u16* rowp = act + (size_t)r * 4096 + col0;
;         const float rstd = __builtin_amdgcn_rsqf(rowss[r] * (1.f / 1024.f) + 1e-6f);
;         const float* bp = bias + (size_t)((u.pm * BM) / S_) * 4096 + col0;
; #pragma unroll
;         for (int bj = 0; bj < 2; ++bj) {
;           f32x4 v0 = acc[ai][bj][m][0] * rstd + *(const f32x4*)(bp + bj * HALF);
;           f32x4 v1 = acc[ai][bj][m][1] * rstd + *(const f32x4*)(bp + bj * HALF + 4);
	ds_read_b128 v[172:175], v151 offset:49152
	ds_read_b128 v[176:179], v151 offset:50176
	ds_read_b128 v[180:183], v151 offset:51200
	ds_read_b128 v[184:187], v151 offset:52224
	ds_read_b128 v[188:191], v151 offset:53248
	ds_read_b128 v[192:195], v151 offset:54272
	ds_read_b128 v[196:199], v151 offset:55296
	ds_read_b128 v[216:219], v151 offset:56320
	global_load_lds_dwordx4 v[148:149], off
	v_lshl_add_u64 v[148:149], v[204:205], 0, s[50:51]
	s_mov_b32 m0, s29
	s_nop 0
	global_load_lds_dwordx4 v[148:149], off
	s_barrier
	s_waitcnt lgkmcnt(0)
	s_setprio 1
	s_waitcnt lgkmcnt(0)
	v_mfma_f32_16x16x32_bf16 v[62:65], v[144:147], v[172:175], v[62:65]
	v_mfma_f32_16x16x32_bf16 v[58:61], v[162:165], v[172:175], v[58:61]
	v_mfma_f32_16x16x32_bf16 v[46:49], v[144:147], v[180:183], v[46:49]
	v_mfma_f32_16x16x32_bf16 v[42:45], v[162:165], v[180:183], v[42:45]
	v_mfma_f32_16x16x32_bf16 v[28:31], v[144:147], v[188:191], v[28:31]
	v_mfma_f32_16x16x32_bf16 v[24:27], v[162:165], v[188:191], v[24:27]
	v_mfma_f32_16x16x32_bf16 v[12:15], v[144:147], v[196:199], v[12:15]
	v_mfma_f32_16x16x32_bf16 v[8:11], v[162:165], v[196:199], v[8:11]
	v_mfma_f32_16x16x32_bf16 v[62:65], v[158:161], v[176:179], v[62:65]
	v_mfma_f32_16x16x32_bf16 v[58:61], v[168:171], v[176:179], v[58:61]
	v_mfma_f32_16x16x32_bf16 v[46:49], v[158:161], v[184:187], v[46:49]
	v_mfma_f32_16x16x32_bf16 v[42:45], v[168:171], v[184:187], v[42:45]
	v_mfma_f32_16x16x32_bf16 v[28:31], v[158:161], v[192:195], v[28:31]
	v_mfma_f32_16x16x32_bf16 v[24:27], v[168:171], v[192:195], v[24:27]
	v_mfma_f32_16x16x32_bf16 v[12:15], v[158:161], v[216:219], v[12:15]
	v_mfma_f32_16x16x32_bf16 v[8:11], v[168:171], v[216:219], v[8:11]
	s_setprio 0
	s_barrier
	s_add_i32 s70, s70, 0x40080
	s_add_u32 s8, s21, s70
	s_addc_u32 s9, s22, 0
	s_add_i32 s70, s72, s23
	v_lshl_add_u64 v[144:145], s[8:9], 0, v[32:33]
	s_mov_b32 m0, s70
	s_nop 0
	global_load_lds_dwordx4 v[144:145], off
	v_lshl_add_u64 v[144:145], s[8:9], 0, v[130:131]
	s_add_i32 m0, s70, 0x2000
	s_nop 0
	global_load_lds_dwordx4 v[144:145], off
	s_waitcnt vmcnt(6)
	s_barrier
	s_setprio 1
	v_mfma_f32_16x16x32_bf16 v[54:57], v[220:223], v[172:175], v[54:57]
	v_mfma_f32_16x16x32_bf16 v[50:53], v[228:231], v[172:175], v[50:53]
	v_mfma_f32_16x16x32_bf16 v[38:41], v[220:223], v[180:183], v[38:41]
	v_mfma_f32_16x16x32_bf16 v[34:37], v[228:231], v[180:183], v[34:37]
	v_mfma_f32_16x16x32_bf16 v[20:23], v[220:223], v[188:191], v[20:23]
	v_mfma_f32_16x16x32_bf16 v[16:19], v[228:231], v[188:191], v[16:19]
	v_mfma_f32_16x16x32_bf16 v[4:7], v[220:223], v[196:199], v[4:7]
	v_mfma_f32_16x16x32_bf16 v[0:3], v[228:231], v[196:199], v[0:3]
	v_mfma_f32_16x16x32_bf16 v[54:57], v[224:227], v[176:179], v[54:57]
	v_mfma_f32_16x16x32_bf16 v[50:53], v[232:235], v[176:179], v[50:53]
	v_mfma_f32_16x16x32_bf16 v[38:41], v[224:227], v[184:187], v[38:41]
	v_mfma_f32_16x16x32_bf16 v[34:37], v[232:235], v[184:187], v[34:37]
	v_mfma_f32_16x16x32_bf16 v[20:23], v[224:227], v[192:195], v[20:23]
	v_mfma_f32_16x16x32_bf16 v[16:19], v[232:235], v[192:195], v[16:19]
	v_mfma_f32_16x16x32_bf16 v[4:7], v[224:227], v[216:219], v[4:7]
	v_mfma_f32_16x16x32_bf16 v[0:3], v[232:235], v[216:219], v[0:3]
	s_setprio 0
	s_add_i32 s69, s69, 2
	s_add_u32 s6, s6, 0x100
	s_addc_u32 s7, s7, 0
	s_cmp_gt_u32 s69, 13
	s_barrier
	s_cbranch_scc0 .LBB0_235
	v_mov_b32_e32 v141, v202
	s_lshl_b32 s6, s39, 8
	v_ashrrev_i32_e32 v140, 2, v141
	v_and_b32_e32 v142, 0xffffffc0, v140
	v_lshrrev_b32_e32 v140, 1, v141
	v_and_or_b32 v141, v141, 15, s6
	s_ashr_i32 s6, s39, 31
	v_add_u32_e32 v146, v141, v142
	s_lshr_b32 s6, s6, 26
	s_add_i32 s6, s39, s6
	v_ashrrev_i32_e32 v147, 31, v146
	s_ashr_i32 s6, s6, 6
	v_lshl_add_u64 v[144:145], v[146:147], 2, s[16:17]
	s_ashr_i32 s7, s6, 31
	global_load_dword v168, v[144:145], off
	global_load_dword v170, v[144:145], off offset:64
	global_load_dword v172, v[144:145], off offset:128
	global_load_dword v174, v[144:145], off offset:192
	global_load_dword v184, v[144:145], off offset:512
	global_load_dword v186, v[144:145], off offset:576
	global_load_dword v188, v[144:145], off offset:640
	global_load_dword v190, v[144:145], off offset:704
	v_and_b32_e32 v140, 0x78, v140
	s_lshl_b64 s[6:7], s[6:7], 14
	v_lshl_or_b32 v140, s65, 8, v140
	s_add_u32 s6, s18, s6
	v_ashrrev_i32_e32 v141, 31, v140
	s_addc_u32 s7, s19, s7
	v_lshl_add_u64 v[142:143], v[140:141], 2, s[6:7]
	global_load_dwordx4 v[158:161], v[142:143], off
	global_load_dwordx4 v[162:165], v[142:143], off offset:16
	global_load_dwordx4 v[176:179], v[142:143], off offset:512
	global_load_dwordx4 v[180:183], v[142:143], off offset:528
	v_lshlrev_b64 v[152:153], 13, v[146:147]
	s_mov_b32 s68, s38
	s_mov_b32 s48, s31
	s_mov_b32 s39, s11
	s_mov_b32 s65, s10
	v_lshlrev_b64 v[148:149], 1, v[140:141]
	v_lshl_add_u64 v[140:141], s[12:13], 0, v[152:153]
	v_lshl_add_u64 v[140:141], v[140:141], 0, v[148:149]
	s_and_b64 vcc, exec, s[4:5]
	s_waitcnt vmcnt(0)
; DI unsigned pk2(float a, float b) { f2_t v = {a, b}; bf2_t r = __builtin_convertvector(v, bf2_t); return __builtin_bit_cast(unsigned, r); }
;   DI bool operator()(f32x4 (&acc)[2][2][4][2], const Unit& u, int, int, int, int) const {
;     ...
;       for (int m = 0; m < 4; ++m) {
;         const int r = row0 + ai * HALF + m * 16;
;         u16* rowp = act + (size_t)r * 4096 + col0;
;         const float rstd = __builtin_amdgcn_rsqf(rowss[r] * (1.f / 1024.f) + 1e-6f);
;         const float* bp = bias + (size_t)((u.pm * BM) / S_) * 4096 + col0;
; #pragma unroll
;         for (int bj = 0; bj < 2; ++bj) {
;           f32x4 v0 = acc[ai][bj][m][0] * rstd + *(const f32x4*)(bp + bj * HALF);
;           f32x4 v1 = acc[ai][bj][m][1] * rstd + *(const f32x4*)(bp + bj * HALF + 4);
; #pragma unroll
;           for (int j = 0; j < 4; ++j) { v0[j] = fmaxf(v0[j], 0.f); v0[j] *= v0[j]; v1[j] = fmaxf(v1[j], 0.f); v1[j] *= v1[j]; }
;           u32x4 w;
;           w.x = pk2(v0[0], v0[1]); w.y = pk2(v0[2], v0[3]); w.z = pk2(v1[0], v1[1]); w.w = pk2(v1[2], v1[3]);
;           *(u32x4*)(rowp + bj * HALF) = w;
;         }
	v_fmamk_f32 v168, v168, 0x3a800000, v203
	v_fmamk_f32 v170, v170, 0x3a800000, v203
	v_fmamk_f32 v172, v172, 0x3a800000, v203
	v_fmamk_f32 v174, v174, 0x3a800000, v203
	v_fmamk_f32 v184, v184, 0x3a800000, v203
	v_fmamk_f32 v186, v186, 0x3a800000, v203
	v_fmamk_f32 v188, v188, 0x3a800000, v203
	v_fmamk_f32 v190, v190, 0x3a800000, v203
	v_rsq_f32_e32 v168, v168
	v_rsq_f32_e32 v170, v170
	v_rsq_f32_e32 v172, v172
	v_rsq_f32_e32 v174, v174
	v_rsq_f32_e32 v184, v184
	v_rsq_f32_e32 v186, v186
	v_rsq_f32_e32 v188, v188
	v_rsq_f32_e32 v190, v190
	v_pk_fma_f32 v[128:129], v[128:129], v[168:169], v[160:161] op_sel_hi:[1,0,1]
	v_pk_fma_f32 v[126:127], v[126:127], v[168:169], v[158:159] op_sel_hi:[1,0,1]
	v_pk_fma_f32 v[124:125], v[124:125], v[168:169], v[164:165] op_sel_hi:[1,0,1]
	v_pk_fma_f32 v[122:123], v[122:123], v[168:169], v[162:163] op_sel_hi:[1,0,1]
	v_max_f32_e32 v126, 0, v126
	v_max_f32_e32 v122, 0, v122
	v_max_f32_e32 v127, 0, v127
	v_max_f32_e32 v123, 0, v123
	v_max_f32_e32 v128, 0, v128
	v_max_f32_e32 v124, 0, v124
	v_max_f32_e32 v129, 0, v129
	v_max_f32_e32 v125, 0, v125
	v_pk_mul_f32 v[126:127], v[126:127], v[126:127]
	v_pk_mul_f32 v[122:123], v[122:123], v[122:123]
	v_pk_mul_f32 v[128:129], v[128:129], v[128:129]
	v_pk_mul_f32 v[124:125], v[124:125], v[124:125]
	v_cvt_pk_bf16_f32 v126, v126, v127
	v_cvt_pk_bf16_f32 v127, v128, v129
	v_cvt_pk_bf16_f32 v128, v122, v123
	v_cvt_pk_bf16_f32 v129, v124, v125
	global_store_dwordx4 v[140:141], v[126:129], off
	v_pk_fma_f32 v[120:121], v[120:121], v[168:169], v[178:179] op_sel_hi:[1,0,1]
	v_pk_fma_f32 v[118:119], v[118:119], v[168:169], v[176:177] op_sel_hi:[1,0,1]
	v_pk_fma_f32 v[116:117], v[116:117], v[168:169], v[182:183] op_sel_hi:[1,0,1]
	v_pk_fma_f32 v[114:115], v[114:115], v[168:169], v[180:181] op_sel_hi:[1,0,1]
	v_max_f32_e32 v118, 0, v118
	v_max_f32_e32 v114, 0, v114
	v_max_f32_e32 v119, 0, v119
	v_max_f32_e32 v115, 0, v115
	v_max_f32_e32 v120, 0, v120
	v_max_f32_e32 v116, 0, v116
	v_max_f32_e32 v121, 0, v121
	v_max_f32_e32 v117, 0, v117
	v_pk_mul_f32 v[118:119], v[118:119], v[118:119]
	v_pk_mul_f32 v[114:115], v[114:115], v[114:115]
	v_pk_mul_f32 v[120:121], v[120:121], v[120:121]
	v_pk_mul_f32 v[116:117], v[116:117], v[116:117]
	v_cvt_pk_bf16_f32 v118, v118, v119
	v_cvt_pk_bf16_f32 v119, v120, v121
	v_cvt_pk_bf16_f32 v120, v114, v115
	v_cvt_pk_bf16_f32 v121, v116, v117
	global_store_dwordx4 v[140:141], v[118:121], off offset:256
	s_mov_b64 s[6:7], 0x20000
	v_lshl_add_u64 v[192:193], v[140:141], 0, s[6:7]
	v_pk_fma_f32 v[112:113], v[112:113], v[170:171], v[160:161] op_sel_hi:[1,0,1]
	v_pk_fma_f32 v[110:111], v[110:111], v[170:171], v[158:159] op_sel_hi:[1,0,1]
	v_pk_fma_f32 v[108:109], v[108:109], v[170:171], v[164:165] op_sel_hi:[1,0,1]
	v_pk_fma_f32 v[106:107], v[106:107], v[170:171], v[162:163] op_sel_hi:[1,0,1]
	v_max_f32_e32 v110, 0, v110
	v_max_f32_e32 v106, 0, v106
	v_max_f32_e32 v111, 0, v111
	v_max_f32_e32 v107, 0, v107
	v_max_f32_e32 v112, 0, v112
	v_max_f32_e32 v108, 0, v108
	v_max_f32_e32 v113, 0, v113
	v_max_f32_e32 v109, 0, v109
	v_pk_mul_f32 v[110:111], v[110:111], v[110:111]
	v_pk_mul_f32 v[106:107], v[106:107], v[106:107]
	v_pk_mul_f32 v[112:113], v[112:113], v[112:113]
	v_pk_mul_f32 v[108:109], v[108:109], v[108:109]
	v_cvt_pk_bf16_f32 v110, v110, v111
	v_cvt_pk_bf16_f32 v111, v112, v113
	v_cvt_pk_bf16_f32 v112, v106, v107
	v_cvt_pk_bf16_f32 v113, v108, v109
	global_store_dwordx4 v[192:193], v[110:113], off
	v_pk_fma_f32 v[104:105], v[104:105], v[170:171], v[178:179] op_sel_hi:[1,0,1]
	v_pk_fma_f32 v[102:103], v[102:103], v[170:171], v[176:177] op_sel_hi:[1,0,1]
	v_pk_fma_f32 v[100:101], v[100:101], v[170:171], v[182:183] op_sel_hi:[1,0,1]
	v_pk_fma_f32 v[98:99], v[98:99], v[170:171], v[180:181] op_sel_hi:[1,0,1]
	v_max_f32_e32 v102, 0, v102
	v_max_f32_e32 v98, 0, v98
	v_max_f32_e32 v103, 0, v103
	v_max_f32_e32 v99, 0, v99
	v_max_f32_e32 v104, 0, v104
	v_max_f32_e32 v100, 0, v100
	v_max_f32_e32 v105, 0, v105
	v_max_f32_e32 v101, 0, v101
	v_pk_mul_f32 v[102:103], v[102:103], v[102:103]
	v_pk_mul_f32 v[98:99], v[98:99], v[98:99]
	v_pk_mul_f32 v[104:105], v[104:105], v[104:105]
	v_pk_mul_f32 v[100:101], v[100:101], v[100:101]
	v_cvt_pk_bf16_f32 v102, v102, v103
	v_cvt_pk_bf16_f32 v103, v104, v105
	v_cvt_pk_bf16_f32 v104, v98, v99
	v_cvt_pk_bf16_f32 v105, v100, v101
	global_store_dwordx4 v[192:193], v[102:105], off offset:256
	s_mov_b64 s[6:7], 0x40000
	v_lshl_add_u64 v[192:193], v[140:141], 0, s[6:7]
	v_pk_fma_f32 v[96:97], v[96:97], v[172:173], v[160:161] op_sel_hi:[1,0,1]
	v_pk_fma_f32 v[94:95], v[94:95], v[172:173], v[158:159] op_sel_hi:[1,0,1]
	v_pk_fma_f32 v[92:93], v[92:93], v[172:173], v[164:165] op_sel_hi:[1,0,1]
	v_pk_fma_f32 v[90:91], v[90:91], v[172:173], v[162:163] op_sel_hi:[1,0,1]
	v_max_f32_e32 v94, 0, v94
	v_max_f32_e32 v90, 0, v90
	v_max_f32_e32 v95, 0, v95
	v_max_f32_e32 v91, 0, v91
	v_max_f32_e32 v96, 0, v96
	v_max_f32_e32 v92, 0, v92
	v_max_f32_e32 v97, 0, v97
	v_max_f32_e32 v93, 0, v93
	v_pk_mul_f32 v[94:95], v[94:95], v[94:95]
	v_pk_mul_f32 v[90:91], v[90:91], v[90:91]
	v_pk_mul_f32 v[96:97], v[96:97], v[96:97]
	v_pk_mul_f32 v[92:93], v[92:93], v[92:93]
	v_cvt_pk_bf16_f32 v94, v94, v95
	v_cvt_pk_bf16_f32 v95, v96, v97
	v_cvt_pk_bf16_f32 v96, v90, v91
	v_cvt_pk_bf16_f32 v97, v92, v93
	global_store_dwordx4 v[192:193], v[94:97], off
	v_pk_fma_f32 v[88:89], v[88:89], v[172:173], v[178:179] op_sel_hi:[1,0,1]
	v_pk_fma_f32 v[86:87], v[86:87], v[172:173], v[176:177] op_sel_hi:[1,0,1]
	v_pk_fma_f32 v[84:85], v[84:85], v[172:173], v[182:183] op_sel_hi:[1,0,1]
	v_pk_fma_f32 v[82:83], v[82:83], v[172:173], v[180:181] op_sel_hi:[1,0,1]
	v_max_f32_e32 v86, 0, v86
; DI unsigned pk2(float a, float b) { f2_t v = {a, b}; bf2_t r = __builtin_convertvector(v, bf2_t); return __builtin_bit_cast(unsigned, r); }
;   DI bool operator()(f32x4 (&acc)[2][2][4][2], const Unit& u, int, int, int, int) const {
;     ...
;       for (int m = 0; m < 4; ++m) {
;         const int r = row0 + ai * HALF + m * 16;
;         u16* rowp = act + (size_t)r * 4096 + col0;
;         const float rstd = __builtin_amdgcn_rsqf(rowss[r] * (1.f / 1024.f) + 1e-6f);
;         const float* bp = bias + (size_t)((u.pm * BM) / S_) * 4096 + col0;
; #pragma unroll
;         for (int bj = 0; bj < 2; ++bj) {
;           f32x4 v0 = acc[ai][bj][m][0] * rstd + *(const f32x4*)(bp + bj * HALF);
;           f32x4 v1 = acc[ai][bj][m][1] * rstd + *(const f32x4*)(bp + bj * HALF + 4);
; #pragma unroll
;           for (int j = 0; j < 4; ++j) { v0[j] = fmaxf(v0[j], 0.f); v0[j] *= v0[j]; v1[j] = fmaxf(v1[j], 0.f); v1[j] *= v1[j]; }
;           u32x4 w;
;           w.x = pk2(v0[0], v0[1]); w.y = pk2(v0[2], v0[3]); w.z = pk2(v1[0], v1[1]); w.w = pk2(v1[2], v1[3]);
;           *(u32x4*)(rowp + bj * HALF) = w;
;         }
	v_max_f32_e32 v82, 0, v82
	v_max_f32_e32 v87, 0, v87
	v_max_f32_e32 v83, 0, v83
	v_max_f32_e32 v88, 0, v88
	v_max_f32_e32 v84, 0, v84
	v_max_f32_e32 v89, 0, v89
	v_max_f32_e32 v85, 0, v85
	v_pk_mul_f32 v[86:87], v[86:87], v[86:87]
	v_pk_mul_f32 v[82:83], v[82:83], v[82:83]
	v_pk_mul_f32 v[88:89], v[88:89], v[88:89]
	v_pk_mul_f32 v[84:85], v[84:85], v[84:85]
	v_cvt_pk_bf16_f32 v86, v86, v87
	v_cvt_pk_bf16_f32 v87, v88, v89
	v_cvt_pk_bf16_f32 v88, v82, v83
	v_cvt_pk_bf16_f32 v89, v84, v85
	global_store_dwordx4 v[192:193], v[86:89], off offset:256
	s_mov_b64 s[6:7], 0x60000
	v_lshl_add_u64 v[192:193], v[140:141], 0, s[6:7]
	v_pk_fma_f32 v[80:81], v[80:81], v[174:175], v[160:161] op_sel_hi:[1,0,1]
	v_pk_fma_f32 v[78:79], v[78:79], v[174:175], v[158:159] op_sel_hi:[1,0,1]
	v_pk_fma_f32 v[76:77], v[76:77], v[174:175], v[164:165] op_sel_hi:[1,0,1]
	v_pk_fma_f32 v[74:75], v[74:75], v[174:175], v[162:163] op_sel_hi:[1,0,1]
	v_max_f32_e32 v78, 0, v78
	v_max_f32_e32 v74, 0, v74
	v_max_f32_e32 v79, 0, v79
	v_max_f32_e32 v75, 0, v75
	v_max_f32_e32 v80, 0, v80
	v_max_f32_e32 v76, 0, v76
	v_max_f32_e32 v81, 0, v81
	v_max_f32_e32 v77, 0, v77
	v_pk_mul_f32 v[78:79], v[78:79], v[78:79]
	v_pk_mul_f32 v[74:75], v[74:75], v[74:75]
	v_pk_mul_f32 v[80:81], v[80:81], v[80:81]
	v_pk_mul_f32 v[76:77], v[76:77], v[76:77]
	v_cvt_pk_bf16_f32 v78, v78, v79
	v_cvt_pk_bf16_f32 v79, v80, v81
	v_cvt_pk_bf16_f32 v80, v74, v75
	v_cvt_pk_bf16_f32 v81, v76, v77
	global_store_dwordx4 v[192:193], v[78:81], off
	v_pk_fma_f32 v[72:73], v[72:73], v[174:175], v[178:179] op_sel_hi:[1,0,1]
	v_pk_fma_f32 v[70:71], v[70:71], v[174:175], v[176:177] op_sel_hi:[1,0,1]
	v_pk_fma_f32 v[68:69], v[68:69], v[174:175], v[182:183] op_sel_hi:[1,0,1]
	v_pk_fma_f32 v[66:67], v[66:67], v[174:175], v[180:181] op_sel_hi:[1,0,1]
	v_max_f32_e32 v70, 0, v70
	v_max_f32_e32 v66, 0, v66
	v_max_f32_e32 v71, 0, v71
	v_max_f32_e32 v67, 0, v67
	v_max_f32_e32 v72, 0, v72
	v_max_f32_e32 v68, 0, v68
	v_max_f32_e32 v73, 0, v73
	v_max_f32_e32 v69, 0, v69
	v_pk_mul_f32 v[70:71], v[70:71], v[70:71]
	v_pk_mul_f32 v[66:67], v[66:67], v[66:67]
	v_pk_mul_f32 v[72:73], v[72:73], v[72:73]
	v_pk_mul_f32 v[68:69], v[68:69], v[68:69]
	v_cvt_pk_bf16_f32 v70, v70, v71
	v_cvt_pk_bf16_f32 v71, v72, v73
	v_cvt_pk_bf16_f32 v72, v66, v67
	v_cvt_pk_bf16_f32 v73, v68, v69
	global_store_dwordx4 v[192:193], v[70:73], off offset:256
	s_mov_b64 s[6:7], 0x100000
	v_lshl_add_u64 v[192:193], v[140:141], 0, s[6:7]
	v_pk_fma_f32 v[64:65], v[64:65], v[184:185], v[160:161] op_sel_hi:[1,0,1]
	v_pk_fma_f32 v[62:63], v[62:63], v[184:185], v[158:159] op_sel_hi:[1,0,1]
	v_pk_fma_f32 v[60:61], v[60:61], v[184:185], v[164:165] op_sel_hi:[1,0,1]
	v_pk_fma_f32 v[58:59], v[58:59], v[184:185], v[162:163] op_sel_hi:[1,0,1]
	v_max_f32_e32 v62, 0, v62
	v_max_f32_e32 v58, 0, v58
	v_max_f32_e32 v63, 0, v63
	v_max_f32_e32 v59, 0, v59
	v_max_f32_e32 v64, 0, v64
	v_max_f32_e32 v60, 0, v60
	v_max_f32_e32 v65, 0, v65
	v_max_f32_e32 v61, 0, v61
	v_pk_mul_f32 v[62:63], v[62:63], v[62:63]
	v_pk_mul_f32 v[58:59], v[58:59], v[58:59]
	v_pk_mul_f32 v[64:65], v[64:65], v[64:65]
	v_pk_mul_f32 v[60:61], v[60:61], v[60:61]
	v_cvt_pk_bf16_f32 v62, v62, v63
	v_cvt_pk_bf16_f32 v63, v64, v65
	v_cvt_pk_bf16_f32 v64, v58, v59
	v_cvt_pk_bf16_f32 v65, v60, v61
	global_store_dwordx4 v[192:193], v[62:65], off
	v_pk_fma_f32 v[56:57], v[56:57], v[184:185], v[178:179] op_sel_hi:[1,0,1]
	v_pk_fma_f32 v[54:55], v[54:55], v[184:185], v[176:177] op_sel_hi:[1,0,1]
	v_pk_fma_f32 v[52:53], v[52:53], v[184:185], v[182:183] op_sel_hi:[1,0,1]
	v_pk_fma_f32 v[50:51], v[50:51], v[184:185], v[180:181] op_sel_hi:[1,0,1]
	v_max_f32_e32 v54, 0, v54
	v_max_f32_e32 v50, 0, v50
	v_max_f32_e32 v55, 0, v55
	v_max_f32_e32 v51, 0, v51
	v_max_f32_e32 v56, 0, v56
	v_max_f32_e32 v52, 0, v52
	v_max_f32_e32 v57, 0, v57
	v_max_f32_e32 v53, 0, v53
	v_pk_mul_f32 v[54:55], v[54:55], v[54:55]
	v_pk_mul_f32 v[50:51], v[50:51], v[50:51]
	v_pk_mul_f32 v[56:57], v[56:57], v[56:57]
	v_pk_mul_f32 v[52:53], v[52:53], v[52:53]
	v_cvt_pk_bf16_f32 v54, v54, v55
	v_cvt_pk_bf16_f32 v55, v56, v57
	v_cvt_pk_bf16_f32 v56, v50, v51
	v_cvt_pk_bf16_f32 v57, v52, v53
	global_store_dwordx4 v[192:193], v[54:57], off offset:256
	s_mov_b64 s[6:7], 0x120000
	v_lshl_add_u64 v[192:193], v[140:141], 0, s[6:7]
	v_pk_fma_f32 v[48:49], v[48:49], v[186:187], v[160:161] op_sel_hi:[1,0,1]
	v_pk_fma_f32 v[46:47], v[46:47], v[186:187], v[158:159] op_sel_hi:[1,0,1]
	v_pk_fma_f32 v[44:45], v[44:45], v[186:187], v[164:165] op_sel_hi:[1,0,1]
	v_pk_fma_f32 v[42:43], v[42:43], v[186:187], v[162:163] op_sel_hi:[1,0,1]
	v_max_f32_e32 v46, 0, v46
	v_max_f32_e32 v42, 0, v42
	v_max_f32_e32 v47, 0, v47
	v_max_f32_e32 v43, 0, v43
	v_max_f32_e32 v48, 0, v48
	v_max_f32_e32 v44, 0, v44
	v_max_f32_e32 v49, 0, v49
	v_max_f32_e32 v45, 0, v45
	v_pk_mul_f32 v[46:47], v[46:47], v[46:47]
; DI unsigned pk2(float a, float b) { f2_t v = {a, b}; bf2_t r = __builtin_convertvector(v, bf2_t); return __builtin_bit_cast(unsigned, r); }
;   DI bool operator()(f32x4 (&acc)[2][2][4][2], const Unit& u, int, int, int, int) const {
;     ...
;       for (int m = 0; m < 4; ++m) {
;         const int r = row0 + ai * HALF + m * 16;
;         u16* rowp = act + (size_t)r * 4096 + col0;
;         const float rstd = __builtin_amdgcn_rsqf(rowss[r] * (1.f / 1024.f) + 1e-6f);
;         const float* bp = bias + (size_t)((u.pm * BM) / S_) * 4096 + col0;
; #pragma unroll
;         for (int bj = 0; bj < 2; ++bj) {
;           f32x4 v0 = acc[ai][bj][m][0] * rstd + *(const f32x4*)(bp + bj * HALF);
;           f32x4 v1 = acc[ai][bj][m][1] * rstd + *(const f32x4*)(bp + bj * HALF + 4);
; #pragma unroll
;           for (int j = 0; j < 4; ++j) { v0[j] = fmaxf(v0[j], 0.f); v0[j] *= v0[j]; v1[j] = fmaxf(v1[j], 0.f); v1[j] *= v1[j]; }
;           u32x4 w;
;           w.x = pk2(v0[0], v0[1]); w.y = pk2(v0[2], v0[3]); w.z = pk2(v1[0], v1[1]); w.w = pk2(v1[2], v1[3]);
;           *(u32x4*)(rowp + bj * HALF) = w;
;         }
	v_pk_mul_f32 v[42:43], v[42:43], v[42:43]
	v_pk_mul_f32 v[48:49], v[48:49], v[48:49]
	v_pk_mul_f32 v[44:45], v[44:45], v[44:45]
	v_cvt_pk_bf16_f32 v46, v46, v47
	v_cvt_pk_bf16_f32 v47, v48, v49
	v_cvt_pk_bf16_f32 v48, v42, v43
	v_cvt_pk_bf16_f32 v49, v44, v45
	global_store_dwordx4 v[192:193], v[46:49], off
	v_pk_fma_f32 v[40:41], v[40:41], v[186:187], v[178:179] op_sel_hi:[1,0,1]
	v_pk_fma_f32 v[38:39], v[38:39], v[186:187], v[176:177] op_sel_hi:[1,0,1]
	v_pk_fma_f32 v[36:37], v[36:37], v[186:187], v[182:183] op_sel_hi:[1,0,1]
	v_pk_fma_f32 v[34:35], v[34:35], v[186:187], v[180:181] op_sel_hi:[1,0,1]
	v_max_f32_e32 v38, 0, v38
	v_max_f32_e32 v34, 0, v34
	v_max_f32_e32 v39, 0, v39
	v_max_f32_e32 v35, 0, v35
	v_max_f32_e32 v40, 0, v40
	v_max_f32_e32 v36, 0, v36
	v_max_f32_e32 v41, 0, v41
	v_max_f32_e32 v37, 0, v37
	v_pk_mul_f32 v[38:39], v[38:39], v[38:39]
	v_pk_mul_f32 v[34:35], v[34:35], v[34:35]
	v_pk_mul_f32 v[40:41], v[40:41], v[40:41]
	v_pk_mul_f32 v[36:37], v[36:37], v[36:37]
	v_cvt_pk_bf16_f32 v38, v38, v39
	v_cvt_pk_bf16_f32 v39, v40, v41
	v_cvt_pk_bf16_f32 v40, v34, v35
	v_cvt_pk_bf16_f32 v41, v36, v37
	global_store_dwordx4 v[192:193], v[38:41], off offset:256
	s_mov_b64 s[6:7], 0x140000
	v_lshl_add_u64 v[192:193], v[140:141], 0, s[6:7]
	v_pk_fma_f32 v[30:31], v[30:31], v[188:189], v[160:161] op_sel_hi:[1,0,1]
	v_pk_fma_f32 v[28:29], v[28:29], v[188:189], v[158:159] op_sel_hi:[1,0,1]
	v_pk_fma_f32 v[26:27], v[26:27], v[188:189], v[164:165] op_sel_hi:[1,0,1]
	v_pk_fma_f32 v[24:25], v[24:25], v[188:189], v[162:163] op_sel_hi:[1,0,1]
	v_max_f32_e32 v28, 0, v28
	v_max_f32_e32 v24, 0, v24
	v_max_f32_e32 v29, 0, v29
	v_max_f32_e32 v25, 0, v25
	v_max_f32_e32 v30, 0, v30
	v_max_f32_e32 v26, 0, v26
	v_max_f32_e32 v31, 0, v31
	v_max_f32_e32 v27, 0, v27
	v_pk_mul_f32 v[28:29], v[28:29], v[28:29]
	v_pk_mul_f32 v[24:25], v[24:25], v[24:25]
	v_pk_mul_f32 v[30:31], v[30:31], v[30:31]
	v_pk_mul_f32 v[26:27], v[26:27], v[26:27]
	v_cvt_pk_bf16_f32 v28, v28, v29
	v_cvt_pk_bf16_f32 v29, v30, v31
	v_cvt_pk_bf16_f32 v30, v24, v25
	v_cvt_pk_bf16_f32 v31, v26, v27
	global_store_dwordx4 v[192:193], v[28:31], off
	v_pk_fma_f32 v[22:23], v[22:23], v[188:189], v[178:179] op_sel_hi:[1,0,1]
	v_pk_fma_f32 v[20:21], v[20:21], v[188:189], v[176:177] op_sel_hi:[1,0,1]
	v_pk_fma_f32 v[18:19], v[18:19], v[188:189], v[182:183] op_sel_hi:[1,0,1]
	v_pk_fma_f32 v[16:17], v[16:17], v[188:189], v[180:181] op_sel_hi:[1,0,1]
	v_max_f32_e32 v20, 0, v20
	v_max_f32_e32 v16, 0, v16
	v_max_f32_e32 v21, 0, v21
	v_max_f32_e32 v17, 0, v17
	v_max_f32_e32 v22, 0, v22
	v_max_f32_e32 v18, 0, v18
	v_max_f32_e32 v23, 0, v23
	v_max_f32_e32 v19, 0, v19
	v_pk_mul_f32 v[20:21], v[20:21], v[20:21]
	v_pk_mul_f32 v[16:17], v[16:17], v[16:17]
	v_pk_mul_f32 v[22:23], v[22:23], v[22:23]
	v_pk_mul_f32 v[18:19], v[18:19], v[18:19]
	v_cvt_pk_bf16_f32 v20, v20, v21
	v_cvt_pk_bf16_f32 v21, v22, v23
	v_cvt_pk_bf16_f32 v22, v16, v17
	v_cvt_pk_bf16_f32 v23, v18, v19
	global_store_dwordx4 v[192:193], v[20:23], off offset:256
	s_mov_b64 s[6:7], 0x160000
	v_lshl_add_u64 v[192:193], v[140:141], 0, s[6:7]
	v_pk_fma_f32 v[14:15], v[14:15], v[190:191], v[160:161] op_sel_hi:[1,0,1]
	v_pk_fma_f32 v[12:13], v[12:13], v[190:191], v[158:159] op_sel_hi:[1,0,1]
	v_pk_fma_f32 v[10:11], v[10:11], v[190:191], v[164:165] op_sel_hi:[1,0,1]
	v_pk_fma_f32 v[8:9], v[8:9], v[190:191], v[162:163] op_sel_hi:[1,0,1]
	v_max_f32_e32 v12, 0, v12
	v_max_f32_e32 v8, 0, v8
	v_max_f32_e32 v13, 0, v13
	v_max_f32_e32 v9, 0, v9
	v_max_f32_e32 v14, 0, v14
	v_max_f32_e32 v10, 0, v10
	v_max_f32_e32 v15, 0, v15
	v_max_f32_e32 v11, 0, v11
	v_pk_mul_f32 v[12:13], v[12:13], v[12:13]
	v_pk_mul_f32 v[8:9], v[8:9], v[8:9]
	v_pk_mul_f32 v[14:15], v[14:15], v[14:15]
	v_pk_mul_f32 v[10:11], v[10:11], v[10:11]
	v_cvt_pk_bf16_f32 v12, v12, v13
	v_cvt_pk_bf16_f32 v13, v14, v15
	v_cvt_pk_bf16_f32 v14, v8, v9
	v_cvt_pk_bf16_f32 v15, v10, v11
	global_store_dwordx4 v[192:193], v[12:15], off
	v_pk_fma_f32 v[6:7], v[6:7], v[190:191], v[178:179] op_sel_hi:[1,0,1]
	v_pk_fma_f32 v[4:5], v[4:5], v[190:191], v[176:177] op_sel_hi:[1,0,1]
	v_pk_fma_f32 v[2:3], v[2:3], v[190:191], v[182:183] op_sel_hi:[1,0,1]
	v_pk_fma_f32 v[0:1], v[0:1], v[190:191], v[180:181] op_sel_hi:[1,0,1]
	v_max_f32_e32 v4, 0, v4
	v_max_f32_e32 v0, 0, v0
	v_max_f32_e32 v5, 0, v5
	v_max_f32_e32 v1, 0, v1
	v_max_f32_e32 v6, 0, v6
	v_max_f32_e32 v2, 0, v2
	v_max_f32_e32 v7, 0, v7
	v_max_f32_e32 v3, 0, v3
	v_pk_mul_f32 v[4:5], v[4:5], v[4:5]
	v_pk_mul_f32 v[0:1], v[0:1], v[0:1]
	v_pk_mul_f32 v[6:7], v[6:7], v[6:7]
	v_pk_mul_f32 v[2:3], v[2:3], v[2:3]
	v_cvt_pk_bf16_f32 v4, v4, v5
	v_cvt_pk_bf16_f32 v5, v6, v7
	v_cvt_pk_bf16_f32 v6, v0, v1
	v_cvt_pk_bf16_f32 v7, v2, v3
	global_store_dwordx4 v[192:193], v[4:7], off offset:256
	s_cbranch_vccz .LBB0_228
	s_waitcnt vmcnt(0)
	s_cmpk_gt_u32 s20, 0xff
	s_cbranch_scc1 .LBB0_239
	s_barrier

;   DI bool operator()(f32x4 (&acc)[2][2][4][2], const Unit& u, int, int, int, int) const {
;     ...
; #pragma unroll
;           for (int bj = 0; bj < 2; ++bj)
; #pragma unroll
;             for (int n = 0; n < 2; ++n) acc[ai][bj][m][n] *= f;
;         }
;       if (u.kg < 3) return true;
;     ...
;       f32x4 gv[2][2], gm[2][2];
; #pragma unroll
;       for (int bj = 0; bj < 2; ++bj)
; #pragma unroll
;         for (int n = 0; n < 2; ++n) {
;           const int c = col0l + bj * HALF + n * 16;
;           gv[bj][n] = *(const f32x4*)(g + c);
;           gm[bj][n] = *(const f32x4*)(gain2 + c) * (*(const f32x4*)(sc2 + (size_t)b * 6144 + c) + 1.f);
;         }
.LBB0_292:
	v_pk_mul_f32 v[26:27], v[6:7], v[170:171] op_sel_hi:[1,0]
	v_pk_mul_f32 v[24:25], v[4:5], v[170:171] op_sel_hi:[1,0]
	v_pk_mul_f32 v[18:19], v[2:3], v[170:171] op_sel_hi:[1,0]
	v_pk_mul_f32 v[16:17], v[0:1], v[170:171] op_sel_hi:[1,0]
	v_pk_mul_f32 v[6:7], v[40:41], v[170:171] op_sel_hi:[1,0]
	v_pk_mul_f32 v[4:5], v[38:39], v[170:171] op_sel_hi:[1,0]
	v_pk_mul_f32 v[2:3], v[36:37], v[170:171] op_sel_hi:[1,0]
	v_pk_mul_f32 v[0:1], v[34:35], v[170:171] op_sel_hi:[1,0]
	v_pk_mul_f32 v[40:41], v[14:15], v[168:169] op_sel_hi:[1,0]
	v_pk_mul_f32 v[38:39], v[12:13], v[168:169] op_sel_hi:[1,0]
	v_pk_mul_f32 v[36:37], v[10:11], v[168:169] op_sel_hi:[1,0]
	v_pk_mul_f32 v[34:35], v[8:9], v[168:169] op_sel_hi:[1,0]
	v_pk_mul_f32 v[14:15], v[56:57], v[168:169] op_sel_hi:[1,0]
	v_pk_mul_f32 v[12:13], v[54:55], v[168:169] op_sel_hi:[1,0]
	v_pk_mul_f32 v[10:11], v[52:53], v[168:169] op_sel_hi:[1,0]
	v_pk_mul_f32 v[8:9], v[50:51], v[168:169] op_sel_hi:[1,0]
	v_pk_mul_f32 v[56:57], v[30:31], v[128:129] op_sel_hi:[1,0]
	v_pk_mul_f32 v[54:55], v[28:29], v[128:129] op_sel_hi:[1,0]
	v_pk_mul_f32 v[52:53], v[22:23], v[128:129] op_sel_hi:[1,0]
	v_pk_mul_f32 v[50:51], v[20:21], v[128:129] op_sel_hi:[1,0]
	v_pk_mul_f32 v[30:31], v[96:97], v[128:129] op_sel_hi:[1,0]
	v_pk_mul_f32 v[28:29], v[94:95], v[128:129] op_sel_hi:[1,0]
	v_pk_mul_f32 v[22:23], v[92:93], v[128:129] op_sel_hi:[1,0]
	v_pk_mul_f32 v[20:21], v[90:91], v[128:129] op_sel_hi:[1,0]
	v_pk_mul_f32 v[96:97], v[72:73], v[126:127] op_sel_hi:[1,0]
	v_pk_mul_f32 v[94:95], v[70:71], v[126:127] op_sel_hi:[1,0]
	v_pk_mul_f32 v[92:93], v[68:69], v[126:127] op_sel_hi:[1,0]
	v_pk_mul_f32 v[90:91], v[66:67], v[126:127] op_sel_hi:[1,0]
	v_pk_mul_f32 v[72:73], v[112:113], v[126:127] op_sel_hi:[1,0]
	v_pk_mul_f32 v[70:71], v[110:111], v[126:127] op_sel_hi:[1,0]
	v_pk_mul_f32 v[68:69], v[108:109], v[126:127] op_sel_hi:[1,0]
	v_pk_mul_f32 v[66:67], v[106:107], v[126:127] op_sel_hi:[1,0]
	v_pk_mul_f32 v[112:113], v[80:81], v[124:125] op_sel_hi:[1,0]
	v_pk_mul_f32 v[110:111], v[78:79], v[124:125] op_sel_hi:[1,0]
	v_pk_mul_f32 v[108:109], v[76:77], v[124:125] op_sel_hi:[1,0]
	v_pk_mul_f32 v[106:107], v[74:75], v[124:125] op_sel_hi:[1,0]
	v_pk_mul_f32 v[80:81], v[120:121], v[124:125] op_sel_hi:[1,0]
	v_pk_mul_f32 v[78:79], v[118:119], v[124:125] op_sel_hi:[1,0]
	v_pk_mul_f32 v[76:77], v[116:117], v[124:125] op_sel_hi:[1,0]
	v_pk_mul_f32 v[74:75], v[114:115], v[124:125] op_sel_hi:[1,0]
	v_pk_mul_f32 v[120:121], v[88:89], v[122:123] op_sel_hi:[1,0]
	v_pk_mul_f32 v[118:119], v[86:87], v[122:123] op_sel_hi:[1,0]
	v_pk_mul_f32 v[116:117], v[84:85], v[122:123] op_sel_hi:[1,0]
	v_pk_mul_f32 v[114:115], v[82:83], v[122:123] op_sel_hi:[1,0]
	v_pk_mul_f32 v[88:89], v[104:105], v[122:123] op_sel_hi:[1,0]
	v_pk_mul_f32 v[86:87], v[102:103], v[122:123] op_sel_hi:[1,0]
	v_pk_mul_f32 v[84:85], v[100:101], v[122:123] op_sel_hi:[1,0]
	v_pk_mul_f32 v[82:83], v[98:99], v[122:123] op_sel_hi:[1,0]
	v_pk_mul_f32 v[122:123], v[42:43], v[150:151] op_sel_hi:[1,0]
	v_cndmask_b32_e64 v42, 0, 1, s[22:23]
	v_pk_mul_f32 v[128:129], v[48:49], v[150:151] op_sel_hi:[1,0]
	v_pk_mul_f32 v[126:127], v[46:47], v[150:151] op_sel_hi:[1,0]
	v_pk_mul_f32 v[124:125], v[44:45], v[150:151] op_sel_hi:[1,0]
	v_pk_mul_f32 v[104:105], v[64:65], v[150:151] op_sel_hi:[1,0]
	v_pk_mul_f32 v[102:103], v[62:63], v[150:151] op_sel_hi:[1,0]
	v_pk_mul_f32 v[100:101], v[60:61], v[150:151] op_sel_hi:[1,0]
	v_pk_mul_f32 v[98:99], v[58:59], v[150:151] op_sel_hi:[1,0]
	v_pk_mul_f32 v[64:65], v[136:137], v[152:153] op_sel_hi:[1,0]
	v_pk_mul_f32 v[62:63], v[134:135], v[152:153] op_sel_hi:[1,0]
	v_pk_mul_f32 v[60:61], v[132:133], v[152:153] op_sel_hi:[1,0]
	v_pk_mul_f32 v[58:59], v[130:131], v[152:153] op_sel_hi:[1,0]
	v_pk_mul_f32 v[48:49], v[144:145], v[152:153] op_sel_hi:[1,0]
	v_pk_mul_f32 v[46:47], v[142:143], v[152:153] op_sel_hi:[1,0]
	v_pk_mul_f32 v[44:45], v[140:141], v[152:153] op_sel_hi:[1,0]
	v_cmp_ne_u32_e64 s[6:7], 1, v42
	s_andn2_b64 vcc, exec, s[22:23]
	v_pk_mul_f32 v[42:43], v[138:139], v[152:153] op_sel_hi:[1,0]
	s_cbranch_vccnz .LBB0_310
	v_bfe_u32 v164, v196, 4, 2
	v_lshrrev_b32_e32 v130, 1, v196
	v_and_b32_e32 v130, 0x60, v130
	v_lshlrev_b32_e32 v131, 2, v164
	s_lshl_b32 s8, s39, 8
	v_or3_b32 v180, v130, s8, v131
	s_ashr_i32 s8, s38, 31
	s_lshr_b32 s8, s8, 26
	s_add_i32 s8, s38, s8
	s_ashr_i32 s8, s8, 6
	s_mul_i32 s22, s8, 0x6000
	s_mul_hi_i32 s23, s8, 0x6000
	s_add_u32 s8, s67, s22
	s_addc_u32 s9, s68, s23
	s_add_u32 s22, s69, s22
	v_ashrrev_i32_e32 v181, 31, v180
	s_addc_u32 s23, s70, s23
	v_lshlrev_b64 v[134:135], 2, v[180:181]
	v_lshl_add_u64 v[162:163], s[22:23], 0, v[134:135]
	v_lshl_add_u64 v[158:159], s[8:9], 0, v[134:135]
	v_lshl_add_u64 v[160:161], s[20:21], 0, v[134:135]
	global_load_dwordx4 v[134:137], v[162:163], off
	global_load_dwordx4 v[130:133], v[160:161], off
	global_load_dwordx4 v[142:145], v[158:159], off
	v_cmp_eq_u32_e32 vcc, 0, v164
	s_waitcnt vmcnt(0)
	v_pk_add_f32 v[136:137], v[136:137], 1.0 op_sel_hi:[1,0]
	v_pk_add_f32 v[134:135], v[134:135], 1.0 op_sel_hi:[1,0]
	v_pk_mul_f32 v[176:177], v[132:133], v[136:137]
	v_pk_mul_f32 v[178:179], v[130:131], v[134:135]
	global_load_dwordx4 v[138:141], v[158:159], off offset:64
	global_load_dwordx4 v[130:133], v[160:161], off offset:64
	global_load_dwordx4 v[134:137], v[162:163], off offset:64
	s_waitcnt vmcnt(0)
	v_pk_add_f32 v[136:137], v[136:137], 1.0 op_sel_hi:[1,0]
	v_pk_add_f32 v[134:135], v[134:135], 1.0 op_sel_hi:[1,0]
	v_pk_mul_f32 v[172:173], v[132:133], v[136:137]
	v_pk_mul_f32 v[174:175], v[130:131], v[134:135]
	global_load_dwordx4 v[134:137], v[158:159], off offset:512
	global_load_dwordx4 v[130:133], v[160:161], off offset:512
	global_load_dwordx4 v[150:153], v[162:163], off offset:512
	s_waitcnt vmcnt(0)
; DI unsigned pk2(float a, float b) { f2_t v = {a, b}; bf2_t r = __builtin_convertvector(v, bf2_t); return __builtin_bit_cast(unsigned, r); }
; DI float shx(float v, int lane, int mask) { return __int_as_float(__builtin_amdgcn_ds_bpermute((lane ^ mask) << 2, __float_as_int(v))); }
;   DI bool operator()(f32x4 (&acc)[2][2][4][2], const Unit& u, int, int, int, int) const {
;     ...
;           gm[bj][n] = *(const f32x4*)(gain2 + c) * (*(const f32x4*)(sc2 + (size_t)b * 6144 + c) + 1.f);
;         }
;       const int lane = tid_ & 63;
; #pragma unroll
;       for (int ai = 0; ai < 2; ++ai)
; #pragma unroll
;         for (int m = 0; m < 4; ++m) {
;           const int r = row0 + ai * HALF + m * 16;
;           float ps = 0.f;
; #pragma unroll
;           for (int bj = 0; bj < 2; ++bj)
; #pragma unroll
;             for (int n = 0; n < 2; ++n) {
;               const size_t o = (size_t)r * 1024 + col0l + bj * HALF + n * 16;
;               const f32x4 xv = *(const f32x4*)(xsrc + o) + gv[bj][n] * acc[ai][bj][m][n];
;               *(f32x4*)(xdst + o) = xv;
;               ps += xv[0] * xv[0] + xv[1] * xv[1] + xv[2] * xv[2] + xv[3] * xv[3];
;               const f32x4 hv = xv * gm[bj][n];
;               u32x2 w;
;               w.x = pk2(hv[0], hv[1]); w.y = pk2(hv[2], hv[3]);
;               *(u32x2*)(hb + o) = w;
;             }
;           ps += shx(ps, lane, 16);
;           ps += shx(ps, lane, 32);
;           if (fq == 0) atomicAdd(rowss + r, ps);
;         }
	v_pk_add_f32 v[152:153], v[152:153], 1.0 op_sel_hi:[1,0]
	v_pk_add_f32 v[150:151], v[150:151], 1.0 op_sel_hi:[1,0]
	v_pk_mul_f32 v[168:169], v[132:133], v[152:153]
	v_pk_mul_f32 v[170:171], v[130:131], v[150:151]
	global_load_dwordx4 v[130:133], v[158:159], off offset:576
	global_load_dwordx4 v[150:153], v[160:161], off offset:576
	s_nop 0
	global_load_dwordx4 v[158:161], v[162:163], off offset:576
	s_waitcnt vmcnt(0)
	v_pk_add_f32 v[158:159], v[158:159], 1.0 op_sel_hi:[1,0]
	s_nop 0
	v_pk_mul_f32 v[150:151], v[150:151], v[158:159]
	v_lshlrev_b32_e32 v158, 2, v196
	v_bitop3_b32 v218, v158, 64, v211 bitop3:0x6c
	v_bitop3_b32 v217, v158, s84, v211 bitop3:0x6c
	v_pk_add_f32 v[160:161], v[160:161], 1.0 op_sel_hi:[1,0]
	s_load_dwordx2 s[8:9], s[0:1], 0x188
	v_pk_mul_f32 v[152:153], v[152:153], v[160:161]
	v_lshlrev_b64 v[228:229], 10, v[186:187]
	v_lshl_add_u64 v[228:229], v[228:229], 0, v[180:181]
	v_lshl_add_u64 v[188:189], v[228:229], 1, s[12:13]
	v_lshlrev_b64 v[228:229], 2, v[228:229]
	v_lshl_add_u64 v[182:183], s[18:19], 0, v[228:229]
	v_lshl_add_u64 v[184:185], s[10:11], 0, v[228:229]
	s_waitcnt lgkmcnt(0)
	v_lshl_add_u64 v[186:187], v[186:187], 2, s[8:9]
	v_mov_b64_e32 v[194:195], v[182:183]
	global_load_dwordx4 v[158:161], v[194:195], off
	global_load_dwordx4 v[162:165], v[194:195], off offset:64
	global_load_dwordx4 v[196:199], v[194:195], off offset:512
	global_load_dwordx4 v[250:253], v[194:195], off offset:576
	s_mov_b64 s[8:9], 0x10000
	v_lshl_add_u64 v[194:195], v[182:183], 0, s[8:9]
	global_load_dwordx4 v[220:223], v[194:195], off
	global_load_dwordx4 v[224:227], v[194:195], off offset:64
	v_mov_b64_e32 v[190:191], v[184:185]
	v_mov_b64_e32 v[192:193], v[188:189]
	s_waitcnt vmcnt(5)
	v_pk_fma_f32 v[158:159], v[126:127], v[142:143], v[158:159]
	s_nop 0
	v_mul_f32_e32 v200, v159, v159
	v_pk_fma_f32 v[160:161], v[128:129], v[144:145], v[160:161]
	v_fmac_f32_e32 v200, v158, v158
	v_fmac_f32_e32 v200, v160, v160
	global_store_dwordx4 v[190:191], v[158:161], off
	v_fmac_f32_e32 v200, v161, v161
	s_nop 0
	v_pk_mul_f32 v[160:161], v[176:177], v[160:161]
	v_pk_mul_f32 v[158:159], v[178:179], v[158:159]
	s_nop 0
	v_cvt_pk_bf16_f32 v158, v158, v159
	v_cvt_pk_bf16_f32 v159, v160, v161
	global_store_dwordx2 v[192:193], v[158:159], off
	global_load_dwordx4 v[158:161], v[194:195], off offset:512
	s_waitcnt vmcnt(7)
	v_pk_fma_f32 v[162:163], v[122:123], v[138:139], v[162:163]
	s_nop 0
	v_mul_f32_e32 v201, v163, v163
	v_pk_fma_f32 v[164:165], v[124:125], v[140:141], v[164:165]
	v_fmac_f32_e32 v201, v162, v162
	v_fmac_f32_e32 v201, v164, v164
	global_store_dwordx4 v[190:191], v[162:165], off offset:64
	v_fmac_f32_e32 v201, v165, v165
	v_add_f32_e32 v200, v200, v201
	v_pk_mul_f32 v[164:165], v[172:173], v[164:165]
	v_pk_mul_f32 v[162:163], v[174:175], v[162:163]
	s_nop 0
	v_cvt_pk_bf16_f32 v162, v162, v163
	v_cvt_pk_bf16_f32 v163, v164, v165
	global_store_dwordx2 v[192:193], v[162:163], off offset:32
	global_load_dwordx4 v[162:165], v[194:195], off offset:576
	s_waitcnt vmcnt(9)
	v_pk_fma_f32 v[196:197], v[102:103], v[134:135], v[196:197]
	s_nop 0
	v_mul_f32_e32 v201, v197, v197
	v_pk_fma_f32 v[198:199], v[104:105], v[136:137], v[198:199]
	v_fmac_f32_e32 v201, v196, v196
	v_fmac_f32_e32 v201, v198, v198
	global_store_dwordx4 v[190:191], v[196:199], off offset:512
	v_fmac_f32_e32 v201, v199, v199
	v_add_f32_e32 v200, v200, v201
	v_pk_mul_f32 v[198:199], v[168:169], v[198:199]
	v_pk_mul_f32 v[196:197], v[170:171], v[196:197]
	s_nop 0
	v_cvt_pk_bf16_f32 v196, v196, v197
	v_cvt_pk_bf16_f32 v197, v198, v199
	global_store_dwordx2 v[192:193], v[196:197], off offset:256
	s_mov_b64 s[8:9], 0x20000
	v_lshl_add_u64 v[194:195], v[182:183], 0, s[8:9]
	global_load_dwordx4 v[196:199], v[194:195], off
	s_waitcnt vmcnt(11)
	v_pk_fma_f32 v[250:251], v[98:99], v[130:131], v[250:251]
	s_nop 0
	v_mul_f32_e32 v201, v251, v251
	v_pk_fma_f32 v[252:253], v[100:101], v[132:133], v[252:253]
	v_fmac_f32_e32 v201, v250, v250
	v_fmac_f32_e32 v201, v252, v252
	global_store_dwordx4 v[190:191], v[250:253], off offset:576
	v_fmac_f32_e32 v201, v253, v253
	v_add_f32_e32 v200, v200, v201
	v_pk_mul_f32 v[252:253], v[152:153], v[252:253]
	v_pk_mul_f32 v[250:251], v[150:151], v[250:251]
	s_nop 0
	v_cvt_pk_bf16_f32 v250, v250, v251
	v_cvt_pk_bf16_f32 v251, v252, v253
	global_store_dwordx2 v[192:193], v[250:251], off offset:288
	ds_bpermute_b32 v219, v218, v200
	s_waitcnt lgkmcnt(0)
	v_add_f32_e32 v228, v200, v219
	ds_bpermute_b32 v229, v217, v228
	s_and_saveexec_b64 s[22:23], vcc
	s_cbranch_execz .Lop_noatom0
	s_waitcnt lgkmcnt(0)
	v_add_f32_e32 v219, v228, v229
	global_atomic_add_f32 v[186:187], v219, off
; DI unsigned pk2(float a, float b) { f2_t v = {a, b}; bf2_t r = __builtin_convertvector(v, bf2_t); return __builtin_bit_cast(unsigned, r); }
; DI float shx(float v, int lane, int mask) { return __int_as_float(__builtin_amdgcn_ds_bpermute((lane ^ mask) << 2, __float_as_int(v))); }
;   DI bool operator()(f32x4 (&acc)[2][2][4][2], const Unit& u, int, int, int, int) const {
;     ...
;       const int lane = tid_ & 63;
; #pragma unroll
;       for (int ai = 0; ai < 2; ++ai)
; #pragma unroll
;         for (int m = 0; m < 4; ++m) {
;           const int r = row0 + ai * HALF + m * 16;
;           float ps = 0.f;
; #pragma unroll
;           for (int bj = 0; bj < 2; ++bj)
; #pragma unroll
;             for (int n = 0; n < 2; ++n) {
;               const size_t o = (size_t)r * 1024 + col0l + bj * HALF + n * 16;
;               const f32x4 xv = *(const f32x4*)(xsrc + o) + gv[bj][n] * acc[ai][bj][m][n];
;               *(f32x4*)(xdst + o) = xv;
;               ps += xv[0] * xv[0] + xv[1] * xv[1] + xv[2] * xv[2] + xv[3] * xv[3];
;               const f32x4 hv = xv * gm[bj][n];
;               u32x2 w;
;               w.x = pk2(hv[0], hv[1]); w.y = pk2(hv[2], hv[3]);
;               *(u32x2*)(hb + o) = w;
;             }
;           ps += shx(ps, lane, 16);
;           ps += shx(ps, lane, 32);
;           if (fq == 0) atomicAdd(rowss + r, ps);
;         }
.Lop_noatom0:
	s_or_b64 exec, exec, s[22:23]
	global_load_dwordx4 v[250:253], v[194:195], off offset:64
	s_mov_b64 s[8:9], 0x10000
	v_lshl_add_u64 v[190:191], v[184:185], 0, s[8:9]
	s_mov_b64 s[8:9], 0x8000
	v_lshl_add_u64 v[192:193], v[188:189], 0, s[8:9]
	s_waitcnt vmcnt(14)
	v_pk_fma_f32 v[220:221], v[118:119], v[142:143], v[220:221]
	s_nop 0
	v_mul_f32_e32 v200, v221, v221
	v_pk_fma_f32 v[222:223], v[120:121], v[144:145], v[222:223]
	v_fmac_f32_e32 v200, v220, v220
	v_fmac_f32_e32 v200, v222, v222
	global_store_dwordx4 v[190:191], v[220:223], off
	v_fmac_f32_e32 v200, v223, v223
	s_nop 0
	v_pk_mul_f32 v[222:223], v[176:177], v[222:223]
	v_pk_mul_f32 v[220:221], v[178:179], v[220:221]
	s_nop 0
	v_cvt_pk_bf16_f32 v220, v220, v221
	v_cvt_pk_bf16_f32 v221, v222, v223
	global_store_dwordx2 v[192:193], v[220:221], off
	global_load_dwordx4 v[220:223], v[194:195], off offset:512
	s_waitcnt vmcnt(16)
	v_pk_fma_f32 v[224:225], v[114:115], v[138:139], v[224:225]
	s_nop 0
	v_mul_f32_e32 v201, v225, v225
	v_pk_fma_f32 v[226:227], v[116:117], v[140:141], v[226:227]
	v_fmac_f32_e32 v201, v224, v224
	v_fmac_f32_e32 v201, v226, v226
	global_store_dwordx4 v[190:191], v[224:227], off offset:64
	v_fmac_f32_e32 v201, v227, v227
	v_add_f32_e32 v200, v200, v201
	v_pk_mul_f32 v[226:227], v[172:173], v[226:227]
	v_pk_mul_f32 v[224:225], v[174:175], v[224:225]
	s_nop 0
	v_cvt_pk_bf16_f32 v224, v224, v225
	v_cvt_pk_bf16_f32 v225, v226, v227
	global_store_dwordx2 v[192:193], v[224:225], off offset:32
	global_load_dwordx4 v[224:227], v[194:195], off offset:576
	s_waitcnt vmcnt(16)
	v_pk_fma_f32 v[158:159], v[86:87], v[134:135], v[158:159]
	s_nop 0
	v_mul_f32_e32 v201, v159, v159
	v_pk_fma_f32 v[160:161], v[88:89], v[136:137], v[160:161]
	v_fmac_f32_e32 v201, v158, v158
	v_fmac_f32_e32 v201, v160, v160
	global_store_dwordx4 v[190:191], v[158:161], off offset:512
	v_fmac_f32_e32 v201, v161, v161
	v_add_f32_e32 v200, v200, v201
	v_pk_mul_f32 v[160:161], v[168:169], v[160:161]
	v_pk_mul_f32 v[158:159], v[170:171], v[158:159]
	s_nop 0
	v_cvt_pk_bf16_f32 v158, v158, v159
	v_cvt_pk_bf16_f32 v159, v160, v161
	global_store_dwordx2 v[192:193], v[158:159], off offset:256
	s_mov_b64 s[8:9], 0x30000
	v_lshl_add_u64 v[194:195], v[182:183], 0, s[8:9]
	global_load_dwordx4 v[158:161], v[194:195], off
	s_waitcnt vmcnt(16)
	v_pk_fma_f32 v[162:163], v[82:83], v[130:131], v[162:163]
	s_nop 0
	v_mul_f32_e32 v201, v163, v163
	v_pk_fma_f32 v[164:165], v[84:85], v[132:133], v[164:165]
	v_fmac_f32_e32 v201, v162, v162
	v_fmac_f32_e32 v201, v164, v164
	global_store_dwordx4 v[190:191], v[162:165], off offset:576
	v_fmac_f32_e32 v201, v165, v165
	v_add_f32_e32 v200, v200, v201
	v_pk_mul_f32 v[164:165], v[152:153], v[164:165]
	v_pk_mul_f32 v[162:163], v[150:151], v[162:163]
	s_nop 0
	v_cvt_pk_bf16_f32 v162, v162, v163
	v_cvt_pk_bf16_f32 v163, v164, v165
	global_store_dwordx2 v[192:193], v[162:163], off offset:288
	ds_bpermute_b32 v219, v218, v200
	s_waitcnt lgkmcnt(0)
	v_add_f32_e32 v228, v200, v219
	ds_bpermute_b32 v229, v217, v228
	s_and_saveexec_b64 s[22:23], vcc
	s_cbranch_execz .Lop_noatom1
	s_waitcnt lgkmcnt(0)
	v_add_f32_e32 v219, v228, v229
	global_atomic_add_f32 v[186:187], v219, off offset:64
.Lop_noatom1:
	s_or_b64 exec, exec, s[22:23]
	global_load_dwordx4 v[162:165], v[194:195], off offset:64
	s_mov_b64 s[8:9], 0x20000
	v_lshl_add_u64 v[190:191], v[184:185], 0, s[8:9]
	s_mov_b64 s[8:9], 0x10000
	v_lshl_add_u64 v[192:193], v[188:189], 0, s[8:9]
	s_waitcnt vmcnt(17)
	v_pk_fma_f32 v[196:197], v[110:111], v[142:143], v[196:197]
	s_nop 0
	v_mul_f32_e32 v200, v197, v197
	v_pk_fma_f32 v[198:199], v[112:113], v[144:145], v[198:199]
	v_fmac_f32_e32 v200, v196, v196
	v_fmac_f32_e32 v200, v198, v198
	global_store_dwordx4 v[190:191], v[196:199], off
	v_fmac_f32_e32 v200, v199, v199
	s_nop 0
	v_pk_mul_f32 v[198:199], v[176:177], v[198:199]
	v_pk_mul_f32 v[196:197], v[178:179], v[196:197]
	s_nop 0
	v_cvt_pk_bf16_f32 v196, v196, v197
	v_cvt_pk_bf16_f32 v197, v198, v199
	global_store_dwordx2 v[192:193], v[196:197], off
	global_load_dwordx4 v[196:199], v[194:195], off offset:512
	s_waitcnt vmcnt(16)
	v_pk_fma_f32 v[250:251], v[106:107], v[138:139], v[250:251]
	s_nop 0
	v_mul_f32_e32 v201, v251, v251
	v_pk_fma_f32 v[252:253], v[108:109], v[140:141], v[252:253]
	v_fmac_f32_e32 v201, v250, v250
	v_fmac_f32_e32 v201, v252, v252
	global_store_dwordx4 v[190:191], v[250:253], off offset:64
	v_fmac_f32_e32 v201, v253, v253
	v_add_f32_e32 v200, v200, v201
	v_pk_mul_f32 v[252:253], v[172:173], v[252:253]
	v_pk_mul_f32 v[250:251], v[174:175], v[250:251]
	s_nop 0
	v_cvt_pk_bf16_f32 v250, v250, v251
	v_cvt_pk_bf16_f32 v251, v252, v253
	global_store_dwordx2 v[192:193], v[250:251], off offset:32
	global_load_dwordx4 v[250:253], v[194:195], off offset:576
	s_waitcnt vmcnt(16)
	v_pk_fma_f32 v[220:221], v[78:79], v[134:135], v[220:221]
	s_nop 0
	v_mul_f32_e32 v201, v221, v221
	v_pk_fma_f32 v[222:223], v[80:81], v[136:137], v[222:223]
	v_fmac_f32_e32 v201, v220, v220
	v_fmac_f32_e32 v201, v222, v222
	global_store_dwordx4 v[190:191], v[220:223], off offset:512
	v_fmac_f32_e32 v201, v223, v223
	v_add_f32_e32 v200, v200, v201
	v_pk_mul_f32 v[222:223], v[168:169], v[222:223]
	v_pk_mul_f32 v[220:221], v[170:171], v[220:221]
	s_nop 0
	v_cvt_pk_bf16_f32 v220, v220, v221
	v_cvt_pk_bf16_f32 v221, v222, v223
	global_store_dwordx2 v[192:193], v[220:221], off offset:256
	s_mov_b64 s[8:9], 0x80000
	v_lshl_add_u64 v[194:195], v[182:183], 0, s[8:9]
	global_load_dwordx4 v[220:223], v[194:195], off
	s_waitcnt vmcnt(16)
	v_pk_fma_f32 v[224:225], v[74:75], v[130:131], v[224:225]
	s_nop 0
	v_mul_f32_e32 v201, v225, v225
	v_pk_fma_f32 v[226:227], v[76:77], v[132:133], v[226:227]
	v_fmac_f32_e32 v201, v224, v224
	v_fmac_f32_e32 v201, v226, v226
	global_store_dwordx4 v[190:191], v[224:227], off offset:576
	v_fmac_f32_e32 v201, v227, v227
	v_add_f32_e32 v200, v200, v201
	v_pk_mul_f32 v[226:227], v[152:153], v[226:227]
	v_pk_mul_f32 v[224:225], v[150:151], v[224:225]
	s_nop 0
	v_cvt_pk_bf16_f32 v224, v224, v225
	v_cvt_pk_bf16_f32 v225, v226, v227
	global_store_dwordx2 v[192:193], v[224:225], off offset:288
	ds_bpermute_b32 v219, v218, v200
	s_waitcnt lgkmcnt(0)
	v_add_f32_e32 v228, v200, v219
	ds_bpermute_b32 v229, v217, v228
	s_and_saveexec_b64 s[22:23], vcc
	s_cbranch_execz .Lop_noatom2
	s_waitcnt lgkmcnt(0)
	v_add_f32_e32 v219, v228, v229
	global_atomic_add_f32 v[186:187], v219, off offset:128
; DI unsigned pk2(float a, float b) { f2_t v = {a, b}; bf2_t r = __builtin_convertvector(v, bf2_t); return __builtin_bit_cast(unsigned, r); }
; DI float shx(float v, int lane, int mask) { return __int_as_float(__builtin_amdgcn_ds_bpermute((lane ^ mask) << 2, __float_as_int(v))); }
;   DI bool operator()(f32x4 (&acc)[2][2][4][2], const Unit& u, int, int, int, int) const {
;     ...
;       const int lane = tid_ & 63;
; #pragma unroll
;       for (int ai = 0; ai < 2; ++ai)
; #pragma unroll
;         for (int m = 0; m < 4; ++m) {
;           const int r = row0 + ai * HALF + m * 16;
;           float ps = 0.f;
; #pragma unroll
;           for (int bj = 0; bj < 2; ++bj)
; #pragma unroll
;             for (int n = 0; n < 2; ++n) {
;               const size_t o = (size_t)r * 1024 + col0l + bj * HALF + n * 16;
;               const f32x4 xv = *(const f32x4*)(xsrc + o) + gv[bj][n] * acc[ai][bj][m][n];
;               *(f32x4*)(xdst + o) = xv;
;               ps += xv[0] * xv[0] + xv[1] * xv[1] + xv[2] * xv[2] + xv[3] * xv[3];
;               const f32x4 hv = xv * gm[bj][n];
;               u32x2 w;
;               w.x = pk2(hv[0], hv[1]); w.y = pk2(hv[2], hv[3]);
;               *(u32x2*)(hb + o) = w;
;             }
;           ps += shx(ps, lane, 16);
;           ps += shx(ps, lane, 32);
;           if (fq == 0) atomicAdd(rowss + r, ps);
;         }
.Lop_noatom2:
	s_or_b64 exec, exec, s[22:23]
	global_load_dwordx4 v[224:227], v[194:195], off offset:64
	s_mov_b64 s[8:9], 0x30000
	v_lshl_add_u64 v[190:191], v[184:185], 0, s[8:9]
	s_mov_b64 s[8:9], 0x18000
	v_lshl_add_u64 v[192:193], v[188:189], 0, s[8:9]
	s_waitcnt vmcnt(17)
	v_pk_fma_f32 v[158:159], v[94:95], v[142:143], v[158:159]
	s_nop 0
	v_mul_f32_e32 v200, v159, v159
	v_pk_fma_f32 v[160:161], v[96:97], v[144:145], v[160:161]
	v_fmac_f32_e32 v200, v158, v158
	v_fmac_f32_e32 v200, v160, v160
	global_store_dwordx4 v[190:191], v[158:161], off
	v_fmac_f32_e32 v200, v161, v161
	s_nop 0
	v_pk_mul_f32 v[160:161], v[176:177], v[160:161]
	v_pk_mul_f32 v[158:159], v[178:179], v[158:159]
	s_nop 0
	v_cvt_pk_bf16_f32 v158, v158, v159
	v_cvt_pk_bf16_f32 v159, v160, v161
	global_store_dwordx2 v[192:193], v[158:159], off
	global_load_dwordx4 v[158:161], v[194:195], off offset:512
	s_waitcnt vmcnt(16)
	v_pk_fma_f32 v[162:163], v[90:91], v[138:139], v[162:163]
	s_nop 0
	v_mul_f32_e32 v201, v163, v163
	v_pk_fma_f32 v[164:165], v[92:93], v[140:141], v[164:165]
	v_fmac_f32_e32 v201, v162, v162
	v_fmac_f32_e32 v201, v164, v164
	global_store_dwordx4 v[190:191], v[162:165], off offset:64
	v_fmac_f32_e32 v201, v165, v165
	v_add_f32_e32 v200, v200, v201
	v_pk_mul_f32 v[164:165], v[172:173], v[164:165]
	v_pk_mul_f32 v[162:163], v[174:175], v[162:163]
	s_nop 0
	v_cvt_pk_bf16_f32 v162, v162, v163
	v_cvt_pk_bf16_f32 v163, v164, v165
	global_store_dwordx2 v[192:193], v[162:163], off offset:32
	global_load_dwordx4 v[162:165], v[194:195], off offset:576
	s_waitcnt vmcnt(16)
	v_pk_fma_f32 v[196:197], v[70:71], v[134:135], v[196:197]
	s_nop 0
	v_mul_f32_e32 v201, v197, v197
	v_pk_fma_f32 v[198:199], v[72:73], v[136:137], v[198:199]
	v_fmac_f32_e32 v201, v196, v196
	v_fmac_f32_e32 v201, v198, v198
	global_store_dwordx4 v[190:191], v[196:199], off offset:512
	v_fmac_f32_e32 v201, v199, v199
	v_add_f32_e32 v200, v200, v201
	v_pk_mul_f32 v[198:199], v[168:169], v[198:199]
	v_pk_mul_f32 v[196:197], v[170:171], v[196:197]
	s_nop 0
	v_cvt_pk_bf16_f32 v196, v196, v197
	v_cvt_pk_bf16_f32 v197, v198, v199
	global_store_dwordx2 v[192:193], v[196:197], off offset:256
	s_mov_b64 s[8:9], 0x90000
	v_lshl_add_u64 v[194:195], v[182:183], 0, s[8:9]
	global_load_dwordx4 v[196:199], v[194:195], off
	s_waitcnt vmcnt(16)
	v_pk_fma_f32 v[250:251], v[66:67], v[130:131], v[250:251]
	s_nop 0
	v_mul_f32_e32 v201, v251, v251
	v_pk_fma_f32 v[252:253], v[68:69], v[132:133], v[252:253]
	v_fmac_f32_e32 v201, v250, v250
	v_fmac_f32_e32 v201, v252, v252
	global_store_dwordx4 v[190:191], v[250:253], off offset:576
	v_fmac_f32_e32 v201, v253, v253
	v_add_f32_e32 v200, v200, v201
	v_pk_mul_f32 v[252:253], v[152:153], v[252:253]
	v_pk_mul_f32 v[250:251], v[150:151], v[250:251]
	s_nop 0
	v_cvt_pk_bf16_f32 v250, v250, v251
	v_cvt_pk_bf16_f32 v251, v252, v253
	global_store_dwordx2 v[192:193], v[250:251], off offset:288
	ds_bpermute_b32 v219, v218, v200
	s_waitcnt lgkmcnt(0)
	v_add_f32_e32 v228, v200, v219
	ds_bpermute_b32 v229, v217, v228
	s_and_saveexec_b64 s[22:23], vcc
	s_cbranch_execz .Lop_noatom3
	s_waitcnt lgkmcnt(0)
	v_add_f32_e32 v219, v228, v229
	global_atomic_add_f32 v[186:187], v219, off offset:192
.Lop_noatom3:
	s_or_b64 exec, exec, s[22:23]
	global_load_dwordx4 v[250:253], v[194:195], off offset:64
	s_mov_b64 s[8:9], 0x80000
	v_lshl_add_u64 v[190:191], v[184:185], 0, s[8:9]
	s_mov_b64 s[8:9], 0x40000
	v_lshl_add_u64 v[192:193], v[188:189], 0, s[8:9]
	s_waitcnt vmcnt(17)
	v_pk_fma_f32 v[220:221], v[54:55], v[142:143], v[220:221]
	s_nop 0
	v_mul_f32_e32 v200, v221, v221
	v_pk_fma_f32 v[222:223], v[56:57], v[144:145], v[222:223]
	v_fmac_f32_e32 v200, v220, v220
	v_fmac_f32_e32 v200, v222, v222
	global_store_dwordx4 v[190:191], v[220:223], off
	v_fmac_f32_e32 v200, v223, v223
	s_nop 0
	v_pk_mul_f32 v[222:223], v[176:177], v[222:223]
	v_pk_mul_f32 v[220:221], v[178:179], v[220:221]
	s_nop 0
	v_cvt_pk_bf16_f32 v220, v220, v221
	v_cvt_pk_bf16_f32 v221, v222, v223
	global_store_dwordx2 v[192:193], v[220:221], off
	global_load_dwordx4 v[220:223], v[194:195], off offset:512
	s_waitcnt vmcnt(16)
	v_pk_fma_f32 v[224:225], v[50:51], v[138:139], v[224:225]
	s_nop 0
	v_mul_f32_e32 v201, v225, v225
	v_pk_fma_f32 v[226:227], v[52:53], v[140:141], v[226:227]
	v_fmac_f32_e32 v201, v224, v224
	v_fmac_f32_e32 v201, v226, v226
	global_store_dwordx4 v[190:191], v[224:227], off offset:64
	v_fmac_f32_e32 v201, v227, v227
	v_add_f32_e32 v200, v200, v201
	v_pk_mul_f32 v[226:227], v[172:173], v[226:227]
	v_pk_mul_f32 v[224:225], v[174:175], v[224:225]
	s_nop 0
	v_cvt_pk_bf16_f32 v224, v224, v225
	v_cvt_pk_bf16_f32 v225, v226, v227
	global_store_dwordx2 v[192:193], v[224:225], off offset:32
	global_load_dwordx4 v[224:227], v[194:195], off offset:576
	s_waitcnt vmcnt(16)
	v_pk_fma_f32 v[158:159], v[28:29], v[134:135], v[158:159]
	s_nop 0
	v_mul_f32_e32 v201, v159, v159
	v_pk_fma_f32 v[160:161], v[30:31], v[136:137], v[160:161]
	v_fmac_f32_e32 v201, v158, v158
	v_fmac_f32_e32 v201, v160, v160
	global_store_dwordx4 v[190:191], v[158:161], off offset:512
	v_fmac_f32_e32 v201, v161, v161
	v_add_f32_e32 v200, v200, v201
	v_pk_mul_f32 v[160:161], v[168:169], v[160:161]
	v_pk_mul_f32 v[158:159], v[170:171], v[158:159]
	s_nop 0
	v_cvt_pk_bf16_f32 v158, v158, v159
	v_cvt_pk_bf16_f32 v159, v160, v161
	global_store_dwordx2 v[192:193], v[158:159], off offset:256
	s_mov_b64 s[8:9], 0xa0000
	v_lshl_add_u64 v[194:195], v[182:183], 0, s[8:9]
	global_load_dwordx4 v[158:161], v[194:195], off
	s_waitcnt vmcnt(16)
	v_pk_fma_f32 v[162:163], v[20:21], v[130:131], v[162:163]
	s_nop 0
	v_mul_f32_e32 v201, v163, v163
	v_pk_fma_f32 v[164:165], v[22:23], v[132:133], v[164:165]
	v_fmac_f32_e32 v201, v162, v162
	v_fmac_f32_e32 v201, v164, v164
	global_store_dwordx4 v[190:191], v[162:165], off offset:576
	v_fmac_f32_e32 v201, v165, v165
	v_add_f32_e32 v200, v200, v201
	v_pk_mul_f32 v[164:165], v[152:153], v[164:165]
	v_pk_mul_f32 v[162:163], v[150:151], v[162:163]
	s_nop 0
	v_cvt_pk_bf16_f32 v162, v162, v163
	v_cvt_pk_bf16_f32 v163, v164, v165
	global_store_dwordx2 v[192:193], v[162:163], off offset:288
	ds_bpermute_b32 v219, v218, v200
	s_waitcnt lgkmcnt(0)
	v_add_f32_e32 v228, v200, v219
	ds_bpermute_b32 v229, v217, v228
	s_and_saveexec_b64 s[22:23], vcc
	s_cbranch_execz .Lop_noatom4
	s_waitcnt lgkmcnt(0)
	v_add_f32_e32 v219, v228, v229
	global_atomic_add_f32 v[186:187], v219, off offset:512
; DI unsigned pk2(float a, float b) { f2_t v = {a, b}; bf2_t r = __builtin_convertvector(v, bf2_t); return __builtin_bit_cast(unsigned, r); }
; DI float shx(float v, int lane, int mask) { return __int_as_float(__builtin_amdgcn_ds_bpermute((lane ^ mask) << 2, __float_as_int(v))); }
;   DI bool operator()(f32x4 (&acc)[2][2][4][2], const Unit& u, int, int, int, int) const {
;     ...
;       const int lane = tid_ & 63;
; #pragma unroll
;       for (int ai = 0; ai < 2; ++ai)
; #pragma unroll
;         for (int m = 0; m < 4; ++m) {
;           const int r = row0 + ai * HALF + m * 16;
;           float ps = 0.f;
; #pragma unroll
;           for (int bj = 0; bj < 2; ++bj)
; #pragma unroll
;             for (int n = 0; n < 2; ++n) {
;               const size_t o = (size_t)r * 1024 + col0l + bj * HALF + n * 16;
;               const f32x4 xv = *(const f32x4*)(xsrc + o) + gv[bj][n] * acc[ai][bj][m][n];
;               *(f32x4*)(xdst + o) = xv;
;               ps += xv[0] * xv[0] + xv[1] * xv[1] + xv[2] * xv[2] + xv[3] * xv[3];
;               const f32x4 hv = xv * gm[bj][n];
;               u32x2 w;
;               w.x = pk2(hv[0], hv[1]); w.y = pk2(hv[2], hv[3]);
;               *(u32x2*)(hb + o) = w;
;             }
;           ps += shx(ps, lane, 16);
;           ps += shx(ps, lane, 32);
;           if (fq == 0) atomicAdd(rowss + r, ps);
;         }
.Lop_noatom4:
	s_or_b64 exec, exec, s[22:23]
	global_load_dwordx4 v[162:165], v[194:195], off offset:64
	s_mov_b64 s[8:9], 0x90000
	v_lshl_add_u64 v[190:191], v[184:185], 0, s[8:9]
	s_mov_b64 s[8:9], 0x48000
	v_lshl_add_u64 v[192:193], v[188:189], 0, s[8:9]
	s_waitcnt vmcnt(17)
	v_pk_fma_f32 v[196:197], v[38:39], v[142:143], v[196:197]
	s_nop 0
	v_mul_f32_e32 v200, v197, v197
	v_pk_fma_f32 v[198:199], v[40:41], v[144:145], v[198:199]
	v_fmac_f32_e32 v200, v196, v196
	v_fmac_f32_e32 v200, v198, v198
	global_store_dwordx4 v[190:191], v[196:199], off
	v_fmac_f32_e32 v200, v199, v199
	s_nop 0
	v_pk_mul_f32 v[198:199], v[176:177], v[198:199]
	v_pk_mul_f32 v[196:197], v[178:179], v[196:197]
	s_nop 0
	v_cvt_pk_bf16_f32 v196, v196, v197
	v_cvt_pk_bf16_f32 v197, v198, v199
	global_store_dwordx2 v[192:193], v[196:197], off
	global_load_dwordx4 v[196:199], v[194:195], off offset:512
	s_waitcnt vmcnt(16)
	v_pk_fma_f32 v[250:251], v[34:35], v[138:139], v[250:251]
	s_nop 0
	v_mul_f32_e32 v201, v251, v251
	v_pk_fma_f32 v[252:253], v[36:37], v[140:141], v[252:253]
	v_fmac_f32_e32 v201, v250, v250
	v_fmac_f32_e32 v201, v252, v252
	global_store_dwordx4 v[190:191], v[250:253], off offset:64
	v_fmac_f32_e32 v201, v253, v253
	v_add_f32_e32 v200, v200, v201
	v_pk_mul_f32 v[252:253], v[172:173], v[252:253]
	v_pk_mul_f32 v[250:251], v[174:175], v[250:251]
	s_nop 0
	v_cvt_pk_bf16_f32 v250, v250, v251
	v_cvt_pk_bf16_f32 v251, v252, v253
	global_store_dwordx2 v[192:193], v[250:251], off offset:32
	global_load_dwordx4 v[250:253], v[194:195], off offset:576
	s_waitcnt vmcnt(16)
	v_pk_fma_f32 v[220:221], v[12:13], v[134:135], v[220:221]
	s_nop 0
	v_mul_f32_e32 v201, v221, v221
	v_pk_fma_f32 v[222:223], v[14:15], v[136:137], v[222:223]
	v_fmac_f32_e32 v201, v220, v220
	v_fmac_f32_e32 v201, v222, v222
	global_store_dwordx4 v[190:191], v[220:223], off offset:512
	v_fmac_f32_e32 v201, v223, v223
	v_add_f32_e32 v200, v200, v201
	v_pk_mul_f32 v[222:223], v[168:169], v[222:223]
	v_pk_mul_f32 v[220:221], v[170:171], v[220:221]
	s_nop 0
	v_cvt_pk_bf16_f32 v220, v220, v221
	v_cvt_pk_bf16_f32 v221, v222, v223
	global_store_dwordx2 v[192:193], v[220:221], off offset:256
	s_mov_b64 s[8:9], 0xb0000
	v_lshl_add_u64 v[194:195], v[182:183], 0, s[8:9]
	global_load_dwordx4 v[220:223], v[194:195], off
	s_waitcnt vmcnt(16)
	v_pk_fma_f32 v[224:225], v[8:9], v[130:131], v[224:225]
	s_nop 0
	v_mul_f32_e32 v201, v225, v225
	v_pk_fma_f32 v[226:227], v[10:11], v[132:133], v[226:227]
	v_fmac_f32_e32 v201, v224, v224
	v_fmac_f32_e32 v201, v226, v226
	global_store_dwordx4 v[190:191], v[224:227], off offset:576
	v_fmac_f32_e32 v201, v227, v227
	v_add_f32_e32 v200, v200, v201
	v_pk_mul_f32 v[226:227], v[152:153], v[226:227]
	v_pk_mul_f32 v[224:225], v[150:151], v[224:225]
	s_nop 0
	v_cvt_pk_bf16_f32 v224, v224, v225
	v_cvt_pk_bf16_f32 v225, v226, v227
	global_store_dwordx2 v[192:193], v[224:225], off offset:288
	ds_bpermute_b32 v219, v218, v200
	s_waitcnt lgkmcnt(0)
	v_add_f32_e32 v228, v200, v219
	ds_bpermute_b32 v229, v217, v228
	s_and_saveexec_b64 s[22:23], vcc
	s_cbranch_execz .Lop_noatom5
	s_waitcnt lgkmcnt(0)
	v_add_f32_e32 v219, v228, v229
	global_atomic_add_f32 v[186:187], v219, off offset:576
; DI unsigned pk2(float a, float b) { f2_t v = {a, b}; bf2_t r = __builtin_convertvector(v, bf2_t); return __builtin_bit_cast(unsigned, r); }
; DI float shx(float v, int lane, int mask) { return __int_as_float(__builtin_amdgcn_ds_bpermute((lane ^ mask) << 2, __float_as_int(v))); }
;   DI bool operator()(f32x4 (&acc)[2][2][4][2], const Unit& u, int, int, int, int) const {
;     ...
;       const int lane = tid_ & 63;
; #pragma unroll
;       for (int ai = 0; ai < 2; ++ai)
; #pragma unroll
;         for (int m = 0; m < 4; ++m) {
;           const int r = row0 + ai * HALF + m * 16;
;           float ps = 0.f;
; #pragma unroll
;           for (int bj = 0; bj < 2; ++bj)
; #pragma unroll
;             for (int n = 0; n < 2; ++n) {
;               const size_t o = (size_t)r * 1024 + col0l + bj * HALF + n * 16;
;               const f32x4 xv = *(const f32x4*)(xsrc + o) + gv[bj][n] * acc[ai][bj][m][n];
;               *(f32x4*)(xdst + o) = xv;
;               ps += xv[0] * xv[0] + xv[1] * xv[1] + xv[2] * xv[2] + xv[3] * xv[3];
;               const f32x4 hv = xv * gm[bj][n];
;               u32x2 w;
;               w.x = pk2(hv[0], hv[1]); w.y = pk2(hv[2], hv[3]);
;               *(u32x2*)(hb + o) = w;
;             }
;           ps += shx(ps, lane, 16);
;           ps += shx(ps, lane, 32);
;           if (fq == 0) atomicAdd(rowss + r, ps);
;         }
.Lop_noatom5:
	s_or_b64 exec, exec, s[22:23]
	global_load_dwordx4 v[224:227], v[194:195], off offset:64
	s_mov_b64 s[8:9], 0xa0000
	v_lshl_add_u64 v[190:191], v[184:185], 0, s[8:9]
	s_mov_b64 s[8:9], 0x50000
	v_lshl_add_u64 v[192:193], v[188:189], 0, s[8:9]
	s_waitcnt vmcnt(17)
	v_pk_fma_f32 v[158:159], v[24:25], v[142:143], v[158:159]
	s_nop 0
	v_mul_f32_e32 v200, v159, v159
	v_pk_fma_f32 v[160:161], v[26:27], v[144:145], v[160:161]
	v_fmac_f32_e32 v200, v158, v158
	v_fmac_f32_e32 v200, v160, v160
	global_store_dwordx4 v[190:191], v[158:161], off
	v_fmac_f32_e32 v200, v161, v161
	s_nop 0
	v_pk_mul_f32 v[160:161], v[176:177], v[160:161]
	v_pk_mul_f32 v[158:159], v[178:179], v[158:159]
	s_nop 0
	v_cvt_pk_bf16_f32 v158, v158, v159
	v_cvt_pk_bf16_f32 v159, v160, v161
	global_store_dwordx2 v[192:193], v[158:159], off
	global_load_dwordx4 v[158:161], v[194:195], off offset:512
	s_waitcnt vmcnt(16)
	v_pk_fma_f32 v[162:163], v[16:17], v[138:139], v[162:163]
	s_nop 0
	v_mul_f32_e32 v201, v163, v163
	v_pk_fma_f32 v[164:165], v[18:19], v[140:141], v[164:165]
	v_fmac_f32_e32 v201, v162, v162
	v_fmac_f32_e32 v201, v164, v164
	global_store_dwordx4 v[190:191], v[162:165], off offset:64
	v_fmac_f32_e32 v201, v165, v165
	v_add_f32_e32 v200, v200, v201
	v_pk_mul_f32 v[164:165], v[172:173], v[164:165]
	v_pk_mul_f32 v[162:163], v[174:175], v[162:163]
	s_nop 0
	v_cvt_pk_bf16_f32 v162, v162, v163
	v_cvt_pk_bf16_f32 v163, v164, v165
	global_store_dwordx2 v[192:193], v[162:163], off offset:32
	global_load_dwordx4 v[162:165], v[194:195], off offset:576
	s_waitcnt vmcnt(16)
	v_pk_fma_f32 v[196:197], v[4:5], v[134:135], v[196:197]
	s_nop 0
	v_mul_f32_e32 v201, v197, v197
	v_pk_fma_f32 v[198:199], v[6:7], v[136:137], v[198:199]
	v_fmac_f32_e32 v201, v196, v196
	v_fmac_f32_e32 v201, v198, v198
	global_store_dwordx4 v[190:191], v[196:199], off offset:512
	v_fmac_f32_e32 v201, v199, v199
	v_add_f32_e32 v200, v200, v201
	v_pk_mul_f32 v[198:199], v[168:169], v[198:199]
	v_pk_mul_f32 v[196:197], v[170:171], v[196:197]
	s_nop 0
	v_cvt_pk_bf16_f32 v196, v196, v197
	v_cvt_pk_bf16_f32 v197, v198, v199
	global_store_dwordx2 v[192:193], v[196:197], off offset:256
	s_waitcnt vmcnt(15)
	v_pk_fma_f32 v[250:251], v[0:1], v[130:131], v[250:251]
	s_nop 0
	v_mul_f32_e32 v201, v251, v251
	v_pk_fma_f32 v[252:253], v[2:3], v[132:133], v[252:253]
	v_fmac_f32_e32 v201, v250, v250
	v_fmac_f32_e32 v201, v252, v252
	global_store_dwordx4 v[190:191], v[250:253], off offset:576
	v_fmac_f32_e32 v201, v253, v253
	v_add_f32_e32 v200, v200, v201
	v_pk_mul_f32 v[252:253], v[152:153], v[252:253]
	v_pk_mul_f32 v[250:251], v[150:151], v[250:251]
	s_nop 0
	v_cvt_pk_bf16_f32 v250, v250, v251
	v_cvt_pk_bf16_f32 v251, v252, v253
	global_store_dwordx2 v[192:193], v[250:251], off offset:288
	ds_bpermute_b32 v219, v218, v200
	s_waitcnt lgkmcnt(0)
	v_add_f32_e32 v228, v200, v219
	ds_bpermute_b32 v229, v217, v228
	s_and_saveexec_b64 s[22:23], vcc
	s_cbranch_execz .Lop_noatom6
	s_waitcnt lgkmcnt(0)
	v_add_f32_e32 v219, v228, v229
	global_atomic_add_f32 v[186:187], v219, off offset:640
.Lop_noatom6:
	s_or_b64 exec, exec, s[22:23]
	s_mov_b64 s[8:9], 0xb0000
	v_lshl_add_u64 v[190:191], v[184:185], 0, s[8:9]
	s_mov_b64 s[8:9], 0x58000
	v_lshl_add_u64 v[192:193], v[188:189], 0, s[8:9]
	s_waitcnt vmcnt(15)
	v_pk_fma_f32 v[220:221], v[62:63], v[142:143], v[220:221]
	s_nop 0
	v_mul_f32_e32 v200, v221, v221
	v_pk_fma_f32 v[222:223], v[64:65], v[144:145], v[222:223]
	v_fmac_f32_e32 v200, v220, v220
	v_fmac_f32_e32 v200, v222, v222
	global_store_dwordx4 v[190:191], v[220:223], off
	v_fmac_f32_e32 v200, v223, v223
	s_nop 0
	v_pk_mul_f32 v[222:223], v[176:177], v[222:223]
	v_pk_mul_f32 v[220:221], v[178:179], v[220:221]
	s_nop 0
	v_cvt_pk_bf16_f32 v220, v220, v221
	v_cvt_pk_bf16_f32 v221, v222, v223
	global_store_dwordx2 v[192:193], v[220:221], off
	s_waitcnt vmcnt(13)
	v_pk_fma_f32 v[224:225], v[58:59], v[138:139], v[224:225]
	s_nop 0
	v_mul_f32_e32 v201, v225, v225
	v_pk_fma_f32 v[226:227], v[60:61], v[140:141], v[226:227]
	v_fmac_f32_e32 v201, v224, v224
	v_fmac_f32_e32 v201, v226, v226
	global_store_dwordx4 v[190:191], v[224:227], off offset:64
	v_fmac_f32_e32 v201, v227, v227
	v_add_f32_e32 v200, v200, v201
	v_pk_mul_f32 v[226:227], v[172:173], v[226:227]
	v_pk_mul_f32 v[224:225], v[174:175], v[224:225]
	s_nop 0
	v_cvt_pk_bf16_f32 v224, v224, v225
	v_cvt_pk_bf16_f32 v225, v226, v227
	global_store_dwordx2 v[192:193], v[224:225], off offset:32
	s_waitcnt vmcnt(12)
	v_pk_fma_f32 v[158:159], v[46:47], v[134:135], v[158:159]
	s_nop 0
	v_mul_f32_e32 v201, v159, v159
	v_pk_fma_f32 v[160:161], v[48:49], v[136:137], v[160:161]
	v_fmac_f32_e32 v201, v158, v158
	v_fmac_f32_e32 v201, v160, v160
	global_store_dwordx4 v[190:191], v[158:161], off offset:512
	v_fmac_f32_e32 v201, v161, v161
	v_add_f32_e32 v200, v200, v201
	v_pk_mul_f32 v[160:161], v[168:169], v[160:161]
	v_pk_mul_f32 v[158:159], v[170:171], v[158:159]
	s_nop 0
	v_cvt_pk_bf16_f32 v158, v158, v159
	v_cvt_pk_bf16_f32 v159, v160, v161
	global_store_dwordx2 v[192:193], v[158:159], off offset:256
	s_waitcnt vmcnt(11)
	v_pk_fma_f32 v[162:163], v[42:43], v[130:131], v[162:163]
	s_nop 0
	v_mul_f32_e32 v201, v163, v163
	v_pk_fma_f32 v[164:165], v[44:45], v[132:133], v[164:165]
	v_fmac_f32_e32 v201, v162, v162
	v_fmac_f32_e32 v201, v164, v164
	global_store_dwordx4 v[190:191], v[162:165], off offset:576
	v_fmac_f32_e32 v201, v165, v165
	v_add_f32_e32 v200, v200, v201
	v_pk_mul_f32 v[164:165], v[152:153], v[164:165]
	v_pk_mul_f32 v[162:163], v[150:151], v[162:163]
	s_nop 0
	v_cvt_pk_bf16_f32 v162, v162, v163
	v_cvt_pk_bf16_f32 v163, v164, v165
	global_store_dwordx2 v[192:193], v[162:163], off offset:288
	ds_bpermute_b32 v219, v218, v200
	s_waitcnt lgkmcnt(0)
	v_add_f32_e32 v228, v200, v219
	ds_bpermute_b32 v229, v217, v228
	s_and_saveexec_b64 s[22:23], vcc
	s_cbranch_execz .Lop_noatom7
	s_waitcnt lgkmcnt(0)
	v_add_f32_e32 v219, v228, v229
	global_atomic_add_f32 v[186:187], v219, off offset:704

; #define MFMA16(a, b, c) __builtin_amdgcn_mfma_f32_16x16x32_bf16((a), (b), (c), 0, 0, 0)
; DI unsigned pk2(float a, float b) { f2_t v = {a, b}; bf2_t r = __builtin_convertvector(v, bf2_t); return __builtin_bit_cast(unsigned, r); }
; DI void ssm_out_item(const CP& p, int l, int item, char* smem) {
;     ...
;       for (int s2 = 0; s2 < 32; ++s2) {
;         const fl2 bu = {__uint_as_float((unsigned)sX[s2 * 136 + lane] << 16), __uint_as_float((unsigned)sX[s2 * 136 + 64 + lane] << 16)};
;         const fl2 xs = {-x.y, x.x};
;         x = x * a_r + xs * a_i + bu;
;         const unsigned pkx = pk2(x.x, x.y);
;         sX[s2 * 136 + lane] = (u16)(pkx & 0xffffu);
;         sX[s2 * 136 + 64 + lane] = (u16)(pkx >> 16);
;       }
;       __syncthreads();
;       f32x4v ya[2];
; #pragma unroll
;       for (int nb = 0; nb < 2; ++nb) {
;         ya[nb] = (f32x4v){0.f, 0.f, 0.f, 0.f};
; #pragma unroll
;         for (int ks = 0; ks < 4; ++ks) {
;           bf16x8 xb = *(const bf16x8*)(sX + (nb * 16 + l16) * 136 + ks * 32 + q4 * 8);
;           ya[nb] = MFMA16(cf[ks], xb, ya[nb]);
;         }
;       }
.LBB0_334:
	v_add_u32_e32 v6, s39, v32
	ds_read_u16 v100, v6
	ds_read_u16 v101, v6 offset:128
	ds_read_u16 v102, v6 offset:272
	ds_read_u16 v103, v6 offset:400
	ds_read_u16 v104, v6 offset:544
	ds_read_u16 v105, v6 offset:672
	ds_read_u16 v106, v6 offset:816
	ds_read_u16 v107, v6 offset:944
	s_addk_i32 s39, 0x880
	v_xor_b32_e32 v2, 0x80000000, v83
	v_mov_b32_e32 v3, v82
	v_pk_mul_f32 v[2:3], v[74:75], v[2:3]
	s_waitcnt lgkmcnt(6)
	v_lshlrev_b32_e32 v100, 16, v100
	v_lshlrev_b32_e32 v101, 16, v101
	v_pk_fma_f32 v[2:3], v[80:81], v[82:83], v[2:3]
	s_nop 0
	v_pk_add_f32 v[0:1], v[2:3], v[100:101]
	s_nop 0
	v_cvt_pk_bf16_f32 v2, v0, v1
	ds_write_b16 v6, v2
	ds_write_b16_d16_hi v6, v2 offset:128
	v_xor_b32_e32 v4, 0x80000000, v1
	v_mov_b32_e32 v5, v0
	v_pk_mul_f32 v[4:5], v[74:75], v[4:5]
	s_waitcnt lgkmcnt(6)
	v_lshlrev_b32_e32 v102, 16, v102
	v_lshlrev_b32_e32 v103, 16, v103
	v_pk_fma_f32 v[0:1], v[80:81], v[0:1], v[4:5]
	s_nop 0
	v_pk_add_f32 v[0:1], v[0:1], v[102:103]
	s_nop 0
	v_cvt_pk_bf16_f32 v2, v0, v1
	ds_write_b16 v6, v2 offset:272
	ds_write_b16_d16_hi v6, v2 offset:400
	v_xor_b32_e32 v4, 0x80000000, v1
	v_mov_b32_e32 v5, v0
	v_pk_mul_f32 v[4:5], v[74:75], v[4:5]
	s_waitcnt lgkmcnt(6)
	v_lshlrev_b32_e32 v104, 16, v104
	v_lshlrev_b32_e32 v105, 16, v105
	v_pk_fma_f32 v[0:1], v[80:81], v[0:1], v[4:5]
	s_nop 0
	v_pk_add_f32 v[0:1], v[0:1], v[104:105]
	s_nop 0
	v_cvt_pk_bf16_f32 v2, v0, v1
	ds_write_b16 v6, v2 offset:544
	ds_write_b16_d16_hi v6, v2 offset:672
	v_xor_b32_e32 v4, 0x80000000, v1
	v_mov_b32_e32 v5, v0
	v_pk_mul_f32 v[4:5], v[74:75], v[4:5]
	s_waitcnt lgkmcnt(6)
	v_lshlrev_b32_e32 v106, 16, v106
	v_lshlrev_b32_e32 v107, 16, v107
	v_pk_fma_f32 v[0:1], v[80:81], v[0:1], v[4:5]
	s_nop 0
	v_pk_add_f32 v[0:1], v[0:1], v[106:107]
	s_nop 0
	v_cvt_pk_bf16_f32 v2, v0, v1
	ds_write_b16 v6, v2 offset:816
	ds_write_b16_d16_hi v6, v2 offset:944
	ds_read_u16 v108, v6 offset:1088
	ds_read_u16 v109, v6 offset:1216
	ds_read_u16 v110, v6 offset:1360
	ds_read_u16 v111, v6 offset:1488
	ds_read_u16 v112, v6 offset:1632
	ds_read_u16 v113, v6 offset:1760
	ds_read_u16 v114, v6 offset:1904
	ds_read_u16 v115, v6 offset:2032
	v_xor_b32_e32 v4, 0x80000000, v1
	v_mov_b32_e32 v5, v0
	v_pk_mul_f32 v[4:5], v[74:75], v[4:5]
	s_waitcnt lgkmcnt(6)
	v_lshlrev_b32_e32 v108, 16, v108
	v_lshlrev_b32_e32 v109, 16, v109
	v_pk_fma_f32 v[0:1], v[80:81], v[0:1], v[4:5]
	s_nop 0
	v_pk_add_f32 v[0:1], v[0:1], v[108:109]
	s_nop 0
	v_cvt_pk_bf16_f32 v2, v0, v1
	ds_write_b16 v6, v2 offset:1088
	ds_write_b16_d16_hi v6, v2 offset:1216
	v_xor_b32_e32 v4, 0x80000000, v1
	v_mov_b32_e32 v5, v0
	v_pk_mul_f32 v[4:5], v[74:75], v[4:5]
	s_waitcnt lgkmcnt(6)
	v_lshlrev_b32_e32 v110, 16, v110
	v_lshlrev_b32_e32 v111, 16, v111
	v_pk_fma_f32 v[0:1], v[80:81], v[0:1], v[4:5]
	s_nop 0
	v_pk_add_f32 v[0:1], v[0:1], v[110:111]
	s_nop 0
	v_cvt_pk_bf16_f32 v2, v0, v1
	ds_write_b16 v6, v2 offset:1360
	ds_write_b16_d16_hi v6, v2 offset:1488
	v_xor_b32_e32 v4, 0x80000000, v1
	v_mov_b32_e32 v5, v0
	v_pk_mul_f32 v[4:5], v[74:75], v[4:5]
	s_waitcnt lgkmcnt(6)
	v_lshlrev_b32_e32 v112, 16, v112
	v_lshlrev_b32_e32 v113, 16, v113
	v_pk_fma_f32 v[0:1], v[80:81], v[0:1], v[4:5]
	s_nop 0
	v_pk_add_f32 v[0:1], v[0:1], v[112:113]
	s_nop 0
	v_cvt_pk_bf16_f32 v2, v0, v1
	ds_write_b16 v6, v2 offset:1632
	ds_write_b16_d16_hi v6, v2 offset:1760
	v_xor_b32_e32 v4, 0x80000000, v1
	v_mov_b32_e32 v5, v0
	v_pk_mul_f32 v[4:5], v[74:75], v[4:5]
	s_waitcnt lgkmcnt(6)
	v_lshlrev_b32_e32 v114, 16, v114
	v_lshlrev_b32_e32 v115, 16, v115
	v_pk_fma_f32 v[0:1], v[80:81], v[0:1], v[4:5]
	s_nop 0
	v_pk_add_f32 v[82:83], v[0:1], v[114:115]
	s_nop 0
	v_cvt_pk_bf16_f32 v0, v82, v83
	ds_write_b16 v6, v0 offset:1904
	ds_write_b16_d16_hi v6, v0 offset:2032
	s_cmpk_eq_i32 s39, 0x2200
	s_cbranch_scc0 .LBB0_334
	s_waitcnt lgkmcnt(0)
	s_barrier
	ds_read_b128 v[0:3], v88
	ds_read_b128 v[4:7], v88 offset:64
	s_waitcnt lgkmcnt(1)
	v_mfma_f32_16x16x32_bf16 v[0:3], v[34:37], v[0:3], 0
	ds_read_b128 v[10:13], v88 offset:4416
	s_mov_b64 s[72:73], 0
	s_waitcnt lgkmcnt(1)
	v_mfma_f32_16x16x32_bf16 v[0:3], v[38:41], v[4:7], v[0:3]
	ds_read_b128 v[4:7], v88 offset:128
	s_waitcnt lgkmcnt(0)
	v_mfma_f32_16x16x32_bf16 v[0:3], v[42:45], v[4:7], v[0:3]
	ds_read_b128 v[4:7], v88 offset:192
	s_waitcnt lgkmcnt(0)
	v_mfma_f32_16x16x32_bf16 v[6:9], v[46:49], v[4:7], v[0:3]
	v_or_b32_e32 v5, s38, v84
	s_nop 3
	ds_read_b128 v[0:3], v88 offset:4352
	v_or_b32_e32 v4, s6, v5
	s_waitcnt lgkmcnt(0)
	v_mfma_f32_16x16x32_bf16 v[0:3], v[34:37], v[0:3], 0
	v_mfma_f32_16x16x32_bf16 v[0:3], v[38:41], v[10:13], v[0:3]
	ds_read_b128 v[10:13], v88 offset:4480
	s_waitcnt lgkmcnt(0)
	v_mfma_f32_16x16x32_bf16 v[0:3], v[42:45], v[10:13], v[0:3]
	ds_read_b128 v[10:13], v88 offset:4544
	s_waitcnt lgkmcnt(0)
	v_mfma_f32_16x16x32_bf16 v[0:3], v[46:49], v[10:13], v[0:3]
	v_mad_u64_u32 v[10:11], s[38:39], v4, s45, v[78:79]
	v_mad_u32_u24 v11, s7, v212, v11
	global_load_dwordx2 v[10:11], v[10:11], off offset:2816
	v_or_b32_e32 v4, 16, v4
	s_waitcnt vmcnt(0)
; DI unsigned pk2(float a, float b) { f2_t v = {a, b}; bf2_t r = __builtin_convertvector(v, bf2_t); return __builtin_bit_cast(unsigned, r); }
; DI float bflo(unsigned u) { return __uint_as_float(u << 16); }
; DI float bfhi(unsigned u) { return __uint_as_float(u & 0xffff0000u); }
; DI float gelu_tanh(float x) {
;   const float u = 0.7978845608028654f * (x + 0.044715f * x * x * x);
;   const float e = __expf(2.f * u);
;   const float th = 1.f - 2.f / (e + 1.f);
;   return 0.5f * x * (1.f + th);
; }
; DI void ssm_out_item(const CP& p, int l, int item, char* smem) {
;     ...
; #pragma unroll
;       for (int nb = 0; nb < 2; ++nb) {
;         const int s = sub * 32 + nb * 16 + l16;
;         const u32x2 uu = *(const u32x2*)(p.R + (tok0 + s) * TMW + 1408 + g * 16 + q4 * 4);
;         const float y0 = gelu_tanh(ya[nb][0] + dsk.x * bflo(uu.x));
;         const float y1 = gelu_tanh(ya[nb][1] + dsk.y * bfhi(uu.x));
;         const float y2 = gelu_tanh(ya[nb][2] + dsk.z * bflo(uu.y));
;         const float y3 = gelu_tanh(ya[nb][3] + dsk.w * bfhi(uu.y));
;         u32x2 v;
;         v.x = pk2(y0, y1); v.y = pk2(y2, y3);
;         *(u32x2*)(sY + s * 264 + g * 16 + q4 * 4) = v;
;       }
;       __syncthreads();
	v_lshlrev_b32_e32 v12, 16, v10
	v_and_b32_e32 v13, 0xffff0000, v10
	v_pk_fma_f32 v[6:7], v[50:51], v[12:13], v[6:7]
	s_nop 0
	v_mul_f32_e32 v10, 0x3d372713, v6
	v_mul_f32_e32 v10, v6, v10
	v_fma_f32 v10, v6, v10, v6
	v_mul_f32_e32 v10, 0x3f4c422a, v10
	v_add_f32_e32 v10, v10, v10
	v_mul_f32_e32 v10, 0x3fb8aa3b, v10
	v_exp_f32_e32 v12, v10
	v_mul_f32_e32 v10, 0x3d372713, v7
	v_mul_f32_e32 v10, v7, v10
	v_fma_f32 v10, v7, v10, v7
	v_mul_f32_e32 v10, 0x3f4c422a, v10
	v_add_f32_e32 v10, v10, v10
	v_mul_f32_e32 v10, 0x3fb8aa3b, v10
	v_exp_f32_e32 v13, v10
	v_pk_mul_f32 v[6:7], v[6:7], 0.5 op_sel_hi:[1,0]
	v_pk_add_f32 v[12:13], v[12:13], 1.0 op_sel_hi:[1,0]
	s_nop 0
	v_div_scale_f32 v10, s[38:39], v13, v13, 2.0
	v_rcp_f32_e32 v14, v10
	s_nop 0
	v_fma_f32 v15, -v10, v14, 1.0
	v_fmac_f32_e32 v14, v15, v14
	v_div_scale_f32 v15, vcc, 2.0, v13, 2.0
	v_mul_f32_e32 v90, v15, v14
	v_fma_f32 v91, -v10, v90, v15
	v_fmac_f32_e32 v90, v91, v14
	v_fma_f32 v10, -v10, v90, v15
	v_div_fmas_f32 v10, v10, v14, v90
	v_div_fixup_f32 v13, v10, v13, 2.0
	v_div_scale_f32 v10, s[38:39], v12, v12, 2.0
	v_rcp_f32_e32 v14, v10
	s_nop 0
	v_fma_f32 v15, -v10, v14, 1.0
	v_fmac_f32_e32 v14, v15, v14
	v_div_scale_f32 v15, vcc, 2.0, v12, 2.0
	v_mul_f32_e32 v90, v15, v14
	v_fma_f32 v91, -v10, v90, v15
	v_fmac_f32_e32 v90, v91, v14
	v_fma_f32 v10, -v10, v90, v15
	v_div_fmas_f32 v10, v10, v14, v90
	v_div_fixup_f32 v12, v10, v12, 2.0
	v_lshlrev_b32_e32 v10, 16, v11
	v_and_b32_e32 v11, 0xffff0000, v11
	v_pk_fma_f32 v[8:9], v[52:53], v[10:11], v[8:9]
	v_pk_add_f32 v[12:13], v[12:13], 1.0 op_sel_hi:[1,0] neg_lo:[1,0] neg_hi:[1,0]
	v_mul_f32_e32 v10, 0x3d372713, v8
	v_mul_f32_e32 v11, 0x3d372713, v9
	v_mul_f32_e32 v10, v8, v10
	v_mul_f32_e32 v11, v9, v11
	v_fma_f32 v10, v8, v10, v8
	v_fma_f32 v11, v9, v11, v9
	v_mul_f32_e32 v10, 0x3f4c422a, v10
	v_mul_f32_e32 v11, 0x3f4c422a, v11
	v_add_f32_e32 v10, v10, v10
	v_add_f32_e32 v11, v11, v11
	v_mul_f32_e32 v10, 0x3fb8aa3b, v10
	v_mul_f32_e32 v11, 0x3fb8aa3b, v11
	v_exp_f32_e32 v10, v10
	v_exp_f32_e32 v11, v11
	v_pk_add_f32 v[12:13], v[12:13], 1.0 op_sel_hi:[1,0]
	v_pk_mul_f32 v[8:9], v[8:9], 0.5 op_sel_hi:[1,0]
	v_pk_mul_f32 v[6:7], v[6:7], v[12:13]
	v_pk_add_f32 v[10:11], v[10:11], 1.0 op_sel_hi:[1,0]
	s_nop 0
	v_div_scale_f32 v12, s[38:39], v11, v11, 2.0
	v_rcp_f32_e32 v13, v12
	s_nop 0
	v_fma_f32 v14, -v12, v13, 1.0
	v_fmac_f32_e32 v13, v14, v13
	v_div_scale_f32 v14, vcc, 2.0, v11, 2.0
	v_mul_f32_e32 v15, v14, v13
	v_fma_f32 v90, -v12, v15, v14
	v_fmac_f32_e32 v15, v90, v13
	v_fma_f32 v12, -v12, v15, v14
	v_div_fmas_f32 v12, v12, v13, v15
	v_div_fixup_f32 v11, v12, v11, 2.0
	v_div_scale_f32 v12, s[38:39], v10, v10, 2.0
	v_rcp_f32_e32 v13, v12
	s_nop 0
	v_fma_f32 v14, -v12, v13, 1.0
	v_fmac_f32_e32 v13, v14, v13
	v_div_scale_f32 v14, vcc, 2.0, v10, 2.0
	v_mul_f32_e32 v15, v14, v13
	v_fma_f32 v90, -v12, v15, v14
	v_fmac_f32_e32 v15, v90, v13
	v_fma_f32 v12, -v12, v15, v14
	v_div_fmas_f32 v12, v12, v13, v15
	v_div_fixup_f32 v10, v12, v10, 2.0
	v_pk_add_f32 v[10:11], v[10:11], 1.0 op_sel_hi:[1,0] neg_lo:[1,0] neg_hi:[1,0]
	s_nop 0
	v_pk_add_f32 v[10:11], v[10:11], 1.0 op_sel_hi:[1,0]
	s_nop 0
	v_pk_mul_f32 v[8:9], v[8:9], v[10:11]
	v_cvt_pk_bf16_f32 v10, v6, v7
	v_mad_u32_u24 v6, v5, s88, v89
	v_mad_u64_u32 v[4:5], s[38:39], v4, s45, v[78:79]
	v_mad_u32_u24 v5, s7, v212, v5
	global_load_dwordx2 v[4:5], v[4:5], off offset:2816
	v_cvt_pk_bf16_f32 v11, v8, v9
	ds_write_b64 v6, v[10:11]
	s_waitcnt vmcnt(0)
	v_lshlrev_b32_e32 v8, 16, v4
	v_and_b32_e32 v9, 0xffff0000, v4
	v_pk_fma_f32 v[0:1], v[50:51], v[8:9], v[0:1]
	s_nop 0
	v_mul_f32_e32 v4, 0x3d372713, v0
	v_mul_f32_e32 v4, v0, v4
	v_fma_f32 v4, v0, v4, v0
	v_mul_f32_e32 v4, 0x3f4c422a, v4
	v_add_f32_e32 v4, v4, v4
	v_mul_f32_e32 v4, 0x3fb8aa3b, v4
	v_exp_f32_e32 v8, v4
	v_mul_f32_e32 v4, 0x3d372713, v1
	v_mul_f32_e32 v4, v1, v4
	v_fma_f32 v4, v1, v4, v1
	v_mul_f32_e32 v4, 0x3f4c422a, v4
	v_add_f32_e32 v4, v4, v4
	v_mul_f32_e32 v4, 0x3fb8aa3b, v4
	v_exp_f32_e32 v9, v4
	v_pk_mul_f32 v[0:1], v[0:1], 0.5 op_sel_hi:[1,0]
	v_pk_add_f32 v[8:9], v[8:9], 1.0 op_sel_hi:[1,0]
	s_nop 0
	v_div_scale_f32 v4, s[38:39], v9, v9, 2.0
	v_rcp_f32_e32 v7, v4
	s_nop 0
	v_fma_f32 v10, -v4, v7, 1.0
	v_fmac_f32_e32 v7, v10, v7
	v_div_scale_f32 v10, vcc, 2.0, v9, 2.0
	v_mul_f32_e32 v11, v10, v7
	v_fma_f32 v12, -v4, v11, v10
	v_fmac_f32_e32 v11, v12, v7
	v_fma_f32 v4, -v4, v11, v10
	v_div_fmas_f32 v4, v4, v7, v11
	v_div_fixup_f32 v9, v4, v9, 2.0
	v_div_scale_f32 v4, s[38:39], v8, v8, 2.0
	v_rcp_f32_e32 v7, v4
	s_nop 0
	v_fma_f32 v10, -v4, v7, 1.0
	v_fmac_f32_e32 v7, v10, v7
	v_div_scale_f32 v10, vcc, 2.0, v8, 2.0
	v_mul_f32_e32 v11, v10, v7
	v_fma_f32 v12, -v4, v11, v10
	v_fmac_f32_e32 v11, v12, v7
	v_fma_f32 v4, -v4, v11, v10
	v_div_fmas_f32 v4, v4, v7, v11
	v_div_fixup_f32 v8, v4, v8, 2.0
	v_lshlrev_b32_e32 v4, 16, v5
	v_and_b32_e32 v5, 0xffff0000, v5
	v_pk_fma_f32 v[2:3], v[52:53], v[4:5], v[2:3]
	v_pk_add_f32 v[8:9], v[8:9], 1.0 op_sel_hi:[1,0] neg_lo:[1,0] neg_hi:[1,0]
	v_mul_f32_e32 v4, 0x3d372713, v2
	v_mul_f32_e32 v5, 0x3d372713, v3
	v_mul_f32_e32 v4, v2, v4
	v_mul_f32_e32 v5, v3, v5
	v_fma_f32 v4, v2, v4, v2
	v_fma_f32 v5, v3, v5, v3
	v_mul_f32_e32 v4, 0x3f4c422a, v4
	v_mul_f32_e32 v5, 0x3f4c422a, v5
	v_add_f32_e32 v4, v4, v4
	v_add_f32_e32 v5, v5, v5
	v_mul_f32_e32 v4, 0x3fb8aa3b, v4
	v_mul_f32_e32 v5, 0x3fb8aa3b, v5
	v_exp_f32_e32 v4, v4
	v_exp_f32_e32 v5, v5
	v_pk_add_f32 v[8:9], v[8:9], 1.0 op_sel_hi:[1,0]
	v_pk_mul_f32 v[2:3], v[2:3], 0.5 op_sel_hi:[1,0]
	v_pk_mul_f32 v[0:1], v[0:1], v[8:9]
	v_pk_add_f32 v[4:5], v[4:5], 1.0 op_sel_hi:[1,0]
	v_cvt_pk_bf16_f32 v0, v0, v1
	v_div_scale_f32 v7, s[38:39], v5, v5, 2.0
	v_rcp_f32_e32 v8, v7
	s_nop 0
	v_fma_f32 v9, -v7, v8, 1.0
	v_fmac_f32_e32 v8, v9, v8
	v_div_scale_f32 v9, vcc, 2.0, v5, 2.0
	v_mul_f32_e32 v10, v9, v8
	v_fma_f32 v11, -v7, v10, v9
	v_fmac_f32_e32 v10, v11, v8
	v_fma_f32 v7, -v7, v10, v9
	v_div_fmas_f32 v7, v7, v8, v10
	v_div_fixup_f32 v5, v7, v5, 2.0
	v_div_scale_f32 v7, s[38:39], v4, v4, 2.0
	v_rcp_f32_e32 v8, v7
	s_mov_b32 s38, 32
	v_fma_f32 v9, -v7, v8, 1.0
	v_fmac_f32_e32 v8, v9, v8
	v_div_scale_f32 v9, vcc, 2.0, v4, 2.0
	v_mul_f32_e32 v10, v9, v8
	v_fma_f32 v11, -v7, v10, v9
	v_fmac_f32_e32 v10, v11, v8
	v_fma_f32 v7, -v7, v10, v9
	v_div_fmas_f32 v7, v7, v8, v10
	v_div_fixup_f32 v4, v7, v4, 2.0
	v_pk_add_f32 v[4:5], v[4:5], 1.0 op_sel_hi:[1,0] neg_lo:[1,0] neg_hi:[1,0]
	s_and_b64 vcc, exec, s[70:71]
	v_pk_add_f32 v[4:5], v[4:5], 1.0 op_sel_hi:[1,0]
	s_nop 0
	v_pk_mul_f32 v[2:3], v[2:3], v[4:5]
	s_nop 0
	v_cvt_pk_bf16_f32 v1, v2, v3
	ds_write_b64 v6, v[0:1] offset:8448
	s_waitcnt lgkmcnt(0)
	s_barrier
; #define MFMA32(a, b, c) __builtin_amdgcn_mfma_f32_32x32x16_bf16((a), (b), (c), 0, 0, 0)
; DI void ssm_out_item(const CP& p, int l, int item, char* smem) {
;     ...
;     }
;   }
;   __syncthreads();
;   f32x16 acc[2];
; #pragma unroll
;   for (int j = 0; j < 2; ++j)
; #pragma unroll
;     for (int r = 0; r < 16; ++r) acc[j][r] = 0.f;
;   const u16* wg = p.wt_glu + (size_t)l * 65536;
; #pragma unroll
;   for (int ks = 0; ks < 16; ++ks) {
;     bf16x8 fa, fb[2];
;     fa = *(const bf16x8*)(wg + (size_t)(w * 32 + l32) * 256 + ks * 16 + hh * 8);
; #pragma unroll
;     for (int i = 0; i < 2; ++i) fb[i] = *(const bf16x8*)(sY + (i * 32 + l32) * 264 + ks * 16 + hh * 8);
; #pragma unroll
;     for (int j = 0; j < 2; ++j) acc[j] = MFMA32(fa, fb[j], acc[j]);
;   }
	s_cbranch_vccz .LBB0_333
	s_mov_b32 s38, 1
	s_mov_b64 s[70:71], 0
	s_and_b64 vcc, exec, s[10:11]
	s_cbranch_vccz .LBB0_332
	v_lshlrev_b32_e32 v37, 5, v59
	v_or_b32_e32 v0, v37, v56
	v_ashrrev_i32_e32 v1, 31, v0
	v_lshlrev_b64 v[0:1], 9, v[0:1]
	v_lshl_add_u64 v[0:1], s[30:31], 0, v[0:1]
	v_lshlrev_b32_e32 v32, 1, v58
	v_lshl_add_u64 v[34:35], v[0:1], 0, v[32:33]
	s_barrier
	global_load_dwordx4 v[0:3], v[34:35], off
	v_add_u32_e32 v4, s44, v32
	v_mad_u32_u24 v50, v56, s88, v4
	v_mad_u32_u24 v32, v56, s88, v213
	v_add_u32_e32 v51, v4, v32
	ds_read_b128 v[4:7], v50
	ds_read_b128 v[38:41], v50 offset:32
	v_mul_u32_u24_e32 v36, 0x210, v56
	v_cmp_gt_u32_e64 s[4:5], 32, v55
	s_waitcnt vmcnt(0) lgkmcnt(1)
	v_mfma_f32_32x32x16_bf16 v[16:31], v[0:3], v[4:7], 0
	ds_read_b128 v[4:7], v51
	ds_read_b128 v[42:45], v51 offset:32
	global_load_dwordx4 v[46:49], v[34:35], off offset:32
	s_waitcnt lgkmcnt(1)
	v_mfma_f32_32x32x16_bf16 v[0:15], v[0:3], v[4:7], 0
	s_waitcnt vmcnt(0)
	v_mfma_f32_32x32x16_bf16 v[16:31], v[46:49], v[38:41], v[16:31]
	global_load_dwordx4 v[38:41], v[34:35], off offset:64
	s_waitcnt lgkmcnt(0)
	v_mfma_f32_32x32x16_bf16 v[0:15], v[46:49], v[42:45], v[0:15]
	ds_read_b128 v[42:45], v50 offset:64
	ds_read_b128 v[46:49], v51 offset:64
	s_waitcnt vmcnt(0) lgkmcnt(1)
	v_mfma_f32_32x32x16_bf16 v[16:31], v[38:41], v[42:45], v[16:31]
	s_waitcnt lgkmcnt(0)
	v_mfma_f32_32x32x16_bf16 v[0:15], v[38:41], v[46:49], v[0:15]
	global_load_dwordx4 v[38:41], v[34:35], off offset:96
	ds_read_b128 v[42:45], v50 offset:96
	ds_read_b128 v[46:49], v51 offset:96
	s_waitcnt vmcnt(0) lgkmcnt(1)
	v_mfma_f32_32x32x16_bf16 v[16:31], v[38:41], v[42:45], v[16:31]
	s_waitcnt lgkmcnt(0)
	v_mfma_f32_32x32x16_bf16 v[0:15], v[38:41], v[46:49], v[0:15]
	global_load_dwordx4 v[38:41], v[34:35], off offset:128
	ds_read_b128 v[42:45], v50 offset:128
	ds_read_b128 v[46:49], v51 offset:128
	s_waitcnt vmcnt(0) lgkmcnt(1)
	v_mfma_f32_32x32x16_bf16 v[16:31], v[38:41], v[42:45], v[16:31]
	s_waitcnt lgkmcnt(0)
	v_mfma_f32_32x32x16_bf16 v[0:15], v[38:41], v[46:49], v[0:15]
	global_load_dwordx4 v[38:41], v[34:35], off offset:160
	ds_read_b128 v[42:45], v50 offset:160
	ds_read_b128 v[46:49], v51 offset:160
	s_waitcnt vmcnt(0) lgkmcnt(1)
	v_mfma_f32_32x32x16_bf16 v[16:31], v[38:41], v[42:45], v[16:31]
	s_waitcnt lgkmcnt(0)
	v_mfma_f32_32x32x16_bf16 v[0:15], v[38:41], v[46:49], v[0:15]
	global_load_dwordx4 v[38:41], v[34:35], off offset:192
	ds_read_b128 v[42:45], v50 offset:192
	ds_read_b128 v[46:49], v51 offset:192
	s_waitcnt vmcnt(0) lgkmcnt(1)
	v_mfma_f32_32x32x16_bf16 v[16:31], v[38:41], v[42:45], v[16:31]
	s_waitcnt lgkmcnt(0)
	v_mfma_f32_32x32x16_bf16 v[0:15], v[38:41], v[46:49], v[0:15]
	global_load_dwordx4 v[38:41], v[34:35], off offset:224
	ds_read_b128 v[42:45], v50 offset:224
	ds_read_b128 v[46:49], v51 offset:224
	s_waitcnt vmcnt(0) lgkmcnt(1)
	v_mfma_f32_32x32x16_bf16 v[16:31], v[38:41], v[42:45], v[16:31]
	s_waitcnt lgkmcnt(0)
	v_mfma_f32_32x32x16_bf16 v[0:15], v[38:41], v[46:49], v[0:15]
	global_load_dwordx4 v[38:41], v[34:35], off offset:256
	ds_read_b128 v[42:45], v50 offset:256
	ds_read_b128 v[46:49], v51 offset:256
	s_waitcnt vmcnt(0) lgkmcnt(1)
	v_mfma_f32_32x32x16_bf16 v[16:31], v[38:41], v[42:45], v[16:31]
	s_waitcnt lgkmcnt(0)
	v_mfma_f32_32x32x16_bf16 v[0:15], v[38:41], v[46:49], v[0:15]
	global_load_dwordx4 v[38:41], v[34:35], off offset:288
	ds_read_b128 v[42:45], v50 offset:288
	ds_read_b128 v[46:49], v51 offset:288
	s_waitcnt vmcnt(0) lgkmcnt(1)
	v_mfma_f32_32x32x16_bf16 v[16:31], v[38:41], v[42:45], v[16:31]
	s_waitcnt lgkmcnt(0)
	v_mfma_f32_32x32x16_bf16 v[0:15], v[38:41], v[46:49], v[0:15]
	global_load_dwordx4 v[38:41], v[34:35], off offset:320
	ds_read_b128 v[42:45], v50 offset:320
	ds_read_b128 v[46:49], v51 offset:320
	s_waitcnt vmcnt(0) lgkmcnt(1)
	v_mfma_f32_32x32x16_bf16 v[16:31], v[38:41], v[42:45], v[16:31]
	s_waitcnt lgkmcnt(0)
	v_mfma_f32_32x32x16_bf16 v[0:15], v[38:41], v[46:49], v[0:15]
	global_load_dwordx4 v[38:41], v[34:35], off offset:352
	ds_read_b128 v[42:45], v50 offset:352
	ds_read_b128 v[46:49], v51 offset:352
	s_waitcnt vmcnt(0) lgkmcnt(1)
	v_mfma_f32_32x32x16_bf16 v[16:31], v[38:41], v[42:45], v[16:31]
	s_waitcnt lgkmcnt(0)
	v_mfma_f32_32x32x16_bf16 v[0:15], v[38:41], v[46:49], v[0:15]
	global_load_dwordx4 v[38:41], v[34:35], off offset:384
	ds_read_b128 v[42:45], v50 offset:384
	ds_read_b128 v[46:49], v51 offset:384
	s_waitcnt vmcnt(0) lgkmcnt(1)
	v_mfma_f32_32x32x16_bf16 v[16:31], v[38:41], v[42:45], v[16:31]
	s_waitcnt lgkmcnt(0)
	v_mfma_f32_32x32x16_bf16 v[0:15], v[38:41], v[46:49], v[0:15]
	global_load_dwordx4 v[38:41], v[34:35], off offset:416
	ds_read_b128 v[42:45], v50 offset:416
	ds_read_b128 v[46:49], v51 offset:416
	s_waitcnt vmcnt(0) lgkmcnt(1)
	v_mfma_f32_32x32x16_bf16 v[16:31], v[38:41], v[42:45], v[16:31]
	s_waitcnt lgkmcnt(0)
	v_mfma_f32_32x32x16_bf16 v[0:15], v[38:41], v[46:49], v[0:15]
	global_load_dwordx4 v[38:41], v[34:35], off offset:448
	ds_read_b128 v[42:45], v50 offset:448
	ds_read_b128 v[46:49], v51 offset:448
	s_waitcnt vmcnt(0) lgkmcnt(1)
	v_mfma_f32_32x32x16_bf16 v[16:31], v[38:41], v[42:45], v[16:31]
	s_waitcnt lgkmcnt(0)
	v_mfma_f32_32x32x16_bf16 v[0:15], v[38:41], v[46:49], v[0:15]
	global_load_dwordx4 v[38:41], v[34:35], off offset:480
	ds_read_b128 v[42:45], v50 offset:480
	ds_read_b128 v[46:49], v51 offset:480
	v_and_b32_e32 v34, 0x3fffffc0, v54
	v_mov_b32_e32 v35, s7
	s_waitcnt vmcnt(0) lgkmcnt(1)
	v_mfma_f32_32x32x16_bf16 v[16:31], v[38:41], v[42:45], v[16:31]
	s_waitcnt lgkmcnt(0)
; DI unsigned pk2(float a, float b) { f2_t v = {a, b}; bf2_t r = __builtin_convertvector(v, bf2_t); return __builtin_bit_cast(unsigned, r); }
; DI float bflo(unsigned u) { return __uint_as_float(u << 16); }
; DI float bfhi(unsigned u) { return __uint_as_float(u & 0xffff0000u); }
; DI void ssm_out_item(const CP& p, int l, int item, char* smem) {
;     ...
;   const float* bg = p.b_glu + (size_t)l * 256;
; #pragma unroll
;   for (int j = 0; j < 2; ++j) {
;     const int token = j * 32 + l32;
;     float sq = 0.f;
; #pragma unroll
;     for (int blk = 0; blk < 4; ++blk) {
;       const int ch = w * 32 + 8 * blk + 4 * hh;
;       const fl4 bv = *(const fl4*)(bg + ch);
;       const u32x2 yy = *(const u32x2*)(sY + token * 264 + ch);
;       const float g0 = 1.f / (1.f + __expf(-(acc[j][4 * blk] + bv.x)));
;       const float g1 = 1.f / (1.f + __expf(-(acc[j][4 * blk + 1] + bv.y)));
;       const float g2 = 1.f / (1.f + __expf(-(acc[j][4 * blk + 2] + bv.z)));
;       const float g3 = 1.f / (1.f + __expf(-(acc[j][4 * blk + 3] + bv.w)));
;       const float o0 = bflo(yy.x) * g0, o1 = bfhi(yy.x) * g1, o2 = bflo(yy.y) * g2, o3 = bfhi(yy.y) * g3;
;       sq += o0 * o0 + o1 * o1 + o2 * o2 + o3 * o3;
;       u32x2 v;
;       v.x = pk2(o0, o1); v.y = pk2(o2, o3);
;       *(u32x2*)(p.mixed + (tok0 + token) * 1024 + 768 + ch) = v;
;     }
	v_mfma_f32_32x32x16_bf16 v[0:15], v[38:41], v[46:49], v[0:15]
	v_lshl_or_b32 v40, v57, 2, v37
	v_ashrrev_i32_e32 v41, 31, v40
	v_lshl_add_u64 v[38:39], v[40:41], 2, s[68:69]
	global_load_dwordx4 v[50:53], v[38:39], off
	v_lshl_add_u32 v48, v34, 2, s36
	v_or_b32_e32 v34, s6, v56
	v_lshlrev_b64 v[34:35], 11, v[34:35]
	v_lshl_add_u64 v[44:45], s[66:67], 0, v[34:35]
	v_lshlrev_b32_e32 v34, 1, v40
	v_add3_u32 v46, s44, v36, v34
	ds_read2_b64 v[34:37], v46 offset1:2
	v_lshl_add_u64 v[44:45], v[40:41], 1, v[44:45]
	s_waitcnt vmcnt(0)
	v_add_f32_e32 v16, v16, v50
	v_add_f32_e32 v17, v17, v51
	v_mul_f32_e32 v16, 0xbfb8aa3b, v16
	v_mul_f32_e32 v17, 0xbfb8aa3b, v17
	v_exp_f32_e32 v16, v16
	v_exp_f32_e32 v17, v17
	v_add_f32_e32 v18, v18, v52
	v_add_f32_e32 v19, v19, v53
	v_mul_f32_e32 v18, 0xbfb8aa3b, v18
	v_pk_add_f32 v[16:17], v[16:17], 1.0 op_sel_hi:[1,0]
	v_mul_f32_e32 v19, 0xbfb8aa3b, v19
	v_div_scale_f32 v42, s[10:11], v17, v17, 1.0
	v_rcp_f32_e32 v43, v42
	v_exp_f32_e32 v18, v18
	v_exp_f32_e32 v19, v19
	v_fma_f32 v47, -v42, v43, 1.0
	v_fmac_f32_e32 v43, v47, v43
	v_div_scale_f32 v47, vcc, 1.0, v17, 1.0
	v_mul_f32_e32 v49, v47, v43
	v_fma_f32 v50, -v42, v49, v47
	v_fmac_f32_e32 v49, v50, v43
	v_fma_f32 v42, -v42, v49, v47
	v_div_fmas_f32 v42, v42, v43, v49
	v_div_fixup_f32 v17, v42, v17, 1.0
	v_div_scale_f32 v42, s[10:11], v16, v16, 1.0
	v_rcp_f32_e32 v43, v42
	v_pk_add_f32 v[18:19], v[18:19], 1.0 op_sel_hi:[1,0]
	v_fma_f32 v47, -v42, v43, 1.0
	v_fmac_f32_e32 v43, v47, v43
	v_div_scale_f32 v47, vcc, 1.0, v16, 1.0
	v_mul_f32_e32 v49, v47, v43
	v_fma_f32 v50, -v42, v49, v47
	v_fmac_f32_e32 v49, v50, v43
	v_fma_f32 v42, -v42, v49, v47
	v_div_fmas_f32 v42, v42, v43, v49
	v_div_fixup_f32 v16, v42, v16, 1.0
	s_waitcnt lgkmcnt(0)
	v_lshlrev_b32_e32 v42, 16, v34
	v_and_b32_e32 v43, 0xffff0000, v34
	v_div_scale_f32 v34, s[10:11], v19, v19, 1.0
	v_pk_mul_f32 v[16:17], v[16:17], v[42:43]
	v_rcp_f32_e32 v42, v34
	s_nop 0
	v_fma_f32 v43, -v34, v42, 1.0
	v_fmac_f32_e32 v42, v43, v42
	v_div_scale_f32 v43, vcc, 1.0, v19, 1.0
	v_mul_f32_e32 v47, v43, v42
	v_fma_f32 v49, -v34, v47, v43
	v_fmac_f32_e32 v47, v49, v42
	v_fma_f32 v34, -v34, v47, v43
	v_div_fmas_f32 v34, v34, v42, v47
	v_div_fixup_f32 v19, v34, v19, 1.0
	v_div_scale_f32 v34, s[10:11], v18, v18, 1.0
	v_rcp_f32_e32 v42, v34
	s_nop 0
	v_fma_f32 v43, -v34, v42, 1.0
	v_fmac_f32_e32 v42, v43, v42
	v_div_scale_f32 v43, vcc, 1.0, v18, 1.0
	v_mul_f32_e32 v47, v43, v42
	v_fma_f32 v49, -v34, v47, v43
	v_fmac_f32_e32 v47, v49, v42
	v_fma_f32 v34, -v34, v47, v43
	v_div_fmas_f32 v34, v34, v42, v47
	v_div_fixup_f32 v18, v34, v18, 1.0
	v_lshlrev_b32_e32 v34, 16, v35
	v_and_b32_e32 v35, 0xffff0000, v35
	v_pk_mul_f32 v[18:19], v[18:19], v[34:35]
	v_pk_mul_f32 v[42:43], v[16:17], v[16:17]
	v_cvt_pk_bf16_f32 v16, v16, v17
	v_cvt_pk_bf16_f32 v17, v18, v19
	global_store_dwordx2 v[44:45], v[16:17], off offset:1536
	v_pk_mul_f32 v[34:35], v[18:19], v[18:19]
	global_load_dwordx4 v[16:19], v[38:39], off offset:32
	s_waitcnt vmcnt(0)
	v_add_f32_e32 v16, v20, v16
	v_add_f32_e32 v17, v21, v17
	v_mul_f32_e32 v16, 0xbfb8aa3b, v16
	v_mul_f32_e32 v17, 0xbfb8aa3b, v17
	v_exp_f32_e32 v16, v16
	v_exp_f32_e32 v17, v17
	v_add_f32_e32 v18, v22, v18
	v_mul_f32_e32 v18, 0xbfb8aa3b, v18
	v_exp_f32_e32 v20, v18
	v_add_f32_e32 v18, v23, v19
	v_mul_f32_e32 v18, 0xbfb8aa3b, v18
	v_pk_add_f32 v[16:17], v[16:17], 1.0 op_sel_hi:[1,0]
	v_exp_f32_e32 v21, v18
	v_div_scale_f32 v18, s[10:11], v17, v17, 1.0
	v_rcp_f32_e32 v19, v18
	v_pk_add_f32 v[20:21], v[20:21], 1.0 op_sel_hi:[1,0]
	v_fma_f32 v22, -v18, v19, 1.0
	v_fmac_f32_e32 v19, v22, v19
	v_div_scale_f32 v22, vcc, 1.0, v17, 1.0
	v_mul_f32_e32 v23, v22, v19
	v_fma_f32 v47, -v18, v23, v22
	v_fmac_f32_e32 v23, v47, v19
	v_fma_f32 v18, -v18, v23, v22
	v_div_fmas_f32 v18, v18, v19, v23
	v_div_fixup_f32 v23, v18, v17, 1.0
	v_div_scale_f32 v17, s[10:11], v16, v16, 1.0
	v_rcp_f32_e32 v18, v17
	s_nop 0
	v_fma_f32 v19, -v17, v18, 1.0
	v_fmac_f32_e32 v18, v19, v18
	v_div_scale_f32 v19, vcc, 1.0, v16, 1.0
	v_mul_f32_e32 v22, v19, v18
	v_fma_f32 v47, -v17, v22, v19
	v_fmac_f32_e32 v22, v47, v18
	v_fma_f32 v17, -v17, v22, v19
	v_div_fmas_f32 v17, v17, v18, v22
	v_div_fixup_f32 v22, v17, v16, 1.0
	ds_read2_b64 v[16:19], v46 offset0:4 offset1:6
	v_lshlrev_b32_e32 v46, 16, v36
	v_and_b32_e32 v47, 0xffff0000, v36
	v_pk_mul_f32 v[46:47], v[22:23], v[46:47]
	v_div_scale_f32 v22, s[10:11], v21, v21, 1.0
	v_rcp_f32_e32 v23, v22
	s_nop 0
	v_fma_f32 v36, -v22, v23, 1.0
	v_fmac_f32_e32 v23, v36, v23
	v_div_scale_f32 v36, vcc, 1.0, v21, 1.0
	v_mul_f32_e32 v49, v36, v23
	v_fma_f32 v50, -v22, v49, v36
	v_fmac_f32_e32 v49, v50, v23
	v_fma_f32 v22, -v22, v49, v36
	v_div_fmas_f32 v22, v22, v23, v49
	v_div_fixup_f32 v21, v22, v21, 1.0
	v_div_scale_f32 v22, s[10:11], v20, v20, 1.0
	v_rcp_f32_e32 v23, v22
	s_nop 0
	v_fma_f32 v36, -v22, v23, 1.0
	v_fmac_f32_e32 v23, v36, v23
	v_div_scale_f32 v36, vcc, 1.0, v20, 1.0
	v_mul_f32_e32 v49, v36, v23
	v_fma_f32 v50, -v22, v49, v36
	v_fmac_f32_e32 v49, v50, v23
	v_fma_f32 v22, -v22, v49, v36
	v_div_fmas_f32 v22, v22, v23, v49
	v_div_fixup_f32 v20, v22, v20, 1.0
	v_lshlrev_b32_e32 v22, 16, v37
	v_and_b32_e32 v23, 0xffff0000, v37
	v_pk_mul_f32 v[36:37], v[20:21], v[22:23]
	v_pk_mul_f32 v[22:23], v[46:47], v[46:47]
	v_cvt_pk_bf16_f32 v46, v46, v47
	v_cvt_pk_bf16_f32 v47, v36, v37
	global_store_dwordx2 v[44:45], v[46:47], off offset:1552
	global_load_dwordx4 v[50:53], v[38:39], off offset:64
	v_pk_mul_f32 v[20:21], v[36:37], v[36:37]
	v_add_f32_e32 v22, v22, v23
	v_add_f32_e32 v20, v20, v22
	v_add_f32_e32 v20, v21, v20
	s_waitcnt vmcnt(0)
; DI unsigned pk2(float a, float b) { f2_t v = {a, b}; bf2_t r = __builtin_convertvector(v, bf2_t); return __builtin_bit_cast(unsigned, r); }
; DI float bflo(unsigned u) { return __uint_as_float(u << 16); }
; DI float bfhi(unsigned u) { return __uint_as_float(u & 0xffff0000u); }
; DI float shx32(float v) { return shx(v, get_tid() & 63, 32); }
; DI void ssm_out_item(const CP& p, int l, int item, char* smem) {
;     ...
; #pragma unroll
;     for (int blk = 0; blk < 4; ++blk) {
;       const int ch = w * 32 + 8 * blk + 4 * hh;
;       const fl4 bv = *(const fl4*)(bg + ch);
;       const u32x2 yy = *(const u32x2*)(sY + token * 264 + ch);
;       const float g0 = 1.f / (1.f + __expf(-(acc[j][4 * blk] + bv.x)));
;       const float g1 = 1.f / (1.f + __expf(-(acc[j][4 * blk + 1] + bv.y)));
;       const float g2 = 1.f / (1.f + __expf(-(acc[j][4 * blk + 2] + bv.z)));
;       const float g3 = 1.f / (1.f + __expf(-(acc[j][4 * blk + 3] + bv.w)));
;       const float o0 = bflo(yy.x) * g0, o1 = bfhi(yy.x) * g1, o2 = bflo(yy.y) * g2, o3 = bfhi(yy.y) * g3;
;       sq += o0 * o0 + o1 * o1 + o2 * o2 + o3 * o3;
;       u32x2 v;
;       v.x = pk2(o0, o1); v.y = pk2(o2, o3);
;       *(u32x2*)(p.mixed + (tok0 + token) * 1024 + 768 + ch) = v;
;     }
;     sq += shx32(sq);
;     if (hh == 0) sSS[w * 64 + token] = sq;
	v_add_f32_e32 v24, v24, v50
	v_add_f32_e32 v25, v25, v51
	v_mul_f32_e32 v24, 0xbfb8aa3b, v24
	v_mul_f32_e32 v25, 0xbfb8aa3b, v25
	v_exp_f32_e32 v24, v24
	v_exp_f32_e32 v25, v25
	v_add_f32_e32 v26, v26, v52
	v_add_f32_e32 v27, v27, v53
	v_mul_f32_e32 v26, 0xbfb8aa3b, v26
	v_pk_add_f32 v[24:25], v[24:25], 1.0 op_sel_hi:[1,0]
	v_mul_f32_e32 v27, 0xbfb8aa3b, v27
	v_div_scale_f32 v36, s[10:11], v25, v25, 1.0
	v_rcp_f32_e32 v37, v36
	v_exp_f32_e32 v26, v26
	v_exp_f32_e32 v27, v27
	v_fma_f32 v46, -v36, v37, 1.0
	v_fmac_f32_e32 v37, v46, v37
	v_div_scale_f32 v46, vcc, 1.0, v25, 1.0
	v_mul_f32_e32 v47, v46, v37
	v_fma_f32 v49, -v36, v47, v46
	v_fmac_f32_e32 v47, v49, v37
	v_fma_f32 v36, -v36, v47, v46
	v_div_fmas_f32 v36, v36, v37, v47
	v_div_fixup_f32 v25, v36, v25, 1.0
	v_div_scale_f32 v36, s[10:11], v24, v24, 1.0
	v_rcp_f32_e32 v37, v36
	v_pk_add_f32 v[26:27], v[26:27], 1.0 op_sel_hi:[1,0]
	v_fma_f32 v46, -v36, v37, 1.0
	v_fmac_f32_e32 v37, v46, v37
	v_div_scale_f32 v46, vcc, 1.0, v24, 1.0
	v_mul_f32_e32 v47, v46, v37
	v_fma_f32 v49, -v36, v47, v46
	v_fmac_f32_e32 v47, v49, v37
	v_fma_f32 v36, -v36, v47, v46
	v_div_fmas_f32 v36, v36, v37, v47
	v_div_fixup_f32 v24, v36, v24, 1.0
	s_waitcnt lgkmcnt(0)
	v_lshlrev_b32_e32 v36, 16, v16
	v_and_b32_e32 v37, 0xffff0000, v16
	v_div_scale_f32 v16, s[10:11], v27, v27, 1.0
	v_pk_mul_f32 v[24:25], v[24:25], v[36:37]
	v_rcp_f32_e32 v36, v16
	s_nop 0
	v_fma_f32 v37, -v16, v36, 1.0
	v_fmac_f32_e32 v36, v37, v36
	v_div_scale_f32 v37, vcc, 1.0, v27, 1.0
	v_mul_f32_e32 v46, v37, v36
	v_fma_f32 v47, -v16, v46, v37
	v_fmac_f32_e32 v46, v47, v36
	v_fma_f32 v16, -v16, v46, v37
	v_div_fmas_f32 v16, v16, v36, v46
	v_div_fixup_f32 v27, v16, v27, 1.0
	v_div_scale_f32 v16, s[10:11], v26, v26, 1.0
	v_rcp_f32_e32 v36, v16
	s_nop 0
	v_fma_f32 v37, -v16, v36, 1.0
	v_fmac_f32_e32 v36, v37, v36
	v_div_scale_f32 v37, vcc, 1.0, v26, 1.0
	v_mul_f32_e32 v46, v37, v36
	v_fma_f32 v47, -v16, v46, v37
	v_fmac_f32_e32 v46, v47, v36
	v_fma_f32 v16, -v16, v46, v37
	v_div_fmas_f32 v16, v16, v36, v46
	v_div_fixup_f32 v26, v16, v26, 1.0
	v_lshlrev_b32_e32 v16, 16, v17
	v_and_b32_e32 v17, 0xffff0000, v17
	v_pk_mul_f32 v[36:37], v[26:27], v[16:17]
	v_pk_mul_f32 v[26:27], v[24:25], v[24:25]
	v_cvt_pk_bf16_f32 v24, v24, v25
	v_cvt_pk_bf16_f32 v25, v36, v37
	global_store_dwordx2 v[44:45], v[24:25], off offset:1568
	global_load_dwordx4 v[50:53], v[38:39], off offset:96
	v_pk_mul_f32 v[16:17], v[36:37], v[36:37]
	v_add_f32_e32 v21, v26, v27
	v_add_f32_e32 v16, v16, v21
	v_add_f32_e32 v16, v17, v16
	v_lshl_add_u32 v26, v56, 2, v48
	s_waitcnt vmcnt(0)
	v_add_f32_e32 v24, v28, v50
	v_add_f32_e32 v25, v29, v51
	v_mul_f32_e32 v24, 0xbfb8aa3b, v24
	v_mul_f32_e32 v25, 0xbfb8aa3b, v25
	v_exp_f32_e32 v24, v24
	v_exp_f32_e32 v25, v25
	v_add_f32_e32 v28, v30, v52
	v_add_f32_e32 v29, v31, v53
	v_mul_f32_e32 v28, 0xbfb8aa3b, v28
	v_pk_add_f32 v[24:25], v[24:25], 1.0 op_sel_hi:[1,0]
	v_mul_f32_e32 v29, 0xbfb8aa3b, v29
	v_div_scale_f32 v30, s[10:11], v25, v25, 1.0
	v_rcp_f32_e32 v31, v30
	v_exp_f32_e32 v28, v28
	v_exp_f32_e32 v29, v29
	v_fma_f32 v36, -v30, v31, 1.0
	v_fmac_f32_e32 v31, v36, v31
	v_div_scale_f32 v36, vcc, 1.0, v25, 1.0
	v_mul_f32_e32 v37, v36, v31
	v_fma_f32 v46, -v30, v37, v36
	v_fmac_f32_e32 v37, v46, v31
	v_fma_f32 v30, -v30, v37, v36
	v_div_fmas_f32 v30, v30, v31, v37
	v_div_fixup_f32 v25, v30, v25, 1.0
	v_div_scale_f32 v30, s[10:11], v24, v24, 1.0
	v_rcp_f32_e32 v31, v30
	v_pk_add_f32 v[28:29], v[28:29], 1.0 op_sel_hi:[1,0]
	v_fma_f32 v36, -v30, v31, 1.0
	v_fmac_f32_e32 v31, v36, v31
	v_div_scale_f32 v36, vcc, 1.0, v24, 1.0
	v_mul_f32_e32 v37, v36, v31
	v_fma_f32 v46, -v30, v37, v36
	v_fmac_f32_e32 v37, v46, v31
	v_fma_f32 v30, -v30, v37, v36
	v_div_fmas_f32 v30, v30, v31, v37
	v_div_fixup_f32 v24, v30, v24, 1.0
	v_lshlrev_b32_e32 v30, 16, v18
	v_and_b32_e32 v31, 0xffff0000, v18
	v_div_scale_f32 v18, s[10:11], v29, v29, 1.0
	v_pk_mul_f32 v[24:25], v[24:25], v[30:31]
	v_rcp_f32_e32 v30, v18
	s_nop 0
	v_fma_f32 v31, -v18, v30, 1.0
	v_fmac_f32_e32 v30, v31, v30
	v_div_scale_f32 v31, vcc, 1.0, v29, 1.0
	v_mul_f32_e32 v36, v31, v30
	v_fma_f32 v37, -v18, v36, v31
	v_fmac_f32_e32 v36, v37, v30
	v_fma_f32 v18, -v18, v36, v31
	v_div_fmas_f32 v18, v18, v30, v36
	v_div_fixup_f32 v29, v18, v29, 1.0
	v_div_scale_f32 v18, s[10:11], v28, v28, 1.0
	v_rcp_f32_e32 v30, v18
	s_nop 0
	v_fma_f32 v31, -v18, v30, 1.0
	v_fmac_f32_e32 v30, v31, v30
	v_div_scale_f32 v31, vcc, 1.0, v28, 1.0
	v_mul_f32_e32 v36, v31, v30
	v_fma_f32 v37, -v18, v36, v31
	v_fmac_f32_e32 v36, v37, v30
	v_fma_f32 v18, -v18, v36, v31
	v_div_fmas_f32 v18, v18, v30, v36
	v_div_fixup_f32 v28, v18, v28, 1.0
	v_lshlrev_b32_e32 v18, 16, v19
	v_and_b32_e32 v19, 0xffff0000, v19
	v_add_f32_e32 v36, v42, v43
	v_pk_mul_f32 v[18:19], v[28:29], v[18:19]
	v_pk_mul_f32 v[28:29], v[24:25], v[24:25]
	v_add_f32_e32 v34, v34, v36
	v_pk_mul_f32 v[30:31], v[18:19], v[18:19]
	v_add_f32_e32 v34, v35, v34
	v_add_f32_e32 v17, v28, v29
	v_add_f32_e32 v20, v34, v20
	v_add_f32_e32 v17, v30, v17
	v_add_f32_e32 v16, v20, v16
	v_add_f32_e32 v17, v31, v17
	v_add_f32_e32 v16, v16, v17
	v_cvt_pk_bf16_f32 v20, v24, v25
	v_cvt_pk_bf16_f32 v21, v18, v19
	v_mov_b32_e32 v17, v202
	global_store_dwordx2 v[44:45], v[20:21], off offset:1584
	s_nop 0
	v_lshlrev_b32_e32 v17, 2, v17
	v_bitop3_b32 v17, v17, s84, v211 bitop3:0x6c
	ds_bpermute_b32 v17, v17, v16
	s_and_saveexec_b64 s[10:11], s[4:5]
	s_cbranch_execz .LBB0_339
	s_waitcnt lgkmcnt(0)
	v_add_f32_e32 v16, v16, v17
	ds_write_b32 v26, v16
